# GEMM K-loops: MFMA issue order changed to accumulator-chained pairs (k0 then k1 back-to-back on the same accumulator, SrcC forwarding) in all four 8-phase loops; bit-identical
# speedup vs baseline: 1.0071x; 1.0071x over previous
; #define PG8_WAIT_V(n) asm volatile("s_waitcnt vmcnt(" #n ")" ::: "memory")
; #define PG8_WAIT_L(n) asm volatile("s_waitcnt lgkmcnt(" #n ")" ::: "memory")
; #define PG8_BAR __builtin_amdgcn_s_barrier()
; #define PG8_SCHED __builtin_amdgcn_sched_barrier(0)
; template <class Epi, class AddrA, class AddrB>
; __device__ __forceinline__ void gemm_phase(const Sched S, const int lda, const int ldb, const int K, const AddrA addrA,
;                                            const AddrB addrB, const Epi E) {
;     ...
;     for (int t = 0; t < nt; t += 2) {
;       const bool last = (t == nt - 2);
;       const char* a1 = cA + (size_t)(t + 1) * kstep;
;       const char* a2 = last ? nA : cA + (size_t)(t + 2) * kstep;
;       const char* b2 = last ? nB : cB + (size_t)(t + 2) * kstep;
;       const char* a3 = a2 + kstep;
;       const char* b3 = b2 + kstep;
;       PG8_LDB(B0, 0, 0); PG8_SCHED; PG8_LDA(At, 0, 0); PG8_STAGE(PG8_SA(1, 1), a1 + hstepA, voffA);
;       PG8_WAIT_L(8); PG8_BAR; PG8_WAIT_L(0); PG8_MMA(0, 0, At, B0); PG8_BAR; PG8_SCHED;
;       PG8_LDB(B1, 0, 1); PG8_STAGE(PG8_SB(0, 0), b2, voffB);
;       PG8_BAR; PG8_WAIT_L(0); PG8_MMA(0, 1, At, B1); PG8_BAR;
;       PG8_LDA(At, 0, 1); PG8_STAGE(PG8_SA(0, 0), a2, voffA);
;       PG8_BAR; PG8_WAIT_L(0); PG8_MMA(1, 0, At, B0); PG8_BAR; PG8_SCHED;
;       PG8_STAGE(PG8_SB(0, 1), b2 + hstepB, voffB);
;       PG8_WAIT_V(6); PG8_BAR; PG8_MMA(1, 1, At, B1); PG8_BAR;
;       PG8_LDB(B0, 1, 0); PG8_SCHED; PG8_LDA(At, 1, 0); PG8_STAGE(PG8_SA(0, 1), a2 + hstepA, voffA);
;       PG8_WAIT_L(8); PG8_BAR; PG8_WAIT_L(0); PG8_MMA(0, 0, At, B0); PG8_BAR; PG8_SCHED;
;       PG8_LDB(B1, 1, 1); PG8_STAGE(PG8_SB(1, 0), b3, voffB);
;       PG8_BAR; PG8_WAIT_L(0); PG8_MMA(0, 1, At, B1); PG8_BAR;
;       PG8_LDA(At, 1, 1); PG8_STAGE(PG8_SA(1, 0), a3, voffA);
;       PG8_BAR; PG8_WAIT_L(0); PG8_MMA(1, 0, At, B0); PG8_BAR; PG8_SCHED;
;       PG8_STAGE(PG8_SB(1, 1), b3 + hstepB, voffB);
;       PG8_WAIT_V(6); PG8_BAR; PG8_MMA(1, 1, At, B1); PG8_BAR;
.LBB0_109:
	s_add_u32 s14, s12, 0xfff80080
	s_addc_u32 s15, s13, -1
	s_add_i32 s40, 0, 0x10000
	v_add_u32_e32 v142, s40, v145
	ds_read_b128 v[148:151], v142
	ds_read_b128 v[152:155], v142 offset:1024
	ds_read_b128 v[156:159], v142 offset:2048
	ds_read_b128 v[160:163], v142 offset:3072
	s_cmp_eq_u32 s39, 28
	s_cselect_b32 s17, s1, s15
	s_cselect_b32 s16, s11, s14
	s_cselect_b32 s15, s3, s38
	s_cselect_b32 s14, s36, s37
	v_lshl_add_u64 v[142:143], s[12:13], 0, v[140:141]
	s_add_i32 m0, s24, 0xc000
	ds_read_b128 v[168:171], v146
	ds_read_b128 v[172:175], v146 offset:1024
	ds_read_b128 v[176:179], v146 offset:2048
	ds_read_b128 v[180:183], v146 offset:3072
	ds_read_b128 v[184:187], v146 offset:4096
	ds_read_b128 v[188:191], v146 offset:5120
	ds_read_b128 v[192:195], v146 offset:6144
	ds_read_b128 v[212:215], v146 offset:7168
	global_load_lds_dwordx4 v[142:143], off
	v_lshl_add_u64 v[142:143], s[12:13], 0, v[138:139]
	s_add_i32 m0, s24, 0xe000
	s_nop 0
	global_load_lds_dwordx4 v[142:143], off
	s_waitcnt lgkmcnt(8)
	s_barrier
	s_waitcnt lgkmcnt(0)
	s_setprio 1
	s_waitcnt lgkmcnt(0)
	v_mfma_f32_16x16x32_bf16 v[128:131], v[148:151], v[168:171], v[128:131]
	v_mfma_f32_16x16x32_bf16 v[128:131], v[152:155], v[172:175], v[128:131]
	v_mfma_f32_16x16x32_bf16 v[124:127], v[156:159], v[168:171], v[124:127]
	v_mfma_f32_16x16x32_bf16 v[124:127], v[160:163], v[172:175], v[124:127]
	v_mfma_f32_16x16x32_bf16 v[120:123], v[148:151], v[176:179], v[120:123]
	v_mfma_f32_16x16x32_bf16 v[120:123], v[152:155], v[180:183], v[120:123]
	v_mfma_f32_16x16x32_bf16 v[112:115], v[156:159], v[176:179], v[112:115]
	v_mfma_f32_16x16x32_bf16 v[112:115], v[160:163], v[180:183], v[112:115]
	v_mfma_f32_16x16x32_bf16 v[104:107], v[148:151], v[184:187], v[104:107]
	v_mfma_f32_16x16x32_bf16 v[104:107], v[152:155], v[188:191], v[104:107]
	v_mfma_f32_16x16x32_bf16 v[96:99], v[156:159], v[184:187], v[96:99]
	v_mfma_f32_16x16x32_bf16 v[96:99], v[160:163], v[188:191], v[96:99]
	v_mfma_f32_16x16x32_bf16 v[88:91], v[148:151], v[192:195], v[88:91]
	v_mfma_f32_16x16x32_bf16 v[88:91], v[152:155], v[212:215], v[88:91]
	v_mfma_f32_16x16x32_bf16 v[80:83], v[156:159], v[192:195], v[80:83]
	v_mfma_f32_16x16x32_bf16 v[80:83], v[160:163], v[212:215], v[80:83]
	s_setprio 0
	s_barrier
	s_add_i32 s42, 0, 0x14000
	v_add_u32_e32 v142, s42, v145
	s_add_i32 s40, s40, s19
	ds_read_b128 v[216:219], v142
	ds_read_b128 v[220:223], v142 offset:1024
	ds_read_b128 v[224:227], v142 offset:2048
	ds_read_b128 v[228:231], v142 offset:3072
	v_lshl_add_u64 v[142:143], s[14:15], 0, v[134:135]
	s_mov_b32 m0, s40
	v_lshl_add_u64 v[196:197], s[14:15], 0, v[0:1]
	global_load_lds_dwordx4 v[142:143], off
	s_add_i32 m0, s40, 0x2000
	s_nop 0
	global_load_lds_dwordx4 v[196:197], off
	s_barrier
	s_waitcnt lgkmcnt(0)
	s_setprio 1
	s_waitcnt lgkmcnt(0)
	v_mfma_f32_16x16x32_bf16 v[116:119], v[216:219], v[168:171], v[116:119]
	v_mfma_f32_16x16x32_bf16 v[116:119], v[220:223], v[172:175], v[116:119]
	v_mfma_f32_16x16x32_bf16 v[108:111], v[224:227], v[168:171], v[108:111]
	v_mfma_f32_16x16x32_bf16 v[108:111], v[228:231], v[172:175], v[108:111]
	v_mfma_f32_16x16x32_bf16 v[100:103], v[216:219], v[176:179], v[100:103]
	v_mfma_f32_16x16x32_bf16 v[100:103], v[220:223], v[180:183], v[100:103]
	v_mfma_f32_16x16x32_bf16 v[92:95], v[224:227], v[176:179], v[92:95]
	v_mfma_f32_16x16x32_bf16 v[92:95], v[228:231], v[180:183], v[92:95]
	v_mfma_f32_16x16x32_bf16 v[84:87], v[216:219], v[184:187], v[84:87]
	v_mfma_f32_16x16x32_bf16 v[84:87], v[220:223], v[188:191], v[84:87]
	v_mfma_f32_16x16x32_bf16 v[76:79], v[224:227], v[184:187], v[76:79]
	v_mfma_f32_16x16x32_bf16 v[76:79], v[228:231], v[188:191], v[76:79]
	v_mfma_f32_16x16x32_bf16 v[72:75], v[216:219], v[192:195], v[72:75]
	v_mfma_f32_16x16x32_bf16 v[72:75], v[220:223], v[212:215], v[72:75]
	v_mfma_f32_16x16x32_bf16 v[68:71], v[224:227], v[192:195], v[68:71]
	v_mfma_f32_16x16x32_bf16 v[68:71], v[228:231], v[212:215], v[68:71]
	s_setprio 0
	s_mov_b32 m0, s24
	v_lshl_add_u64 v[232:233], s[16:17], 0, v[136:137]
	s_barrier
	ds_read_b128 v[168:171], v146 offset:16384
	ds_read_b128 v[172:175], v146 offset:17408
	ds_read_b128 v[176:179], v146 offset:18432
	ds_read_b128 v[180:183], v146 offset:19456
	ds_read_b128 v[184:187], v146 offset:20480
	ds_read_b128 v[188:191], v146 offset:21504
	ds_read_b128 v[192:195], v146 offset:22528
	ds_read_b128 v[212:215], v146 offset:23552
	global_load_lds_dwordx4 v[232:233], off
	v_lshl_add_u64 v[234:235], s[16:17], 0, v[132:133]
	s_mov_b32 m0, s25
	s_nop 0
	global_load_lds_dwordx4 v[234:235], off
	s_barrier
	s_waitcnt lgkmcnt(0)
	s_setprio 1
	s_waitcnt lgkmcnt(0)
	v_mfma_f32_16x16x32_bf16 v[64:67], v[148:151], v[168:171], v[64:67]
	v_mfma_f32_16x16x32_bf16 v[64:67], v[152:155], v[172:175], v[64:67]
	v_mfma_f32_16x16x32_bf16 v[60:63], v[156:159], v[168:171], v[60:63]
	v_mfma_f32_16x16x32_bf16 v[60:63], v[160:163], v[172:175], v[60:63]
	v_mfma_f32_16x16x32_bf16 v[56:59], v[148:151], v[176:179], v[56:59]
	v_mfma_f32_16x16x32_bf16 v[56:59], v[152:155], v[180:183], v[56:59]
	v_mfma_f32_16x16x32_bf16 v[48:51], v[156:159], v[176:179], v[48:51]
	v_mfma_f32_16x16x32_bf16 v[48:51], v[160:163], v[180:183], v[48:51]
	v_mfma_f32_16x16x32_bf16 v[40:43], v[148:151], v[184:187], v[40:43]
	v_mfma_f32_16x16x32_bf16 v[40:43], v[152:155], v[188:191], v[40:43]
	v_mfma_f32_16x16x32_bf16 v[32:35], v[156:159], v[184:187], v[32:35]
	v_mfma_f32_16x16x32_bf16 v[32:35], v[160:163], v[188:191], v[32:35]
	v_mfma_f32_16x16x32_bf16 v[24:27], v[148:151], v[192:195], v[24:27]
	v_mfma_f32_16x16x32_bf16 v[24:27], v[152:155], v[212:215], v[24:27]
	v_mfma_f32_16x16x32_bf16 v[16:19], v[156:159], v[192:195], v[16:19]
	v_mfma_f32_16x16x32_bf16 v[16:19], v[160:163], v[212:215], v[16:19]
	s_setprio 0
	s_barrier
; #define PG8_WAIT_V(n) asm volatile("s_waitcnt vmcnt(" #n ")" ::: "memory")
; #define PG8_WAIT_L(n) asm volatile("s_waitcnt lgkmcnt(" #n ")" ::: "memory")
; #define PG8_BAR __builtin_amdgcn_s_barrier()
; #define PG8_SCHED __builtin_amdgcn_sched_barrier(0)
; template <class Epi, class AddrA, class AddrB>
; __device__ __forceinline__ void gemm_phase(const Sched S, const int lda, const int ldb, const int K, const AddrA addrA,
;                                            const AddrB addrB, const Epi E) {
;     ...
;     for (int t = 0; t < nt; t += 2) {
;       const bool last = (t == nt - 2);
;       const char* a1 = cA + (size_t)(t + 1) * kstep;
;       const char* a2 = last ? nA : cA + (size_t)(t + 2) * kstep;
;       const char* b2 = last ? nB : cB + (size_t)(t + 2) * kstep;
;       const char* a3 = a2 + kstep;
;       const char* b3 = b2 + kstep;
;       PG8_LDB(B0, 0, 0); PG8_SCHED; PG8_LDA(At, 0, 0); PG8_STAGE(PG8_SA(1, 1), a1 + hstepA, voffA);
;       PG8_WAIT_L(8); PG8_BAR; PG8_WAIT_L(0); PG8_MMA(0, 0, At, B0); PG8_BAR; PG8_SCHED;
;       PG8_LDB(B1, 0, 1); PG8_STAGE(PG8_SB(0, 0), b2, voffB);
;       PG8_BAR; PG8_WAIT_L(0); PG8_MMA(0, 1, At, B1); PG8_BAR;
;       PG8_LDA(At, 0, 1); PG8_STAGE(PG8_SA(0, 0), a2, voffA);
;       PG8_BAR; PG8_WAIT_L(0); PG8_MMA(1, 0, At, B0); PG8_BAR; PG8_SCHED;
;       PG8_STAGE(PG8_SB(0, 1), b2 + hstepB, voffB);
;       PG8_WAIT_V(6); PG8_BAR; PG8_MMA(1, 1, At, B1); PG8_BAR;
;       PG8_LDB(B0, 1, 0); PG8_SCHED; PG8_LDA(At, 1, 0); PG8_STAGE(PG8_SA(0, 1), a2 + hstepA, voffA);
;       PG8_WAIT_L(8); PG8_BAR; PG8_WAIT_L(0); PG8_MMA(0, 0, At, B0); PG8_BAR; PG8_SCHED;
;       PG8_LDB(B1, 1, 1); PG8_STAGE(PG8_SB(1, 0), b3, voffB);
;       PG8_BAR; PG8_WAIT_L(0); PG8_MMA(0, 1, At, B1); PG8_BAR;
;       PG8_LDA(At, 1, 1); PG8_STAGE(PG8_SA(1, 0), a3, voffA);
;       PG8_BAR; PG8_WAIT_L(0); PG8_MMA(1, 0, At, B0); PG8_BAR; PG8_SCHED;
;       PG8_STAGE(PG8_SB(1, 1), b3 + hstepB, voffB);
;       PG8_WAIT_V(6); PG8_BAR; PG8_MMA(1, 1, At, B1); PG8_BAR;
	s_add_u32 s40, s14, 0x80000
	s_addc_u32 s41, s15, 0
	s_add_i32 s42, s42, s19
	v_lshl_add_u64 v[148:149], s[40:41], 0, v[134:135]
	s_mov_b32 m0, s42
	s_nop 0
	global_load_lds_dwordx4 v[148:149], off
	v_lshl_add_u64 v[148:149], s[40:41], 0, v[0:1]
	s_add_i32 m0, s42, 0x2000
	s_nop 0
	global_load_lds_dwordx4 v[148:149], off
	s_waitcnt vmcnt(6)
	s_barrier
	s_setprio 1
	v_mfma_f32_16x16x32_bf16 v[52:55], v[216:219], v[168:171], v[52:55]
	v_mfma_f32_16x16x32_bf16 v[52:55], v[220:223], v[172:175], v[52:55]
	v_mfma_f32_16x16x32_bf16 v[44:47], v[224:227], v[168:171], v[44:47]
	v_mfma_f32_16x16x32_bf16 v[44:47], v[228:231], v[172:175], v[44:47]
	v_mfma_f32_16x16x32_bf16 v[36:39], v[216:219], v[176:179], v[36:39]
	v_mfma_f32_16x16x32_bf16 v[36:39], v[220:223], v[180:183], v[36:39]
	v_mfma_f32_16x16x32_bf16 v[28:31], v[224:227], v[176:179], v[28:31]
	v_mfma_f32_16x16x32_bf16 v[28:31], v[228:231], v[180:183], v[28:31]
	v_mfma_f32_16x16x32_bf16 v[20:23], v[216:219], v[184:187], v[20:23]
	v_mfma_f32_16x16x32_bf16 v[20:23], v[220:223], v[188:191], v[20:23]
	v_mfma_f32_16x16x32_bf16 v[12:15], v[224:227], v[184:187], v[12:15]
	v_mfma_f32_16x16x32_bf16 v[12:15], v[228:231], v[188:191], v[12:15]
	v_mfma_f32_16x16x32_bf16 v[8:11], v[216:219], v[192:195], v[8:11]
	v_mfma_f32_16x16x32_bf16 v[8:11], v[220:223], v[212:215], v[8:11]
	v_mfma_f32_16x16x32_bf16 v[4:7], v[224:227], v[192:195], v[4:7]
	v_mfma_f32_16x16x32_bf16 v[4:7], v[228:231], v[212:215], v[4:7]
	s_setprio 0
	s_add_i32 s40, 0, 0x18000
	v_add_u32_e32 v147, s40, v145
	s_barrier
	ds_read_b128 v[148:151], v147
	ds_read_b128 v[152:155], v147 offset:1024
	ds_read_b128 v[156:159], v147 offset:2048
	ds_read_b128 v[160:163], v147 offset:3072
	s_add_u32 s16, s16, 0x80000
	s_addc_u32 s17, s17, 0
	s_mov_b32 m0, s26
	v_lshl_add_u64 v[216:217], s[16:17], 0, v[136:137]
	ds_read_b128 v[168:171], v146 offset:32768
	ds_read_b128 v[172:175], v146 offset:33792
	ds_read_b128 v[176:179], v146 offset:34816
	ds_read_b128 v[180:183], v146 offset:35840
	ds_read_b128 v[184:187], v146 offset:36864
	ds_read_b128 v[188:191], v146 offset:37888
	ds_read_b128 v[192:195], v146 offset:38912
	ds_read_b128 v[212:215], v146 offset:39936
	global_load_lds_dwordx4 v[216:217], off
	v_lshl_add_u64 v[216:217], s[16:17], 0, v[132:133]
	s_mov_b32 m0, s27
	s_nop 0
	global_load_lds_dwordx4 v[216:217], off
	s_waitcnt lgkmcnt(8)
	s_barrier
	s_waitcnt lgkmcnt(0)
	s_setprio 1
	s_waitcnt lgkmcnt(0)
	v_mfma_f32_16x16x32_bf16 v[128:131], v[148:151], v[168:171], v[128:131]
	v_mfma_f32_16x16x32_bf16 v[128:131], v[152:155], v[172:175], v[128:131]
	v_mfma_f32_16x16x32_bf16 v[124:127], v[156:159], v[168:171], v[124:127]
	v_mfma_f32_16x16x32_bf16 v[124:127], v[160:163], v[172:175], v[124:127]
	v_mfma_f32_16x16x32_bf16 v[120:123], v[148:151], v[176:179], v[120:123]
	v_mfma_f32_16x16x32_bf16 v[120:123], v[152:155], v[180:183], v[120:123]
	v_mfma_f32_16x16x32_bf16 v[112:115], v[156:159], v[176:179], v[112:115]
	v_mfma_f32_16x16x32_bf16 v[112:115], v[160:163], v[180:183], v[112:115]
	v_mfma_f32_16x16x32_bf16 v[104:107], v[148:151], v[184:187], v[104:107]
	v_mfma_f32_16x16x32_bf16 v[104:107], v[152:155], v[188:191], v[104:107]
	v_mfma_f32_16x16x32_bf16 v[96:99], v[156:159], v[184:187], v[96:99]
	v_mfma_f32_16x16x32_bf16 v[96:99], v[160:163], v[188:191], v[96:99]
	v_mfma_f32_16x16x32_bf16 v[88:91], v[148:151], v[192:195], v[88:91]
	v_mfma_f32_16x16x32_bf16 v[88:91], v[152:155], v[212:215], v[88:91]
	v_mfma_f32_16x16x32_bf16 v[80:83], v[156:159], v[192:195], v[80:83]
	v_mfma_f32_16x16x32_bf16 v[80:83], v[160:163], v[212:215], v[80:83]
	s_setprio 0
	s_barrier
	s_add_i32 s16, 0, 0x1c000
	s_add_i32 s17, s40, s19
	v_add_u32_e32 v147, s16, v145
	v_lshl_add_u64 v[142:143], v[142:143], 0, s[52:53]
	s_mov_b32 m0, s17
	ds_read_b128 v[216:219], v147
	ds_read_b128 v[220:223], v147 offset:1024
	ds_read_b128 v[224:227], v147 offset:2048
	ds_read_b128 v[228:231], v147 offset:3072
	global_load_lds_dwordx4 v[142:143], off
	v_lshl_add_u64 v[142:143], v[196:197], 0, s[52:53]
	s_add_i32 m0, s17, 0x2000
	s_nop 0
	global_load_lds_dwordx4 v[142:143], off
	s_barrier
	s_waitcnt lgkmcnt(0)
	s_setprio 1
	s_waitcnt lgkmcnt(0)
	v_mfma_f32_16x16x32_bf16 v[116:119], v[216:219], v[168:171], v[116:119]
	v_mfma_f32_16x16x32_bf16 v[116:119], v[220:223], v[172:175], v[116:119]
	v_mfma_f32_16x16x32_bf16 v[108:111], v[224:227], v[168:171], v[108:111]
	v_mfma_f32_16x16x32_bf16 v[108:111], v[228:231], v[172:175], v[108:111]
	v_mfma_f32_16x16x32_bf16 v[100:103], v[216:219], v[176:179], v[100:103]
	v_mfma_f32_16x16x32_bf16 v[100:103], v[220:223], v[180:183], v[100:103]
	v_mfma_f32_16x16x32_bf16 v[92:95], v[224:227], v[176:179], v[92:95]
	v_mfma_f32_16x16x32_bf16 v[92:95], v[228:231], v[180:183], v[92:95]
	v_mfma_f32_16x16x32_bf16 v[84:87], v[216:219], v[184:187], v[84:87]
	v_mfma_f32_16x16x32_bf16 v[84:87], v[220:223], v[188:191], v[84:87]
	v_mfma_f32_16x16x32_bf16 v[76:79], v[224:227], v[184:187], v[76:79]
	v_mfma_f32_16x16x32_bf16 v[76:79], v[228:231], v[188:191], v[76:79]
	v_mfma_f32_16x16x32_bf16 v[72:75], v[216:219], v[192:195], v[72:75]
	v_mfma_f32_16x16x32_bf16 v[72:75], v[220:223], v[212:215], v[72:75]
	v_mfma_f32_16x16x32_bf16 v[68:71], v[224:227], v[192:195], v[68:71]
	v_mfma_f32_16x16x32_bf16 v[68:71], v[228:231], v[212:215], v[68:71]
	s_setprio 0
	s_mov_b32 m0, s30
	v_lshl_add_u64 v[142:143], v[232:233], 0, s[52:53]
	s_barrier
	ds_read_b128 v[168:171], v146 offset:49152
	ds_read_b128 v[172:175], v146 offset:50176
	ds_read_b128 v[176:179], v146 offset:51200
	ds_read_b128 v[180:183], v146 offset:52224
	ds_read_b128 v[184:187], v146 offset:53248
	ds_read_b128 v[188:191], v146 offset:54272
	ds_read_b128 v[192:195], v146 offset:55296
	ds_read_b128 v[212:215], v146 offset:56320
	global_load_lds_dwordx4 v[142:143], off
	v_lshl_add_u64 v[142:143], v[234:235], 0, s[52:53]
	s_mov_b32 m0, s31
	s_nop 0
	global_load_lds_dwordx4 v[142:143], off
	s_barrier
; #define PG8_WAIT_V(n) asm volatile("s_waitcnt vmcnt(" #n ")" ::: "memory")
; #define PG8_WAIT_L(n) asm volatile("s_waitcnt lgkmcnt(" #n ")" ::: "memory")
; #define PG8_BAR __builtin_amdgcn_s_barrier()
; #define PG8_SCHED __builtin_amdgcn_sched_barrier(0)
; template <class Epi, class AddrA, class AddrB>
; __device__ __forceinline__ void gemm_phase(const Sched S, const int lda, const int ldb, const int K, const AddrA addrA,
;                                            const AddrB addrB, const Epi E) {
;     ...
;     for (int t = 0; t < nt; t += 2) {
;       const bool last = (t == nt - 2);
;       const char* a1 = cA + (size_t)(t + 1) * kstep;
;       const char* a2 = last ? nA : cA + (size_t)(t + 2) * kstep;
;       const char* b2 = last ? nB : cB + (size_t)(t + 2) * kstep;
;       const char* a3 = a2 + kstep;
;       const char* b3 = b2 + kstep;
;       PG8_LDB(B0, 0, 0); PG8_SCHED; PG8_LDA(At, 0, 0); PG8_STAGE(PG8_SA(1, 1), a1 + hstepA, voffA);
;       PG8_WAIT_L(8); PG8_BAR; PG8_WAIT_L(0); PG8_MMA(0, 0, At, B0); PG8_BAR; PG8_SCHED;
;       PG8_LDB(B1, 0, 1); PG8_STAGE(PG8_SB(0, 0), b2, voffB);
;       PG8_BAR; PG8_WAIT_L(0); PG8_MMA(0, 1, At, B1); PG8_BAR;
;       PG8_LDA(At, 0, 1); PG8_STAGE(PG8_SA(0, 0), a2, voffA);
;       PG8_BAR; PG8_WAIT_L(0); PG8_MMA(1, 0, At, B0); PG8_BAR; PG8_SCHED;
;       PG8_STAGE(PG8_SB(0, 1), b2 + hstepB, voffB);
;       PG8_WAIT_V(6); PG8_BAR; PG8_MMA(1, 1, At, B1); PG8_BAR;
;       PG8_LDB(B0, 1, 0); PG8_SCHED; PG8_LDA(At, 1, 0); PG8_STAGE(PG8_SA(0, 1), a2 + hstepA, voffA);
;       PG8_WAIT_L(8); PG8_BAR; PG8_WAIT_L(0); PG8_MMA(0, 0, At, B0); PG8_BAR; PG8_SCHED;
;       PG8_LDB(B1, 1, 1); PG8_STAGE(PG8_SB(1, 0), b3, voffB);
;       PG8_BAR; PG8_WAIT_L(0); PG8_MMA(0, 1, At, B1); PG8_BAR;
;       PG8_LDA(At, 1, 1); PG8_STAGE(PG8_SA(1, 0), a3, voffA);
;       PG8_BAR; PG8_WAIT_L(0); PG8_MMA(1, 0, At, B0); PG8_BAR; PG8_SCHED;
;       PG8_STAGE(PG8_SB(1, 1), b3 + hstepB, voffB);
;       PG8_WAIT_V(6); PG8_BAR; PG8_MMA(1, 1, At, B1); PG8_BAR;
	s_waitcnt lgkmcnt(0)
	s_setprio 1
	s_waitcnt lgkmcnt(0)
	v_mfma_f32_16x16x32_bf16 v[64:67], v[148:151], v[168:171], v[64:67]
	v_mfma_f32_16x16x32_bf16 v[64:67], v[152:155], v[172:175], v[64:67]
	v_mfma_f32_16x16x32_bf16 v[60:63], v[156:159], v[168:171], v[60:63]
	v_mfma_f32_16x16x32_bf16 v[60:63], v[160:163], v[172:175], v[60:63]
	v_mfma_f32_16x16x32_bf16 v[56:59], v[148:151], v[176:179], v[56:59]
	v_mfma_f32_16x16x32_bf16 v[56:59], v[152:155], v[180:183], v[56:59]
	v_mfma_f32_16x16x32_bf16 v[48:51], v[156:159], v[176:179], v[48:51]
	v_mfma_f32_16x16x32_bf16 v[48:51], v[160:163], v[180:183], v[48:51]
	v_mfma_f32_16x16x32_bf16 v[40:43], v[148:151], v[184:187], v[40:43]
	v_mfma_f32_16x16x32_bf16 v[40:43], v[152:155], v[188:191], v[40:43]
	v_mfma_f32_16x16x32_bf16 v[32:35], v[156:159], v[184:187], v[32:35]
	v_mfma_f32_16x16x32_bf16 v[32:35], v[160:163], v[188:191], v[32:35]
	v_mfma_f32_16x16x32_bf16 v[24:27], v[148:151], v[192:195], v[24:27]
	v_mfma_f32_16x16x32_bf16 v[24:27], v[152:155], v[212:215], v[24:27]
	v_mfma_f32_16x16x32_bf16 v[16:19], v[156:159], v[192:195], v[16:19]
	v_mfma_f32_16x16x32_bf16 v[16:19], v[160:163], v[212:215], v[16:19]
	s_setprio 0
	s_barrier
	s_add_u32 s14, s14, 0x80080
	s_addc_u32 s15, s15, 0
	s_add_i32 s16, s16, s19
	v_lshl_add_u64 v[142:143], s[14:15], 0, v[134:135]
	s_mov_b32 m0, s16
	s_nop 0
	global_load_lds_dwordx4 v[142:143], off
	v_lshl_add_u64 v[142:143], s[14:15], 0, v[0:1]
	s_add_i32 m0, s16, 0x2000
	s_nop 0
	global_load_lds_dwordx4 v[142:143], off
	s_waitcnt vmcnt(6)
	s_barrier
	s_setprio 1
	v_mfma_f32_16x16x32_bf16 v[52:55], v[216:219], v[168:171], v[52:55]
	v_mfma_f32_16x16x32_bf16 v[52:55], v[220:223], v[172:175], v[52:55]
	v_mfma_f32_16x16x32_bf16 v[44:47], v[224:227], v[168:171], v[44:47]
	v_mfma_f32_16x16x32_bf16 v[44:47], v[228:231], v[172:175], v[44:47]
	v_mfma_f32_16x16x32_bf16 v[36:39], v[216:219], v[176:179], v[36:39]
	v_mfma_f32_16x16x32_bf16 v[36:39], v[220:223], v[180:183], v[36:39]
	v_mfma_f32_16x16x32_bf16 v[28:31], v[224:227], v[176:179], v[28:31]
	v_mfma_f32_16x16x32_bf16 v[28:31], v[228:231], v[180:183], v[28:31]
	v_mfma_f32_16x16x32_bf16 v[20:23], v[216:219], v[184:187], v[20:23]
	v_mfma_f32_16x16x32_bf16 v[20:23], v[220:223], v[188:191], v[20:23]
	v_mfma_f32_16x16x32_bf16 v[12:15], v[224:227], v[184:187], v[12:15]
	v_mfma_f32_16x16x32_bf16 v[12:15], v[228:231], v[188:191], v[12:15]
	v_mfma_f32_16x16x32_bf16 v[8:11], v[216:219], v[192:195], v[8:11]
	v_mfma_f32_16x16x32_bf16 v[8:11], v[220:223], v[212:215], v[8:11]
	v_mfma_f32_16x16x32_bf16 v[4:7], v[224:227], v[192:195], v[4:7]
	v_mfma_f32_16x16x32_bf16 v[4:7], v[228:231], v[212:215], v[4:7]
	s_setprio 0
	s_add_i32 s39, s39, 2
	s_add_u32 s37, s37, 0x100
	s_addc_u32 s38, s38, 0
	s_add_u32 s12, s12, 0x100
	s_addc_u32 s13, s13, 0
	s_cmp_gt_u32 s39, 29
	s_barrier
	s_cbranch_scc0 .LBB0_109
; template <class Epi, class AddrA, class AddrB>
; __device__ __forceinline__ void gemm_phase(const Sched S, const int lda, const int ldb, const int K, const AddrA addrA,
;                                            const AddrB addrB, const Epi E) {
;     ...
;     E(acc, cur, wr, wc, fr, fq);
;     if (!has_next) break;
;     if (!(Epi::KEEP && cur.br + 1 < S.nbr)) {
; #pragma unroll
;       for (int a = 0; a < 2; ++a)
; #pragma unroll
;         for (int b = 0; b < 2; ++b)
; #pragma unroll
;           for (int m = 0; m < 4; ++m)
; #pragma unroll
;             for (int n = 0; n < 2; ++n) acc[a][b][m][n] = (f32x4){0.f, 0.f, 0.f, 0.f};
;     }
;     cur = nxt; cA = nA; cB = nB; ++ui;
;   __device__ __forceinline__ void operator()(EPI_ARGS) const {
;     bf16_t* base = proj + ((size_t)u.pn * MTOK + (size_t)(u.pm * 256 + wr * 64 + fr)) * PLD + wc * 32 + 8 * fq;
; #pragma unroll
;     for (int ai = 0; ai < 2; ++ai)
; #pragma unroll
;       for (int m = 0; m < 4; ++m) {
;         bf16_t* rowp = base + (size_t)(ai * HALF + m * 16) * PLD;
; #pragma unroll
;         for (int bj = 0; bj < 2; ++bj) {
;           const f32x4 v0 = acc[ai][bj][m][0], v1 = acc[ai][bj][m][1];
;           u32x4 o;
;           o.x = pack2(v0[0], v0[1]); o.y = pack2(v0[2], v0[3]); o.z = pack2(v1[0], v1[1]); o.w = pack2(v1[2], v1[3]);
;           *(u32x4*)(rowp + bj * HALF) = o;
;         }
;       }
;   }
	s_ashr_i32 s11, s10, 31
	v_lshl_add_u32 v142, s35, 8, v144
	s_lshl_b64 s[10:11], s[10:11], 23
	v_ashrrev_i32_e32 v143, 31, v142
	s_add_u32 s10, s28, s10
	s_addc_u32 s11, s29, s11
	v_lshlrev_b64 v[142:143], 9, v[142:143]
	v_lshl_add_u64 v[142:143], s[10:11], 0, v[142:143]
	v_lshl_add_u64 v[142:143], v[142:143], 0, s[72:73]
	v_lshl_add_u64 v[142:143], v[142:143], 0, v[2:3]
	v_cvt_pk_bf16_f32 v116, v116, v117
	v_cvt_pk_bf16_f32 v117, v118, v119
	v_cvt_pk_bf16_f32 v119, v110, v111
	v_cvt_pk_bf16_f32 v110, v112, v113
	v_add_co_u32_e32 v112, vcc, s96, v142
	s_movk_i32 s1, 0x4000
	s_nop 0
	v_addc_co_u32_e32 v113, vcc, 0, v143, vcc
	v_cvt_pk_bf16_f32 v100, v100, v101
	v_cvt_pk_bf16_f32 v101, v102, v103
	v_cvt_pk_bf16_f32 v103, v94, v95
	v_cvt_pk_bf16_f32 v94, v96, v97
	v_add_co_u32_e32 v96, vcc, s1, v142
	s_movk_i32 s1, 0x6000
	s_nop 0
	v_addc_co_u32_e32 v97, vcc, 0, v143, vcc
	v_cvt_pk_bf16_f32 v84, v84, v85
	v_cvt_pk_bf16_f32 v85, v86, v87
	v_cvt_pk_bf16_f32 v87, v78, v79
	v_cvt_pk_bf16_f32 v78, v80, v81
	v_add_co_u32_e32 v80, vcc, s1, v142
	v_cvt_pk_bf16_f32 v64, v64, v65
	v_cvt_pk_bf16_f32 v65, v66, v67
	v_cvt_pk_bf16_f32 v66, v60, v61
	s_mov_b32 s1, 0x12000
	s_nop 0
	v_addc_co_u32_e32 v81, vcc, 0, v143, vcc
	v_add_co_u32_e32 v60, vcc, s67, v142
	v_cvt_pk_bf16_f32 v52, v52, v53
	v_cvt_pk_bf16_f32 v53, v54, v55
	v_cvt_pk_bf16_f32 v55, v46, v47
	v_cvt_pk_bf16_f32 v46, v48, v49
	s_nop 1
	v_addc_co_u32_e32 v61, vcc, 0, v143, vcc
	v_add_co_u32_e32 v48, vcc, s1, v142
	s_mov_b32 s1, 0x14000
	s_nop 0
	v_addc_co_u32_e32 v49, vcc, 0, v143, vcc
	v_cvt_pk_bf16_f32 v36, v36, v37
	v_cvt_pk_bf16_f32 v37, v38, v39
	v_cvt_pk_bf16_f32 v39, v30, v31
	v_cvt_pk_bf16_f32 v30, v32, v33
	v_add_co_u32_e32 v32, vcc, s1, v142
	s_mov_b32 s1, 0x16000
	s_nop 0
	v_addc_co_u32_e32 v33, vcc, 0, v143, vcc
	v_cvt_pk_bf16_f32 v20, v20, v21
	v_cvt_pk_bf16_f32 v21, v22, v23
	v_cvt_pk_bf16_f32 v23, v14, v15
	v_cvt_pk_bf16_f32 v14, v16, v17
	v_add_co_u32_e32 v16, vcc, s1, v142
	s_mov_b32 s10, s2
	s_nop 0
	v_addc_co_u32_e32 v17, vcc, 0, v143, vcc
	s_and_b64 vcc, exec, s[4:5]
	s_mov_b32 s35, s0
	s_mov_b64 s[12:13], s[8:9]
	s_mov_b64 s[14:15], s[6:7]
	v_cvt_pk_bf16_f32 v128, v128, v129
	v_cvt_pk_bf16_f32 v129, v130, v131
	v_cvt_pk_bf16_f32 v130, v124, v125
	v_cvt_pk_bf16_f32 v131, v126, v127
	flat_store_dwordx4 v[142:143], v[128:131]
	v_cvt_pk_bf16_f32 v118, v108, v109
	flat_store_dwordx4 v[142:143], v[116:119] offset:256
	v_cvt_pk_bf16_f32 v108, v120, v121
	v_cvt_pk_bf16_f32 v109, v122, v123
	v_cvt_pk_bf16_f32 v111, v114, v115
	flat_store_dwordx4 v[112:113], v[108:111]
	v_cvt_pk_bf16_f32 v102, v92, v93
	flat_store_dwordx4 v[112:113], v[100:103] offset:256
	v_cvt_pk_bf16_f32 v92, v104, v105
	v_cvt_pk_bf16_f32 v93, v106, v107
	v_cvt_pk_bf16_f32 v95, v98, v99
	flat_store_dwordx4 v[96:97], v[92:95]
	v_cvt_pk_bf16_f32 v86, v76, v77
	flat_store_dwordx4 v[96:97], v[84:87] offset:256
	v_cvt_pk_bf16_f32 v76, v88, v89
	v_cvt_pk_bf16_f32 v77, v90, v91
	v_cvt_pk_bf16_f32 v79, v82, v83
	flat_store_dwordx4 v[80:81], v[76:79]
	v_cvt_pk_bf16_f32 v72, v72, v73
	v_cvt_pk_bf16_f32 v73, v74, v75
	v_cvt_pk_bf16_f32 v74, v68, v69
	v_cvt_pk_bf16_f32 v75, v70, v71
	flat_store_dwordx4 v[80:81], v[72:75] offset:256
	v_cvt_pk_bf16_f32 v67, v62, v63
	flat_store_dwordx4 v[60:61], v[64:67]
	v_cvt_pk_bf16_f32 v54, v44, v45
	flat_store_dwordx4 v[60:61], v[52:55] offset:256
	v_cvt_pk_bf16_f32 v44, v56, v57
	v_cvt_pk_bf16_f32 v45, v58, v59
	v_cvt_pk_bf16_f32 v47, v50, v51
	flat_store_dwordx4 v[48:49], v[44:47]
	v_cvt_pk_bf16_f32 v38, v28, v29
	flat_store_dwordx4 v[48:49], v[36:39] offset:256
	v_cvt_pk_bf16_f32 v28, v40, v41
	v_cvt_pk_bf16_f32 v29, v42, v43
	v_cvt_pk_bf16_f32 v31, v34, v35
	flat_store_dwordx4 v[32:33], v[28:31]
	v_cvt_pk_bf16_f32 v22, v12, v13
	flat_store_dwordx4 v[32:33], v[20:23] offset:256
	v_cvt_pk_bf16_f32 v12, v24, v25
	v_cvt_pk_bf16_f32 v13, v26, v27
	v_cvt_pk_bf16_f32 v15, v18, v19
	flat_store_dwordx4 v[16:17], v[12:15]
	v_cvt_pk_bf16_f32 v8, v8, v9
	v_cvt_pk_bf16_f32 v9, v10, v11
	v_cvt_pk_bf16_f32 v10, v4, v5
	v_cvt_pk_bf16_f32 v11, v6, v7
	flat_store_dwordx4 v[16:17], v[8:11] offset:256
	s_cbranch_vccz .LBB0_106
	s_waitcnt vmcnt(0)
	s_cmpk_gt_u32 s18, 0xff
	s_cbranch_scc1 .LBB0_113
	s_barrier

; #define PG8_WAIT_V(n) asm volatile("s_waitcnt vmcnt(" #n ")" ::: "memory")
; #define PG8_WAIT_L(n) asm volatile("s_waitcnt lgkmcnt(" #n ")" ::: "memory")
; #define PG8_BAR __builtin_amdgcn_s_barrier()
; #define PG8_SCHED __builtin_amdgcn_sched_barrier(0)
; template <class Epi, class AddrA, class AddrB>
; __device__ __forceinline__ void gemm_phase(const Sched S, const int lda, const int ldb, const int K, const AddrA addrA,
;                                            const AddrB addrB, const Epi E) {
;     ...
;     for (int t = 0; t < nt; t += 2) {
;       const bool last = (t == nt - 2);
;       const char* a1 = cA + (size_t)(t + 1) * kstep;
;       const char* a2 = last ? nA : cA + (size_t)(t + 2) * kstep;
;       const char* b2 = last ? nB : cB + (size_t)(t + 2) * kstep;
;       const char* a3 = a2 + kstep;
;       const char* b3 = b2 + kstep;
;       PG8_LDB(B0, 0, 0); PG8_SCHED; PG8_LDA(At, 0, 0); PG8_STAGE(PG8_SA(1, 1), a1 + hstepA, voffA);
;       PG8_WAIT_L(8); PG8_BAR; PG8_WAIT_L(0); PG8_MMA(0, 0, At, B0); PG8_BAR; PG8_SCHED;
;       PG8_LDB(B1, 0, 1); PG8_STAGE(PG8_SB(0, 0), b2, voffB);
;       PG8_BAR; PG8_WAIT_L(0); PG8_MMA(0, 1, At, B1); PG8_BAR;
;       PG8_LDA(At, 0, 1); PG8_STAGE(PG8_SA(0, 0), a2, voffA);
;       PG8_BAR; PG8_WAIT_L(0); PG8_MMA(1, 0, At, B0); PG8_BAR; PG8_SCHED;
;       PG8_STAGE(PG8_SB(0, 1), b2 + hstepB, voffB);
;       PG8_WAIT_V(6); PG8_BAR; PG8_MMA(1, 1, At, B1); PG8_BAR;
;       PG8_LDB(B0, 1, 0); PG8_SCHED; PG8_LDA(At, 1, 0); PG8_STAGE(PG8_SA(0, 1), a2 + hstepA, voffA);
;       PG8_WAIT_L(8); PG8_BAR; PG8_WAIT_L(0); PG8_MMA(0, 0, At, B0); PG8_BAR; PG8_SCHED;
;       PG8_LDB(B1, 1, 1); PG8_STAGE(PG8_SB(1, 0), b3, voffB);
;       PG8_BAR; PG8_WAIT_L(0); PG8_MMA(0, 1, At, B1); PG8_BAR;
;       PG8_LDA(At, 1, 1); PG8_STAGE(PG8_SA(1, 0), a3, voffA);
;       PG8_BAR; PG8_WAIT_L(0); PG8_MMA(1, 0, At, B0); PG8_BAR; PG8_SCHED;
;       PG8_STAGE(PG8_SB(1, 1), b3 + hstepB, voffB);
;       PG8_WAIT_V(6); PG8_BAR; PG8_MMA(1, 1, At, B1); PG8_BAR;
.LBB0_485:
	s_add_u32 s6, s4, 0xfff80080
	s_addc_u32 s7, s5, -1
	s_add_i32 s44, 0, 0x10000
	v_add_u32_e32 v2, s44, v167
	ds_read_b128 v[92:95], v2
	ds_read_b128 v[100:103], v2 offset:1024
	ds_read_b128 v[132:135], v2 offset:2048
	ds_read_b128 v[144:147], v2 offset:3072
	s_cmp_eq_u32 s43, 4
	s_cselect_b32 s11, s3, s7
	s_cselect_b32 s10, s15, s6
	s_cselect_b32 s7, s17, s42
	s_cselect_b32 s6, s40, s41
	v_lshl_add_u64 v[196:197], s[4:5], 0, v[172:173]
	s_add_i32 m0, s30, 0xc000
	ds_read_b128 v[148:151], v169
	ds_read_b128 v[152:155], v169 offset:1024
	ds_read_b128 v[176:179], v169 offset:2048
	ds_read_b128 v[180:183], v169 offset:3072
	ds_read_b128 v[184:187], v169 offset:4096
	ds_read_b128 v[188:191], v169 offset:5120
	ds_read_b128 v[192:195], v169 offset:6144
	ds_read_b128 v[212:215], v169 offset:7168
	global_load_lds_dwordx4 v[196:197], off
	v_lshl_add_u64 v[196:197], s[4:5], 0, v[170:171]
	s_add_i32 m0, s30, 0xe000
	s_nop 0
	global_load_lds_dwordx4 v[196:197], off
	s_waitcnt lgkmcnt(8)
	s_barrier
	s_waitcnt lgkmcnt(0)
	s_setprio 1
	s_waitcnt lgkmcnt(0)
	v_mfma_f32_16x16x32_bf16 v[140:143], v[92:95], v[148:151], v[140:143]
	v_mfma_f32_16x16x32_bf16 v[140:143], v[100:103], v[152:155], v[140:143]
	v_mfma_f32_16x16x32_bf16 v[136:139], v[132:135], v[148:151], v[136:139]
	v_mfma_f32_16x16x32_bf16 v[136:139], v[144:147], v[152:155], v[136:139]
	v_mfma_f32_16x16x32_bf16 v[128:131], v[92:95], v[176:179], v[128:131]
	v_mfma_f32_16x16x32_bf16 v[128:131], v[100:103], v[180:183], v[128:131]
	v_mfma_f32_16x16x32_bf16 v[124:127], v[132:135], v[176:179], v[124:127]
	v_mfma_f32_16x16x32_bf16 v[124:127], v[144:147], v[180:183], v[124:127]
	v_mfma_f32_16x16x32_bf16 v[120:123], v[92:95], v[184:187], v[120:123]
	v_mfma_f32_16x16x32_bf16 v[120:123], v[100:103], v[188:191], v[120:123]
	v_mfma_f32_16x16x32_bf16 v[116:119], v[132:135], v[184:187], v[116:119]
	v_mfma_f32_16x16x32_bf16 v[116:119], v[144:147], v[188:191], v[116:119]
	v_mfma_f32_16x16x32_bf16 v[112:115], v[92:95], v[192:195], v[112:115]
	v_mfma_f32_16x16x32_bf16 v[112:115], v[100:103], v[212:215], v[112:115]
	v_mfma_f32_16x16x32_bf16 v[108:111], v[132:135], v[192:195], v[108:111]
	v_mfma_f32_16x16x32_bf16 v[108:111], v[144:147], v[212:215], v[108:111]
	s_setprio 0
	s_barrier
	s_add_i32 s46, 0, 0x14000
	s_add_i32 s44, s44, s29
	v_add_u32_e32 v2, s46, v167
	v_lshl_add_u64 v[196:197], s[6:7], 0, v[158:159]
	s_mov_b32 m0, s44
	ds_read_b128 v[216:219], v2
	ds_read_b128 v[220:223], v2 offset:1024
	ds_read_b128 v[224:227], v2 offset:2048
	ds_read_b128 v[228:231], v2 offset:3072
	global_load_lds_dwordx4 v[196:197], off
	v_lshl_add_u64 v[232:233], s[6:7], 0, v[0:1]
	s_add_i32 m0, s44, 0x2000
	s_nop 0
	global_load_lds_dwordx4 v[232:233], off
	s_barrier
	s_waitcnt lgkmcnt(0)
	s_setprio 1
	s_waitcnt lgkmcnt(0)
	v_mfma_f32_16x16x32_bf16 v[64:67], v[216:219], v[148:151], v[64:67]
	v_mfma_f32_16x16x32_bf16 v[64:67], v[220:223], v[152:155], v[64:67]
	v_mfma_f32_16x16x32_bf16 v[60:63], v[224:227], v[148:151], v[60:63]
	v_mfma_f32_16x16x32_bf16 v[60:63], v[228:231], v[152:155], v[60:63]
	v_mfma_f32_16x16x32_bf16 v[56:59], v[216:219], v[176:179], v[56:59]
	v_mfma_f32_16x16x32_bf16 v[56:59], v[220:223], v[180:183], v[56:59]
	v_mfma_f32_16x16x32_bf16 v[52:55], v[224:227], v[176:179], v[52:55]
	v_mfma_f32_16x16x32_bf16 v[52:55], v[228:231], v[180:183], v[52:55]
	v_mfma_f32_16x16x32_bf16 v[48:51], v[216:219], v[184:187], v[48:51]
	v_mfma_f32_16x16x32_bf16 v[48:51], v[220:223], v[188:191], v[48:51]
	v_mfma_f32_16x16x32_bf16 v[44:47], v[224:227], v[184:187], v[44:47]
	v_mfma_f32_16x16x32_bf16 v[44:47], v[228:231], v[188:191], v[44:47]
	v_mfma_f32_16x16x32_bf16 v[40:43], v[216:219], v[192:195], v[40:43]
	v_mfma_f32_16x16x32_bf16 v[40:43], v[220:223], v[212:215], v[40:43]
	v_mfma_f32_16x16x32_bf16 v[36:39], v[224:227], v[192:195], v[36:39]
	v_mfma_f32_16x16x32_bf16 v[36:39], v[228:231], v[212:215], v[36:39]
	s_setprio 0
	s_mov_b32 m0, s30
	v_lshl_add_u64 v[234:235], s[10:11], 0, v[160:161]
	s_barrier
	ds_read_b128 v[148:151], v169 offset:16384
	ds_read_b128 v[152:155], v169 offset:17408
	ds_read_b128 v[176:179], v169 offset:18432
	ds_read_b128 v[180:183], v169 offset:19456
	ds_read_b128 v[184:187], v169 offset:20480
	ds_read_b128 v[188:191], v169 offset:21504
	ds_read_b128 v[192:195], v169 offset:22528
	ds_read_b128 v[212:215], v169 offset:23552
	global_load_lds_dwordx4 v[234:235], off
	v_lshl_add_u64 v[236:237], s[10:11], 0, v[156:157]
	s_mov_b32 m0, s31
	s_nop 0
	global_load_lds_dwordx4 v[236:237], off
	s_barrier
	s_waitcnt lgkmcnt(0)
	s_setprio 1
	s_waitcnt lgkmcnt(0)
	v_mfma_f32_16x16x32_bf16 v[104:107], v[92:95], v[148:151], v[104:107]
	v_mfma_f32_16x16x32_bf16 v[104:107], v[100:103], v[152:155], v[104:107]
	v_mfma_f32_16x16x32_bf16 v[96:99], v[132:135], v[148:151], v[96:99]
	v_mfma_f32_16x16x32_bf16 v[96:99], v[144:147], v[152:155], v[96:99]
	v_mfma_f32_16x16x32_bf16 v[88:91], v[92:95], v[176:179], v[88:91]
	v_mfma_f32_16x16x32_bf16 v[88:91], v[100:103], v[180:183], v[88:91]
	v_mfma_f32_16x16x32_bf16 v[84:87], v[132:135], v[176:179], v[84:87]
	v_mfma_f32_16x16x32_bf16 v[84:87], v[144:147], v[180:183], v[84:87]
	v_mfma_f32_16x16x32_bf16 v[80:83], v[92:95], v[184:187], v[80:83]
	v_mfma_f32_16x16x32_bf16 v[80:83], v[100:103], v[188:191], v[80:83]
	v_mfma_f32_16x16x32_bf16 v[76:79], v[132:135], v[184:187], v[76:79]
	v_mfma_f32_16x16x32_bf16 v[76:79], v[144:147], v[188:191], v[76:79]
	v_mfma_f32_16x16x32_bf16 v[72:75], v[92:95], v[192:195], v[72:75]
	v_mfma_f32_16x16x32_bf16 v[72:75], v[100:103], v[212:215], v[72:75]
	v_mfma_f32_16x16x32_bf16 v[68:71], v[132:135], v[192:195], v[68:71]
	v_mfma_f32_16x16x32_bf16 v[68:71], v[144:147], v[212:215], v[68:71]
	s_setprio 0
	s_barrier
; #define PG8_WAIT_V(n) asm volatile("s_waitcnt vmcnt(" #n ")" ::: "memory")
; #define PG8_WAIT_L(n) asm volatile("s_waitcnt lgkmcnt(" #n ")" ::: "memory")
; #define PG8_BAR __builtin_amdgcn_s_barrier()
; #define PG8_SCHED __builtin_amdgcn_sched_barrier(0)
; template <class Epi, class AddrA, class AddrB>
; __device__ __forceinline__ void gemm_phase(const Sched S, const int lda, const int ldb, const int K, const AddrA addrA,
;                                            const AddrB addrB, const Epi E) {
;     ...
;     for (int t = 0; t < nt; t += 2) {
;       const bool last = (t == nt - 2);
;       const char* a1 = cA + (size_t)(t + 1) * kstep;
;       const char* a2 = last ? nA : cA + (size_t)(t + 2) * kstep;
;       const char* b2 = last ? nB : cB + (size_t)(t + 2) * kstep;
;       const char* a3 = a2 + kstep;
;       const char* b3 = b2 + kstep;
;       PG8_LDB(B0, 0, 0); PG8_SCHED; PG8_LDA(At, 0, 0); PG8_STAGE(PG8_SA(1, 1), a1 + hstepA, voffA);
;       PG8_WAIT_L(8); PG8_BAR; PG8_WAIT_L(0); PG8_MMA(0, 0, At, B0); PG8_BAR; PG8_SCHED;
;       PG8_LDB(B1, 0, 1); PG8_STAGE(PG8_SB(0, 0), b2, voffB);
;       PG8_BAR; PG8_WAIT_L(0); PG8_MMA(0, 1, At, B1); PG8_BAR;
;       PG8_LDA(At, 0, 1); PG8_STAGE(PG8_SA(0, 0), a2, voffA);
;       PG8_BAR; PG8_WAIT_L(0); PG8_MMA(1, 0, At, B0); PG8_BAR; PG8_SCHED;
;       PG8_STAGE(PG8_SB(0, 1), b2 + hstepB, voffB);
;       PG8_WAIT_V(6); PG8_BAR; PG8_MMA(1, 1, At, B1); PG8_BAR;
;       PG8_LDB(B0, 1, 0); PG8_SCHED; PG8_LDA(At, 1, 0); PG8_STAGE(PG8_SA(0, 1), a2 + hstepA, voffA);
;       PG8_WAIT_L(8); PG8_BAR; PG8_WAIT_L(0); PG8_MMA(0, 0, At, B0); PG8_BAR; PG8_SCHED;
;       PG8_LDB(B1, 1, 1); PG8_STAGE(PG8_SB(1, 0), b3, voffB);
;       PG8_BAR; PG8_WAIT_L(0); PG8_MMA(0, 1, At, B1); PG8_BAR;
;       PG8_LDA(At, 1, 1); PG8_STAGE(PG8_SA(1, 0), a3, voffA);
;       PG8_BAR; PG8_WAIT_L(0); PG8_MMA(1, 0, At, B0); PG8_BAR; PG8_SCHED;
;       PG8_STAGE(PG8_SB(1, 1), b3 + hstepB, voffB);
;       PG8_WAIT_V(6); PG8_BAR; PG8_MMA(1, 1, At, B1); PG8_BAR;
	s_add_u32 s44, s6, 0x20000
	s_addc_u32 s45, s7, 0
	s_add_i32 s46, s46, s29
	v_lshl_add_u64 v[92:93], s[44:45], 0, v[158:159]
	s_mov_b32 m0, s46
	s_nop 0
	global_load_lds_dwordx4 v[92:93], off
	v_lshl_add_u64 v[92:93], s[44:45], 0, v[0:1]
	s_add_i32 m0, s46, 0x2000
	s_nop 0
	global_load_lds_dwordx4 v[92:93], off
	s_waitcnt vmcnt(6)
	s_barrier
	s_setprio 1
	v_mfma_f32_16x16x32_bf16 v[32:35], v[216:219], v[148:151], v[32:35]
	v_mfma_f32_16x16x32_bf16 v[32:35], v[220:223], v[152:155], v[32:35]
	v_mfma_f32_16x16x32_bf16 v[28:31], v[224:227], v[148:151], v[28:31]
	v_mfma_f32_16x16x32_bf16 v[28:31], v[228:231], v[152:155], v[28:31]
	v_mfma_f32_16x16x32_bf16 v[24:27], v[216:219], v[176:179], v[24:27]
	v_mfma_f32_16x16x32_bf16 v[24:27], v[220:223], v[180:183], v[24:27]
	v_mfma_f32_16x16x32_bf16 v[20:23], v[224:227], v[176:179], v[20:23]
	v_mfma_f32_16x16x32_bf16 v[20:23], v[228:231], v[180:183], v[20:23]
	v_mfma_f32_16x16x32_bf16 v[16:19], v[216:219], v[184:187], v[16:19]
	v_mfma_f32_16x16x32_bf16 v[16:19], v[220:223], v[188:191], v[16:19]
	v_mfma_f32_16x16x32_bf16 v[12:15], v[224:227], v[184:187], v[12:15]
	v_mfma_f32_16x16x32_bf16 v[12:15], v[228:231], v[188:191], v[12:15]
	v_mfma_f32_16x16x32_bf16 v[8:11], v[216:219], v[192:195], v[8:11]
	v_mfma_f32_16x16x32_bf16 v[8:11], v[220:223], v[212:215], v[8:11]
	v_mfma_f32_16x16x32_bf16 v[4:7], v[224:227], v[192:195], v[4:7]
	v_mfma_f32_16x16x32_bf16 v[4:7], v[228:231], v[212:215], v[4:7]
	s_setprio 0
	s_add_i32 s44, 0, 0x18000
	v_add_u32_e32 v2, s44, v167
	s_barrier
	ds_read_b128 v[92:95], v2
	ds_read_b128 v[100:103], v2 offset:1024
	ds_read_b128 v[132:135], v2 offset:2048
	ds_read_b128 v[144:147], v2 offset:3072
	s_add_u32 s10, s10, 0x80000
	s_addc_u32 s11, s11, 0
	s_mov_b32 m0, s34
	v_lshl_add_u64 v[216:217], s[10:11], 0, v[160:161]
	ds_read_b128 v[148:151], v169 offset:32768
	ds_read_b128 v[152:155], v169 offset:33792
	ds_read_b128 v[176:179], v169 offset:34816
	ds_read_b128 v[180:183], v169 offset:35840
	ds_read_b128 v[184:187], v169 offset:36864
	ds_read_b128 v[188:191], v169 offset:37888
	ds_read_b128 v[192:195], v169 offset:38912
	ds_read_b128 v[212:215], v169 offset:39936
	global_load_lds_dwordx4 v[216:217], off
	v_lshl_add_u64 v[216:217], s[10:11], 0, v[156:157]
	s_mov_b32 m0, s35
	s_nop 0
	global_load_lds_dwordx4 v[216:217], off
	s_waitcnt lgkmcnt(8)
	s_barrier
	s_waitcnt lgkmcnt(0)
	s_setprio 1
	s_waitcnt lgkmcnt(0)
	v_mfma_f32_16x16x32_bf16 v[140:143], v[92:95], v[148:151], v[140:143]
	v_mfma_f32_16x16x32_bf16 v[140:143], v[100:103], v[152:155], v[140:143]
	v_mfma_f32_16x16x32_bf16 v[136:139], v[132:135], v[148:151], v[136:139]
	v_mfma_f32_16x16x32_bf16 v[136:139], v[144:147], v[152:155], v[136:139]
	v_mfma_f32_16x16x32_bf16 v[128:131], v[92:95], v[176:179], v[128:131]
	v_mfma_f32_16x16x32_bf16 v[128:131], v[100:103], v[180:183], v[128:131]
	v_mfma_f32_16x16x32_bf16 v[124:127], v[132:135], v[176:179], v[124:127]
	v_mfma_f32_16x16x32_bf16 v[124:127], v[144:147], v[180:183], v[124:127]
	v_mfma_f32_16x16x32_bf16 v[120:123], v[92:95], v[184:187], v[120:123]
	v_mfma_f32_16x16x32_bf16 v[120:123], v[100:103], v[188:191], v[120:123]
	v_mfma_f32_16x16x32_bf16 v[116:119], v[132:135], v[184:187], v[116:119]
	v_mfma_f32_16x16x32_bf16 v[116:119], v[144:147], v[188:191], v[116:119]
	v_mfma_f32_16x16x32_bf16 v[112:115], v[92:95], v[192:195], v[112:115]
	v_mfma_f32_16x16x32_bf16 v[112:115], v[100:103], v[212:215], v[112:115]
	v_mfma_f32_16x16x32_bf16 v[108:111], v[132:135], v[192:195], v[108:111]
	v_mfma_f32_16x16x32_bf16 v[108:111], v[144:147], v[212:215], v[108:111]
	s_setprio 0
	s_barrier
	s_add_i32 s10, 0, 0x1c000
	s_add_i32 s11, s44, s29
	v_add_u32_e32 v2, s10, v167
	v_lshl_add_u64 v[196:197], v[196:197], 0, s[52:53]
	s_mov_b32 m0, s11
	ds_read_b128 v[216:219], v2
	ds_read_b128 v[220:223], v2 offset:1024
	ds_read_b128 v[224:227], v2 offset:2048
	ds_read_b128 v[228:231], v2 offset:3072
	global_load_lds_dwordx4 v[196:197], off
	v_lshl_add_u64 v[196:197], v[232:233], 0, s[52:53]
	s_add_i32 m0, s11, 0x2000
	s_nop 0
	global_load_lds_dwordx4 v[196:197], off
	s_barrier
	s_waitcnt lgkmcnt(0)
	s_setprio 1
	s_waitcnt lgkmcnt(0)
	v_mfma_f32_16x16x32_bf16 v[64:67], v[216:219], v[148:151], v[64:67]
	v_mfma_f32_16x16x32_bf16 v[64:67], v[220:223], v[152:155], v[64:67]
	v_mfma_f32_16x16x32_bf16 v[60:63], v[224:227], v[148:151], v[60:63]
	v_mfma_f32_16x16x32_bf16 v[60:63], v[228:231], v[152:155], v[60:63]
	v_mfma_f32_16x16x32_bf16 v[56:59], v[216:219], v[176:179], v[56:59]
	v_mfma_f32_16x16x32_bf16 v[56:59], v[220:223], v[180:183], v[56:59]
	v_mfma_f32_16x16x32_bf16 v[52:55], v[224:227], v[176:179], v[52:55]
	v_mfma_f32_16x16x32_bf16 v[52:55], v[228:231], v[180:183], v[52:55]
	v_mfma_f32_16x16x32_bf16 v[48:51], v[216:219], v[184:187], v[48:51]
	v_mfma_f32_16x16x32_bf16 v[48:51], v[220:223], v[188:191], v[48:51]
	v_mfma_f32_16x16x32_bf16 v[44:47], v[224:227], v[184:187], v[44:47]
	v_mfma_f32_16x16x32_bf16 v[44:47], v[228:231], v[188:191], v[44:47]
	v_mfma_f32_16x16x32_bf16 v[40:43], v[216:219], v[192:195], v[40:43]
	v_mfma_f32_16x16x32_bf16 v[40:43], v[220:223], v[212:215], v[40:43]
	v_mfma_f32_16x16x32_bf16 v[36:39], v[224:227], v[192:195], v[36:39]
	v_mfma_f32_16x16x32_bf16 v[36:39], v[228:231], v[212:215], v[36:39]
	s_setprio 0
	s_mov_b32 m0, s37
	v_lshl_add_u64 v[196:197], v[234:235], 0, s[52:53]
	s_barrier
	ds_read_b128 v[148:151], v169 offset:49152
	ds_read_b128 v[152:155], v169 offset:50176
	ds_read_b128 v[176:179], v169 offset:51200
	ds_read_b128 v[180:183], v169 offset:52224
	ds_read_b128 v[184:187], v169 offset:53248
	ds_read_b128 v[188:191], v169 offset:54272
	ds_read_b128 v[192:195], v169 offset:55296
	ds_read_b128 v[212:215], v169 offset:56320
	global_load_lds_dwordx4 v[196:197], off
	v_lshl_add_u64 v[196:197], v[236:237], 0, s[52:53]
	s_mov_b32 m0, s38
	s_nop 0
	global_load_lds_dwordx4 v[196:197], off
	s_barrier
; __device__ __forceinline__ size_t pidx(size_t row, int col) { return ((size_t)(col >> 8) * MTOK + row) * PLD + (col & 255); }
; __device__ __forceinline__ float bflo(unsigned v) { return __uint_as_float(v << 16); }
; __device__ __forceinline__ float bfhi(unsigned v) { return __uint_as_float(v & 0xffff0000u); }
; __device__ __forceinline__ float siluf_(float x) { return x * __builtin_amdgcn_rcpf(1.0f + __expf(-x)); }
; #define PG8_WAIT_V(n) asm volatile("s_waitcnt vmcnt(" #n ")" ::: "memory")
; #define PG8_WAIT_L(n) asm volatile("s_waitcnt lgkmcnt(" #n ")" ::: "memory")
; #define PG8_BAR __builtin_amdgcn_s_barrier()
; #define PG8_SCHED __builtin_amdgcn_sched_barrier(0)
; template <class Epi, class AddrA, class AddrB>
; __device__ __forceinline__ void gemm_phase(const Sched S, const int lda, const int ldb, const int K, const AddrA addrA,
;                                            const AddrB addrB, const Epi E) {
;     ...
;       PG8_BAR; PG8_WAIT_L(0); PG8_MMA(1, 0, At, B0); PG8_BAR; PG8_SCHED;
;       PG8_STAGE(PG8_SB(1, 1), b3 + hstepB, voffB);
;       PG8_WAIT_V(6); PG8_BAR; PG8_MMA(1, 1, At, B1); PG8_BAR;
;   __device__ __forceinline__ void operator()(EPI_ARGS) const {
;     const size_t row0 = (size_t)u.pm * 256 + wr * 64 + fr;
;     const int col0 = u.pn * 256 + wc * 32 + 8 * fq;
; #pragma unroll
;     for (int bj = 0; bj < 2; ++bj) {
;       const int c = col0 + bj * HALF;
;       const f32x4 s0 = *(const f32x4*)(psc + c), s1 = *(const f32x4*)(psc + c + 4);
; #pragma unroll
;       for (int ai = 0; ai < 2; ++ai) {
;         u32x4 z[4];
; #pragma unroll
;         for (int m = 0; m < 4; ++m) z[m] = *(const u32x4*)(proj + pidx(row0 + ai * HALF + m * 16, PZ + c));
;         __builtin_amdgcn_sched_barrier(0);
; #pragma unroll
;         for (int m = 0; m < 4; ++m) {
;           const size_t row = row0 + ai * HALF + m * 16;
;           const f32x4 v0 = acc[ai][bj][m][0], v1 = acc[ai][bj][m][1];
;           u32x4 o;
;           o.x = pack2(v0[0] * s0[0] * siluf_(bflo(z[m].x)), v0[1] * s0[1] * siluf_(bfhi(z[m].x)));
;           o.y = pack2(v0[2] * s0[2] * siluf_(bflo(z[m].y)), v0[3] * s0[3] * siluf_(bfhi(z[m].y)));
;           o.z = pack2(v1[0] * s1[0] * siluf_(bflo(z[m].z)), v1[1] * s1[1] * siluf_(bfhi(z[m].z)));
;           o.w = pack2(v1[2] * s1[2] * siluf_(bflo(z[m].w)), v1[3] * s1[3] * siluf_(bfhi(z[m].w)));
;           *(u32x4*)(y0 + row * DM + c) = o;
	s_waitcnt lgkmcnt(0)
	s_setprio 1
	s_waitcnt lgkmcnt(0)
	v_mfma_f32_16x16x32_bf16 v[104:107], v[92:95], v[148:151], v[104:107]
	v_mfma_f32_16x16x32_bf16 v[104:107], v[100:103], v[152:155], v[104:107]
	v_mfma_f32_16x16x32_bf16 v[96:99], v[132:135], v[148:151], v[96:99]
	v_mfma_f32_16x16x32_bf16 v[96:99], v[144:147], v[152:155], v[96:99]
	v_mfma_f32_16x16x32_bf16 v[88:91], v[92:95], v[176:179], v[88:91]
	v_mfma_f32_16x16x32_bf16 v[88:91], v[100:103], v[180:183], v[88:91]
	v_mfma_f32_16x16x32_bf16 v[84:87], v[132:135], v[176:179], v[84:87]
	v_mfma_f32_16x16x32_bf16 v[84:87], v[144:147], v[180:183], v[84:87]
	v_mfma_f32_16x16x32_bf16 v[80:83], v[92:95], v[184:187], v[80:83]
	v_mfma_f32_16x16x32_bf16 v[80:83], v[100:103], v[188:191], v[80:83]
	v_mfma_f32_16x16x32_bf16 v[76:79], v[132:135], v[184:187], v[76:79]
	v_mfma_f32_16x16x32_bf16 v[76:79], v[144:147], v[188:191], v[76:79]
	v_mfma_f32_16x16x32_bf16 v[72:75], v[92:95], v[192:195], v[72:75]
	v_mfma_f32_16x16x32_bf16 v[72:75], v[100:103], v[212:215], v[72:75]
	v_mfma_f32_16x16x32_bf16 v[68:71], v[132:135], v[192:195], v[68:71]
	v_mfma_f32_16x16x32_bf16 v[68:71], v[144:147], v[212:215], v[68:71]
	s_setprio 0
	s_barrier
	s_add_u32 s6, s6, 0x20080
	s_addc_u32 s7, s7, 0
	s_add_i32 s10, s10, s29
	v_lshl_add_u64 v[92:93], s[6:7], 0, v[158:159]
	s_mov_b32 m0, s10
	s_nop 0
	global_load_lds_dwordx4 v[92:93], off
	v_lshl_add_u64 v[92:93], s[6:7], 0, v[0:1]
	s_add_i32 m0, s10, 0x2000
	s_nop 0
	global_load_lds_dwordx4 v[92:93], off
	s_waitcnt vmcnt(6)
	s_barrier
	s_setprio 1
	v_mfma_f32_16x16x32_bf16 v[32:35], v[216:219], v[148:151], v[32:35]
	v_mfma_f32_16x16x32_bf16 v[32:35], v[220:223], v[152:155], v[32:35]
	v_mfma_f32_16x16x32_bf16 v[28:31], v[224:227], v[148:151], v[28:31]
	v_mfma_f32_16x16x32_bf16 v[28:31], v[228:231], v[152:155], v[28:31]
	v_mfma_f32_16x16x32_bf16 v[24:27], v[216:219], v[176:179], v[24:27]
	v_mfma_f32_16x16x32_bf16 v[24:27], v[220:223], v[180:183], v[24:27]
	v_mfma_f32_16x16x32_bf16 v[20:23], v[224:227], v[176:179], v[20:23]
	v_mfma_f32_16x16x32_bf16 v[20:23], v[228:231], v[180:183], v[20:23]
	v_mfma_f32_16x16x32_bf16 v[16:19], v[216:219], v[184:187], v[16:19]
	v_mfma_f32_16x16x32_bf16 v[16:19], v[220:223], v[188:191], v[16:19]
	v_mfma_f32_16x16x32_bf16 v[12:15], v[224:227], v[184:187], v[12:15]
	v_mfma_f32_16x16x32_bf16 v[12:15], v[228:231], v[188:191], v[12:15]
	v_mfma_f32_16x16x32_bf16 v[8:11], v[216:219], v[192:195], v[8:11]
	v_mfma_f32_16x16x32_bf16 v[8:11], v[220:223], v[212:215], v[8:11]
	v_mfma_f32_16x16x32_bf16 v[4:7], v[224:227], v[192:195], v[4:7]
	v_mfma_f32_16x16x32_bf16 v[4:7], v[228:231], v[212:215], v[4:7]
	s_setprio 0
	s_add_i32 s43, s43, 2
	s_add_u32 s41, s41, 0x100
	s_addc_u32 s42, s42, 0
	s_add_u32 s4, s4, 0x100
	s_addc_u32 s5, s5, 0
	s_cmp_gt_u32 s43, 5
	s_barrier
	s_cbranch_scc0 .LBB0_485
	s_ashr_i32 s3, s2, 31
	s_lshl_b64 s[2:3], s[2:3], 8
	v_lshl_add_u64 v[186:187], s[2:3], 0, v[162:163]
	s_lshl_b32 s2, s33, 8
	v_or_b32_e32 v196, s2, v168
	s_addk_i32 s2, 0x800
	s_ashr_i32 s2, s2, 8
	s_ashr_i32 s3, s2, 31
	s_lshl_b64 s[2:3], s[2:3], 23
	s_add_u32 s2, s0, s2
	s_addc_u32 s3, s1, s3
	v_lshlrev_b32_e32 v2, 1, v168
	v_or_b32_e32 v194, 16, v186
	v_mov_b32_e32 v195, v187
	v_ashrrev_i32_e32 v197, 31, v196
	v_lshl_add_u64 v[188:189], s[2:3], 0, v[2:3]
	v_lshlrev_b64 v[178:179], 9, v[186:187]
	v_lshlrev_b64 v[180:181], 9, v[194:195]
	v_or_b32_e32 v192, 32, v186
	v_mov_b32_e32 v193, v187
	v_or_b32_e32 v190, 48, v186
	v_mov_b32_e32 v191, v187
	v_lshl_add_u64 v[176:177], v[196:197], 2, s[12:13]
	v_lshl_add_u64 v[132:133], v[188:189], 0, v[178:179]
	v_lshl_add_u64 v[134:135], v[188:189], 0, v[180:181]
	v_lshlrev_b64 v[182:183], 9, v[192:193]
	v_lshlrev_b64 v[184:185], 9, v[190:191]
	global_load_dwordx4 v[92:95], v[176:177], off offset:16
	global_load_dwordx4 v[100:103], v[176:177], off
	flat_load_dwordx4 v[152:155], v[132:133]
	flat_load_dwordx4 v[148:151], v[134:135]
	v_lshl_add_u64 v[132:133], v[188:189], 0, v[182:183]
	v_lshl_add_u64 v[134:135], v[188:189], 0, v[184:185]
	flat_load_dwordx4 v[144:147], v[132:133]
	s_nop 0
	flat_load_dwordx4 v[132:135], v[134:135]
	s_waitcnt vmcnt(0) lgkmcnt(0)
	v_lshlrev_b32_e32 v213, 16, v152
	v_mul_f32_e32 v2, 0xbfb8aa3b, v213
	v_exp_f32_e32 v2, v2
	v_mov_b32_e32 v214, v140
	v_mov_b32_e32 v212, v100
	s_mov_b64 s[4:5], 0x90
	v_add_f32_e32 v2, 1.0, v2
	v_rcp_f32_e32 v215, v2
	s_nop 0
	v_pk_mul_f32 v[212:213], v[214:215], v[212:213]
	s_nop 0
	v_mul_f32_e32 v2, v212, v213
	v_and_b32_e32 v213, 0xffff0000, v152
	v_mul_f32_e32 v140, 0xbfb8aa3b, v213
	v_exp_f32_e32 v140, v140
	v_mov_b32_e32 v214, v141
	v_mov_b32_e32 v212, v101
	v_add_f32_e32 v140, 1.0, v140
	v_rcp_f32_e32 v215, v140
	s_nop 0
	v_pk_mul_f32 v[140:141], v[214:215], v[212:213]
	s_nop 0
	v_mul_f32_e32 v140, v140, v141
	v_lshlrev_b32_e32 v141, 16, v153
	v_cvt_pk_bf16_f32 v152, v2, v140
	v_mul_f32_e32 v2, 0xbfb8aa3b, v141
	v_exp_f32_e32 v2, v2
	v_mov_b32_e32 v212, v142
	v_mov_b32_e32 v140, v102
	v_mov_b32_e32 v142, v136
	v_add_f32_e32 v2, 1.0, v2
	v_rcp_f32_e32 v213, v2
	s_nop 0
	v_pk_mul_f32 v[140:141], v[212:213], v[140:141]
	s_nop 0
	v_mul_f32_e32 v2, v140, v141
	v_and_b32_e32 v141, 0xffff0000, v153
	v_mul_f32_e32 v140, 0xbfb8aa3b, v141
	v_exp_f32_e32 v140, v140
	v_mov_b32_e32 v212, v143
	v_add_f32_e32 v140, 1.0, v140
	v_rcp_f32_e32 v213, v140
	v_mov_b32_e32 v140, v103
	v_pk_mul_f32 v[140:141], v[212:213], v[140:141]
	s_nop 0
	v_mul_f32_e32 v140, v140, v141
	v_lshlrev_b32_e32 v141, 16, v154
	v_cvt_pk_bf16_f32 v153, v2, v140
	v_mul_f32_e32 v2, 0xbfb8aa3b, v141
	v_exp_f32_e32 v2, v2
	v_mov_b32_e32 v140, v92
	v_add_f32_e32 v2, 1.0, v2
	v_rcp_f32_e32 v143, v2
	s_nop 0
; __device__ __forceinline__ float bflo(unsigned v) { return __uint_as_float(v << 16); }
; __device__ __forceinline__ float bfhi(unsigned v) { return __uint_as_float(v & 0xffff0000u); }
; __device__ __forceinline__ float siluf_(float x) { return x * __builtin_amdgcn_rcpf(1.0f + __expf(-x)); }
;   __device__ __forceinline__ void operator()(EPI_ARGS) const {
;     ...
;         for (int m = 0; m < 4; ++m) {
;           const size_t row = row0 + ai * HALF + m * 16;
;           const f32x4 v0 = acc[ai][bj][m][0], v1 = acc[ai][bj][m][1];
;           u32x4 o;
;           o.x = pack2(v0[0] * s0[0] * siluf_(bflo(z[m].x)), v0[1] * s0[1] * siluf_(bfhi(z[m].x)));
;           o.y = pack2(v0[2] * s0[2] * siluf_(bflo(z[m].y)), v0[3] * s0[3] * siluf_(bfhi(z[m].y)));
;           o.z = pack2(v1[0] * s1[0] * siluf_(bflo(z[m].z)), v1[1] * s1[1] * siluf_(bfhi(z[m].z)));
;           o.w = pack2(v1[2] * s1[2] * siluf_(bflo(z[m].w)), v1[3] * s1[3] * siluf_(bfhi(z[m].w)));
;           *(u32x4*)(y0 + row * DM + c) = o;
;         }
	v_pk_mul_f32 v[140:141], v[142:143], v[140:141]
	s_nop 0
	v_mul_f32_e32 v2, v140, v141
	v_and_b32_e32 v141, 0xffff0000, v154
	v_mul_f32_e32 v136, 0xbfb8aa3b, v141
	v_exp_f32_e32 v136, v136
	v_mov_b32_e32 v142, v137
	v_mov_b32_e32 v140, v93
	v_add_f32_e32 v136, 1.0, v136
	v_rcp_f32_e32 v143, v136
	s_nop 0
	v_pk_mul_f32 v[136:137], v[142:143], v[140:141]
	s_nop 0
	v_mul_f32_e32 v136, v136, v137
	v_lshlrev_b32_e32 v137, 16, v155
	v_cvt_pk_bf16_f32 v154, v2, v136
	v_mul_f32_e32 v2, 0xbfb8aa3b, v137
	v_exp_f32_e32 v2, v2
	v_mov_b32_e32 v140, v138
	v_mov_b32_e32 v136, v94
	v_mov_b32_e32 v142, v128
	v_add_f32_e32 v2, 1.0, v2
	v_rcp_f32_e32 v141, v2
	v_mov_b32_e32 v138, v100
	v_pk_mul_f32 v[136:137], v[140:141], v[136:137]
	s_nop 0
	v_mul_f32_e32 v2, v136, v137
	v_and_b32_e32 v137, 0xffff0000, v155
	v_mul_f32_e32 v136, 0xbfb8aa3b, v137
	v_exp_f32_e32 v136, v136
	v_mov_b32_e32 v140, v139
	v_lshlrev_b32_e32 v139, 16, v148
	v_add_f32_e32 v136, 1.0, v136
	v_rcp_f32_e32 v141, v136
	v_mov_b32_e32 v136, v95
	v_pk_mul_f32 v[136:137], v[140:141], v[136:137]
	s_nop 0
	v_mul_f32_e32 v136, v136, v137
	v_cvt_pk_bf16_f32 v155, v2, v136
	v_mul_f32_e32 v2, 0xbfb8aa3b, v139
	v_exp_f32_e32 v2, v2
	v_lshlrev_b64 v[140:141], 1, v[196:197]
	v_lshlrev_b64 v[136:137], 12, v[186:187]
	v_lshl_add_u64 v[136:137], s[8:9], 0, v[136:137]
	v_add_f32_e32 v2, 1.0, v2
	v_rcp_f32_e32 v143, v2
	v_lshl_add_u64 v[136:137], v[136:137], 0, v[140:141]
	flat_store_dwordx4 v[136:137], v[152:155]
	v_pk_mul_f32 v[138:139], v[142:143], v[138:139]
	s_nop 0
	v_mul_f32_e32 v2, v138, v139
	v_and_b32_e32 v139, 0xffff0000, v148
	v_mul_f32_e32 v128, 0xbfb8aa3b, v139
	v_exp_f32_e32 v128, v128
	v_mov_b32_e32 v142, v129
	v_mov_b32_e32 v138, v101
	v_add_f32_e32 v128, 1.0, v128
	v_rcp_f32_e32 v143, v128
	s_nop 0
	v_pk_mul_f32 v[128:129], v[142:143], v[138:139]
	s_nop 0
	v_mul_f32_e32 v128, v128, v129
	v_lshlrev_b32_e32 v139, 16, v149
	v_cvt_pk_bf16_f32 v128, v2, v128
	v_mul_f32_e32 v2, 0xbfb8aa3b, v139
	v_exp_f32_e32 v2, v2
	v_mov_b32_e32 v142, v130
	v_mov_b32_e32 v138, v102
	v_add_f32_e32 v2, 1.0, v2
	v_rcp_f32_e32 v143, v2
	s_nop 0
	v_pk_mul_f32 v[138:139], v[142:143], v[138:139]
	s_nop 0
	v_mul_f32_e32 v2, v138, v139
	v_and_b32_e32 v139, 0xffff0000, v149
	v_mul_f32_e32 v129, 0xbfb8aa3b, v139
	v_exp_f32_e32 v129, v129
	v_mov_b32_e32 v142, v131
	v_mov_b32_e32 v138, v103
	v_lshl_add_u64 v[148:149], v[186:187], 0, s[52:53]
	v_add_f32_e32 v129, 1.0, v129
	v_rcp_f32_e32 v143, v129
	s_nop 0
	v_pk_mul_f32 v[130:131], v[142:143], v[138:139]
	s_nop 0
	v_mul_f32_e32 v129, v130, v131
	v_lshlrev_b32_e32 v131, 16, v150
	v_cvt_pk_bf16_f32 v129, v2, v129
	v_mul_f32_e32 v2, 0xbfb8aa3b, v131
	v_exp_f32_e32 v2, v2
	v_mov_b32_e32 v138, v124
	v_mov_b32_e32 v130, v92
	v_add_f32_e32 v2, 1.0, v2
	v_rcp_f32_e32 v139, v2
	s_nop 0
	v_pk_mul_f32 v[130:131], v[138:139], v[130:131]
	s_nop 0
	v_mul_f32_e32 v2, v130, v131
	v_and_b32_e32 v131, 0xffff0000, v150
	v_mul_f32_e32 v124, 0xbfb8aa3b, v131
	v_exp_f32_e32 v124, v124
	v_mov_b32_e32 v138, v125
	v_mov_b32_e32 v130, v93
	v_add_f32_e32 v124, 1.0, v124
	v_rcp_f32_e32 v139, v124
	s_nop 0
	v_pk_mul_f32 v[124:125], v[138:139], v[130:131]
	s_nop 0
	v_mul_f32_e32 v124, v124, v125
	v_lshlrev_b32_e32 v125, 16, v151
	v_cvt_pk_bf16_f32 v130, v2, v124
	v_mul_f32_e32 v2, 0xbfb8aa3b, v125
	v_exp_f32_e32 v2, v2
	v_mov_b32_e32 v138, v126
	v_mov_b32_e32 v124, v94
	v_mov_b32_e32 v126, v100
	v_add_f32_e32 v2, 1.0, v2
	v_rcp_f32_e32 v139, v2
	s_nop 0
	v_pk_mul_f32 v[124:125], v[138:139], v[124:125]
	s_nop 0
	v_mul_f32_e32 v2, v124, v125
	v_and_b32_e32 v125, 0xffff0000, v151
	v_mul_f32_e32 v124, 0xbfb8aa3b, v125
	v_exp_f32_e32 v124, v124
	v_mov_b32_e32 v138, v127
	v_lshlrev_b32_e32 v127, 16, v144
	v_add_f32_e32 v124, 1.0, v124
	v_rcp_f32_e32 v139, v124
	v_mov_b32_e32 v124, v95
	v_pk_mul_f32 v[124:125], v[138:139], v[124:125]
	s_nop 0
	v_mul_f32_e32 v124, v124, v125
	v_cvt_pk_bf16_f32 v131, v2, v124
	v_mul_f32_e32 v2, 0xbfb8aa3b, v127
	v_exp_f32_e32 v2, v2
	v_lshlrev_b64 v[124:125], 12, v[194:195]
	v_lshl_add_u64 v[124:125], s[8:9], 0, v[124:125]
	v_lshl_add_u64 v[124:125], v[124:125], 0, v[140:141]
	v_add_f32_e32 v2, 1.0, v2
	flat_store_dwordx4 v[124:125], v[128:131]
	s_nop 1
	v_rcp_f32_e32 v129, v2
	v_mov_b32_e32 v128, v120
	v_lshlrev_b64 v[130:131], 9, v[148:149]
	v_pk_mul_f32 v[126:127], v[128:129], v[126:127]
	s_nop 0
	v_mul_f32_e32 v2, v126, v127
	v_and_b32_e32 v127, 0xffff0000, v144
	v_mul_f32_e32 v120, 0xbfb8aa3b, v127
	v_exp_f32_e32 v120, v120
	v_mov_b32_e32 v128, v121
	v_mov_b32_e32 v126, v101
	v_add_f32_e32 v120, 1.0, v120
	v_rcp_f32_e32 v129, v120
	s_nop 0
	v_pk_mul_f32 v[120:121], v[128:129], v[126:127]
	s_nop 0
	v_mul_f32_e32 v120, v120, v121
	v_lshlrev_b32_e32 v127, 16, v145
	v_cvt_pk_bf16_f32 v120, v2, v120
	v_mul_f32_e32 v2, 0xbfb8aa3b, v127
	v_exp_f32_e32 v2, v2
	v_mov_b32_e32 v128, v122
	v_mov_b32_e32 v126, v102
	v_add_f32_e32 v2, 1.0, v2
	v_rcp_f32_e32 v129, v2
	s_nop 0
	v_pk_mul_f32 v[126:127], v[128:129], v[126:127]
	s_nop 0
	v_mul_f32_e32 v2, v126, v127
	v_and_b32_e32 v127, 0xffff0000, v145
	v_mul_f32_e32 v121, 0xbfb8aa3b, v127
	v_exp_f32_e32 v121, v121
	v_mov_b32_e32 v128, v123
	v_mov_b32_e32 v126, v103
	v_add_f32_e32 v121, 1.0, v121
	v_rcp_f32_e32 v129, v121
	s_nop 0
	v_pk_mul_f32 v[122:123], v[128:129], v[126:127]
	s_nop 0
	v_mul_f32_e32 v121, v122, v123
	v_lshlrev_b32_e32 v123, 16, v146
	v_cvt_pk_bf16_f32 v121, v2, v121
	v_mul_f32_e32 v2, 0xbfb8aa3b, v123
	v_exp_f32_e32 v2, v2
	v_mov_b32_e32 v126, v116
	v_mov_b32_e32 v122, v92
	v_add_f32_e32 v2, 1.0, v2
	v_rcp_f32_e32 v127, v2
	s_nop 0
	v_pk_mul_f32 v[122:123], v[126:127], v[122:123]
	s_nop 0
	v_mul_f32_e32 v2, v122, v123
; __device__ __forceinline__ size_t pidx(size_t row, int col) { return ((size_t)(col >> 8) * MTOK + row) * PLD + (col & 255); }
; __device__ __forceinline__ float bflo(unsigned v) { return __uint_as_float(v << 16); }
; __device__ __forceinline__ float bfhi(unsigned v) { return __uint_as_float(v & 0xffff0000u); }
; __device__ __forceinline__ float siluf_(float x) { return x * __builtin_amdgcn_rcpf(1.0f + __expf(-x)); }
;   __device__ __forceinline__ void operator()(EPI_ARGS) const {
;     ...
;         for (int m = 0; m < 4; ++m) z[m] = *(const u32x4*)(proj + pidx(row0 + ai * HALF + m * 16, PZ + c));
;         __builtin_amdgcn_sched_barrier(0);
; #pragma unroll
;         for (int m = 0; m < 4; ++m) {
;           const size_t row = row0 + ai * HALF + m * 16;
;           const f32x4 v0 = acc[ai][bj][m][0], v1 = acc[ai][bj][m][1];
;           u32x4 o;
;           o.x = pack2(v0[0] * s0[0] * siluf_(bflo(z[m].x)), v0[1] * s0[1] * siluf_(bfhi(z[m].x)));
;           o.y = pack2(v0[2] * s0[2] * siluf_(bflo(z[m].y)), v0[3] * s0[3] * siluf_(bfhi(z[m].y)));
;           o.z = pack2(v1[0] * s1[0] * siluf_(bflo(z[m].z)), v1[1] * s1[1] * siluf_(bfhi(z[m].z)));
;           o.w = pack2(v1[2] * s1[2] * siluf_(bflo(z[m].w)), v1[3] * s1[3] * siluf_(bfhi(z[m].w)));
;           *(u32x4*)(y0 + row * DM + c) = o;
;         }
	v_and_b32_e32 v123, 0xffff0000, v146
	v_mul_f32_e32 v116, 0xbfb8aa3b, v123
	v_exp_f32_e32 v116, v116
	v_mov_b32_e32 v126, v117
	v_mov_b32_e32 v122, v93
	v_add_f32_e32 v116, 1.0, v116
	v_rcp_f32_e32 v127, v116
	s_nop 0
	v_pk_mul_f32 v[116:117], v[126:127], v[122:123]
	s_nop 0
	v_mul_f32_e32 v116, v116, v117
	v_lshlrev_b32_e32 v117, 16, v147
	v_cvt_pk_bf16_f32 v122, v2, v116
	v_mul_f32_e32 v2, 0xbfb8aa3b, v117
	v_exp_f32_e32 v2, v2
	v_mov_b32_e32 v126, v118
	v_mov_b32_e32 v116, v94
	v_mov_b32_e32 v118, v112
	v_add_f32_e32 v2, 1.0, v2
	v_rcp_f32_e32 v127, v2
	s_nop 0
	v_pk_mul_f32 v[116:117], v[126:127], v[116:117]
	s_nop 0
	v_mul_f32_e32 v2, v116, v117
	v_and_b32_e32 v117, 0xffff0000, v147
	v_mul_f32_e32 v116, 0xbfb8aa3b, v117
	v_exp_f32_e32 v116, v116
	v_mov_b32_e32 v126, v119
	v_lshl_add_u64 v[146:147], v[186:187], 0, s[4:5]
	s_mov_b64 s[4:5], 0xa0
	v_add_f32_e32 v116, 1.0, v116
	v_rcp_f32_e32 v127, v116
	v_mov_b32_e32 v116, v95
	v_lshl_add_u64 v[144:145], v[186:187], 0, s[4:5]
	s_mov_b64 s[4:5], 0xb0
	v_pk_mul_f32 v[116:117], v[126:127], v[116:117]
	v_lshl_add_u64 v[142:143], v[186:187], 0, s[4:5]
	v_mul_f32_e32 v116, v116, v117
	v_cvt_pk_bf16_f32 v123, v2, v116
	v_lshlrev_b64 v[116:117], 12, v[192:193]
	v_lshl_add_u64 v[116:117], s[8:9], 0, v[116:117]
	v_lshl_add_u64 v[128:129], v[116:117], 0, v[140:141]
	v_lshlrev_b32_e32 v117, 16, v132
	v_mul_f32_e32 v2, 0xbfb8aa3b, v117
	v_exp_f32_e32 v2, v2
	v_mov_b32_e32 v116, v100
	flat_store_dwordx4 v[128:129], v[120:123]
	v_lshlrev_b64 v[138:139], 9, v[142:143]
	v_add_f32_e32 v2, 1.0, v2
	v_rcp_f32_e32 v119, v2
	s_nop 0
	v_pk_mul_f32 v[116:117], v[118:119], v[116:117]
	s_nop 0
	v_mul_f32_e32 v2, v116, v117
	v_and_b32_e32 v117, 0xffff0000, v132
	v_mul_f32_e32 v112, 0xbfb8aa3b, v117
	v_exp_f32_e32 v112, v112
	v_mov_b32_e32 v118, v113
	v_mov_b32_e32 v116, v101
	v_add_f32_e32 v112, 1.0, v112
	v_rcp_f32_e32 v119, v112
	s_nop 0
	v_pk_mul_f32 v[112:113], v[118:119], v[116:117]
	s_nop 0
	v_mul_f32_e32 v112, v112, v113
	v_lshlrev_b32_e32 v117, 16, v133
	v_cvt_pk_bf16_f32 v112, v2, v112
	v_mul_f32_e32 v2, 0xbfb8aa3b, v117
	v_exp_f32_e32 v2, v2
	v_mov_b32_e32 v118, v114
	v_mov_b32_e32 v116, v102
	v_add_f32_e32 v2, 1.0, v2
	v_rcp_f32_e32 v119, v2
	s_nop 0
	v_pk_mul_f32 v[116:117], v[118:119], v[116:117]
	s_nop 0
	v_mul_f32_e32 v2, v116, v117
	v_and_b32_e32 v117, 0xffff0000, v133
	v_mul_f32_e32 v113, 0xbfb8aa3b, v117
	v_exp_f32_e32 v113, v113
	v_mov_b32_e32 v118, v115
	v_mov_b32_e32 v116, v103
	v_lshlrev_b64 v[132:133], 9, v[146:147]
	v_add_f32_e32 v113, 1.0, v113
	v_rcp_f32_e32 v119, v113
	s_nop 0
	v_pk_mul_f32 v[114:115], v[118:119], v[116:117]
	s_nop 0
	v_mul_f32_e32 v113, v114, v115
	v_lshlrev_b32_e32 v115, 16, v134
	v_cvt_pk_bf16_f32 v113, v2, v113
	v_mul_f32_e32 v2, 0xbfb8aa3b, v115
	v_exp_f32_e32 v2, v2
	v_mov_b32_e32 v116, v108
	v_mov_b32_e32 v114, v92
	v_add_f32_e32 v2, 1.0, v2
	v_rcp_f32_e32 v117, v2
	s_nop 0
	v_pk_mul_f32 v[114:115], v[116:117], v[114:115]
	s_nop 0
	v_mul_f32_e32 v2, v114, v115
	v_and_b32_e32 v115, 0xffff0000, v134
	v_mul_f32_e32 v108, 0xbfb8aa3b, v115
	v_exp_f32_e32 v108, v108
	v_mov_b32_e32 v116, v109
	v_mov_b32_e32 v114, v93
	v_add_f32_e32 v108, 1.0, v108
	v_rcp_f32_e32 v117, v108
	s_nop 0
	v_pk_mul_f32 v[108:109], v[116:117], v[114:115]
	s_nop 0
	v_mul_f32_e32 v108, v108, v109
	v_lshlrev_b32_e32 v109, 16, v135
	v_cvt_pk_bf16_f32 v114, v2, v108
	v_mul_f32_e32 v2, 0xbfb8aa3b, v109
	v_exp_f32_e32 v2, v2
	v_mov_b32_e32 v116, v110
	v_mov_b32_e32 v108, v94
	v_add_f32_e32 v2, 1.0, v2
	v_rcp_f32_e32 v117, v2
	s_nop 0
	v_pk_mul_f32 v[108:109], v[116:117], v[108:109]
	s_nop 0
	v_mul_f32_e32 v2, v108, v109
	v_and_b32_e32 v109, 0xffff0000, v135
	v_mul_f32_e32 v108, 0xbfb8aa3b, v109
	v_exp_f32_e32 v108, v108
	v_mov_b32_e32 v116, v111
	v_lshlrev_b64 v[134:135], 9, v[144:145]
	v_add_f32_e32 v108, 1.0, v108
	v_rcp_f32_e32 v117, v108
	v_mov_b32_e32 v108, v95
	v_pk_mul_f32 v[108:109], v[116:117], v[108:109]
	s_nop 0
	v_mul_f32_e32 v108, v108, v109
	v_cvt_pk_bf16_f32 v115, v2, v108
	v_lshlrev_b64 v[108:109], 12, v[190:191]
	v_lshl_add_u64 v[108:109], s[8:9], 0, v[108:109]
	v_lshl_add_u64 v[126:127], v[108:109], 0, v[140:141]
	flat_store_dwordx4 v[126:127], v[112:115]
	v_lshl_add_u64 v[108:109], v[188:189], 0, v[130:131]
	flat_load_dwordx4 v[120:123], v[108:109]
	v_lshl_add_u64 v[108:109], v[188:189], 0, v[132:133]
	flat_load_dwordx4 v[116:119], v[108:109]
	v_lshl_add_u64 v[108:109], v[188:189], 0, v[134:135]
	flat_load_dwordx4 v[112:115], v[108:109]
	v_lshl_add_u64 v[108:109], v[188:189], 0, v[138:139]
	flat_load_dwordx4 v[108:111], v[108:109]
	s_waitcnt vmcnt(0) lgkmcnt(0)
; __device__ __forceinline__ float bflo(unsigned v) { return __uint_as_float(v << 16); }
; __device__ __forceinline__ float bfhi(unsigned v) { return __uint_as_float(v & 0xffff0000u); }
; __device__ __forceinline__ float siluf_(float x) { return x * __builtin_amdgcn_rcpf(1.0f + __expf(-x)); }
;   __device__ __forceinline__ void operator()(EPI_ARGS) const {
;     ...
;         for (int m = 0; m < 4; ++m) {
;           const size_t row = row0 + ai * HALF + m * 16;
;           const f32x4 v0 = acc[ai][bj][m][0], v1 = acc[ai][bj][m][1];
;           u32x4 o;
;           o.x = pack2(v0[0] * s0[0] * siluf_(bflo(z[m].x)), v0[1] * s0[1] * siluf_(bfhi(z[m].x)));
;           o.y = pack2(v0[2] * s0[2] * siluf_(bflo(z[m].y)), v0[3] * s0[3] * siluf_(bfhi(z[m].y)));
;           o.z = pack2(v1[0] * s1[0] * siluf_(bflo(z[m].z)), v1[1] * s1[1] * siluf_(bfhi(z[m].z)));
;           o.w = pack2(v1[2] * s1[2] * siluf_(bflo(z[m].w)), v1[3] * s1[3] * siluf_(bfhi(z[m].w)));
;           *(u32x4*)(y0 + row * DM + c) = o;
;         }
	v_lshlrev_b32_e32 v151, 16, v120
	v_mul_f32_e32 v2, 0xbfb8aa3b, v151
	v_exp_f32_e32 v2, v2
	v_mov_b32_e32 v152, v104
	v_mov_b32_e32 v150, v100
	v_mov_b32_e32 v175, v3
	v_add_f32_e32 v2, 1.0, v2
	v_rcp_f32_e32 v153, v2
	s_nop 0
	v_pk_mul_f32 v[150:151], v[152:153], v[150:151]
	s_nop 0
	v_mul_f32_e32 v2, v150, v151
	v_and_b32_e32 v151, 0xffff0000, v120
	v_mul_f32_e32 v104, 0xbfb8aa3b, v151
	v_exp_f32_e32 v104, v104
	v_mov_b32_e32 v152, v105
	v_mov_b32_e32 v150, v101
	v_mov_b32_e32 v120, v103
	v_add_f32_e32 v104, 1.0, v104
	v_rcp_f32_e32 v153, v104
	s_nop 0
	v_pk_mul_f32 v[104:105], v[152:153], v[150:151]
	s_nop 0
	v_mul_f32_e32 v104, v104, v105
	v_lshlrev_b32_e32 v151, 16, v121
	v_cvt_pk_bf16_f32 v104, v2, v104
	v_mul_f32_e32 v2, 0xbfb8aa3b, v151
	v_exp_f32_e32 v2, v2
	v_and_b32_e32 v121, 0xffff0000, v121
	v_mul_f32_e32 v105, 0xbfb8aa3b, v121
	v_exp_f32_e32 v105, v105
	v_add_f32_e32 v2, 1.0, v2
	v_rcp_f32_e32 v153, v2
	v_mov_b32_e32 v152, v106
	v_mov_b32_e32 v150, v102
	v_add_f32_e32 v105, 1.0, v105
	v_pk_mul_f32 v[150:151], v[152:153], v[150:151]
	s_nop 0
	v_mul_f32_e32 v2, v150, v151
	v_rcp_f32_e32 v151, v105
	v_mov_b32_e32 v150, v107
	v_pk_mul_f32 v[106:107], v[150:151], v[120:121]
	s_nop 0
	v_mul_f32_e32 v105, v106, v107
	v_lshlrev_b32_e32 v107, 16, v122
	v_cvt_pk_bf16_f32 v105, v2, v105
	v_mul_f32_e32 v2, 0xbfb8aa3b, v107
	v_exp_f32_e32 v2, v2
	v_mov_b32_e32 v120, v96
	v_mov_b32_e32 v106, v92
	v_add_f32_e32 v2, 1.0, v2
	v_rcp_f32_e32 v121, v2
	s_nop 0
	v_pk_mul_f32 v[106:107], v[120:121], v[106:107]
	s_nop 0
	v_mul_f32_e32 v2, v106, v107
	v_and_b32_e32 v107, 0xffff0000, v122
	v_mul_f32_e32 v96, 0xbfb8aa3b, v107
	v_exp_f32_e32 v96, v96
	v_mov_b32_e32 v120, v97
	v_mov_b32_e32 v106, v93
	v_add_f32_e32 v96, 1.0, v96
	v_rcp_f32_e32 v121, v96
	s_nop 0
	v_pk_mul_f32 v[96:97], v[120:121], v[106:107]
	s_nop 0
	v_mul_f32_e32 v96, v96, v97
	v_lshlrev_b32_e32 v97, 16, v123
	v_cvt_pk_bf16_f32 v106, v2, v96
	v_mul_f32_e32 v2, 0xbfb8aa3b, v97
	v_exp_f32_e32 v2, v2
	v_mov_b32_e32 v120, v98
	v_mov_b32_e32 v96, v94
	v_mov_b32_e32 v98, v100
	v_add_f32_e32 v2, 1.0, v2
	v_rcp_f32_e32 v121, v2
	s_nop 0
	v_pk_mul_f32 v[96:97], v[120:121], v[96:97]
	s_nop 0
	v_mul_f32_e32 v2, v96, v97
	v_and_b32_e32 v97, 0xffff0000, v123
	v_mul_f32_e32 v96, 0xbfb8aa3b, v97
	v_exp_f32_e32 v96, v96
	v_mov_b32_e32 v120, v99
	v_lshlrev_b32_e32 v99, 16, v116
	v_add_f32_e32 v96, 1.0, v96
	v_rcp_f32_e32 v121, v96
	v_mov_b32_e32 v96, v95
	v_pk_mul_f32 v[96:97], v[120:121], v[96:97]
	s_nop 0
	v_mul_f32_e32 v96, v96, v97
	v_cvt_pk_bf16_f32 v107, v2, v96
	v_mul_f32_e32 v2, 0xbfb8aa3b, v99
	v_exp_f32_e32 v2, v2
	v_lshlrev_b64 v[96:97], 12, v[148:149]
	v_lshl_add_u64 v[96:97], s[8:9], 0, v[96:97]
	v_lshl_add_u64 v[96:97], v[96:97], 0, v[140:141]
	v_add_f32_e32 v2, 1.0, v2
	flat_store_dwordx4 v[96:97], v[104:107]
	s_nop 1
	v_rcp_f32_e32 v105, v2
	v_mov_b32_e32 v104, v88
	v_pk_mul_f32 v[98:99], v[104:105], v[98:99]
	s_nop 0
	v_mul_f32_e32 v2, v98, v99
	v_and_b32_e32 v99, 0xffff0000, v116
	v_mul_f32_e32 v88, 0xbfb8aa3b, v99
	v_exp_f32_e32 v88, v88
	v_mov_b32_e32 v104, v89
	v_mov_b32_e32 v98, v101
	v_add_f32_e32 v88, 1.0, v88
	v_rcp_f32_e32 v105, v88
	s_nop 0
	v_pk_mul_f32 v[88:89], v[104:105], v[98:99]
	s_nop 0
	v_mul_f32_e32 v88, v88, v89
	v_lshlrev_b32_e32 v99, 16, v117
	v_cvt_pk_bf16_f32 v88, v2, v88
	v_mul_f32_e32 v2, 0xbfb8aa3b, v99
	v_exp_f32_e32 v2, v2
	v_mov_b32_e32 v104, v90
	v_mov_b32_e32 v98, v102
	v_add_f32_e32 v2, 1.0, v2
	v_rcp_f32_e32 v105, v2
	s_nop 0
	v_pk_mul_f32 v[98:99], v[104:105], v[98:99]
	s_nop 0
	v_mul_f32_e32 v2, v98, v99
	v_and_b32_e32 v99, 0xffff0000, v117
	v_mul_f32_e32 v89, 0xbfb8aa3b, v99
	v_exp_f32_e32 v89, v89
	v_mov_b32_e32 v104, v91
	v_mov_b32_e32 v98, v103
	v_add_f32_e32 v89, 1.0, v89
	v_rcp_f32_e32 v105, v89
	s_nop 0
	v_pk_mul_f32 v[90:91], v[104:105], v[98:99]
	s_nop 0
	v_mul_f32_e32 v89, v90, v91
	v_lshlrev_b32_e32 v91, 16, v118
	v_cvt_pk_bf16_f32 v89, v2, v89
	v_mul_f32_e32 v2, 0xbfb8aa3b, v91
	v_exp_f32_e32 v2, v2
	v_mov_b32_e32 v98, v84
	v_mov_b32_e32 v90, v92
	v_add_f32_e32 v2, 1.0, v2
	v_rcp_f32_e32 v99, v2
	s_nop 0
	v_pk_mul_f32 v[90:91], v[98:99], v[90:91]
	s_nop 0
	v_mul_f32_e32 v2, v90, v91
	v_and_b32_e32 v91, 0xffff0000, v118
	v_mul_f32_e32 v84, 0xbfb8aa3b, v91
	v_exp_f32_e32 v84, v84
	v_mov_b32_e32 v98, v85
	v_mov_b32_e32 v90, v93
	v_add_f32_e32 v84, 1.0, v84
	v_rcp_f32_e32 v99, v84
	s_nop 0
	v_pk_mul_f32 v[84:85], v[98:99], v[90:91]
	s_nop 0
	v_mul_f32_e32 v84, v84, v85
	v_lshlrev_b32_e32 v85, 16, v119
	v_cvt_pk_bf16_f32 v90, v2, v84
	v_mul_f32_e32 v2, 0xbfb8aa3b, v85
	v_exp_f32_e32 v2, v2
	v_mov_b32_e32 v98, v86
	v_mov_b32_e32 v84, v94
	v_mov_b32_e32 v86, v80
	v_add_f32_e32 v2, 1.0, v2
	v_rcp_f32_e32 v99, v2
	s_nop 0
	v_pk_mul_f32 v[84:85], v[98:99], v[84:85]
	s_nop 0
	v_mul_f32_e32 v2, v84, v85
	v_and_b32_e32 v85, 0xffff0000, v119
	v_mul_f32_e32 v84, 0xbfb8aa3b, v85
	v_exp_f32_e32 v84, v84
	v_mov_b32_e32 v98, v87
	v_add_f32_e32 v84, 1.0, v84
	v_rcp_f32_e32 v99, v84
	v_mov_b32_e32 v84, v95
	v_pk_mul_f32 v[84:85], v[98:99], v[84:85]
	s_nop 0
	v_mul_f32_e32 v84, v84, v85
	v_cvt_pk_bf16_f32 v91, v2, v84
	v_lshlrev_b64 v[84:85], 12, v[146:147]
	v_lshl_add_u64 v[84:85], s[8:9], 0, v[84:85]
	v_lshl_add_u64 v[98:99], v[84:85], 0, v[140:141]
	v_lshlrev_b32_e32 v85, 16, v112
	v_mul_f32_e32 v2, 0xbfb8aa3b, v85
	v_exp_f32_e32 v2, v2
	v_mov_b32_e32 v84, v100
	flat_store_dwordx4 v[98:99], v[88:91]
	v_add_f32_e32 v2, 1.0, v2
	v_rcp_f32_e32 v87, v2
	s_nop 0
	v_pk_mul_f32 v[84:85], v[86:87], v[84:85]
	s_nop 0
	v_mul_f32_e32 v2, v84, v85
	v_and_b32_e32 v85, 0xffff0000, v112
	v_mul_f32_e32 v80, 0xbfb8aa3b, v85
	v_exp_f32_e32 v80, v80
	v_mov_b32_e32 v86, v81
; __device__ __forceinline__ size_t pidx(size_t row, int col) { return ((size_t)(col >> 8) * MTOK + row) * PLD + (col & 255); }
; __device__ __forceinline__ float bflo(unsigned v) { return __uint_as_float(v << 16); }
; __device__ __forceinline__ float bfhi(unsigned v) { return __uint_as_float(v & 0xffff0000u); }
; __device__ __forceinline__ float siluf_(float x) { return x * __builtin_amdgcn_rcpf(1.0f + __expf(-x)); }
;   __device__ __forceinline__ void operator()(EPI_ARGS) const {
;     ...
;     for (int bj = 0; bj < 2; ++bj) {
;       const int c = col0 + bj * HALF;
;       const f32x4 s0 = *(const f32x4*)(psc + c), s1 = *(const f32x4*)(psc + c + 4);
; #pragma unroll
;       for (int ai = 0; ai < 2; ++ai) {
;         u32x4 z[4];
; #pragma unroll
;         for (int m = 0; m < 4; ++m) z[m] = *(const u32x4*)(proj + pidx(row0 + ai * HALF + m * 16, PZ + c));
;         __builtin_amdgcn_sched_barrier(0);
; #pragma unroll
;         for (int m = 0; m < 4; ++m) {
;           const size_t row = row0 + ai * HALF + m * 16;
;           const f32x4 v0 = acc[ai][bj][m][0], v1 = acc[ai][bj][m][1];
;           u32x4 o;
;           o.x = pack2(v0[0] * s0[0] * siluf_(bflo(z[m].x)), v0[1] * s0[1] * siluf_(bfhi(z[m].x)));
;           o.y = pack2(v0[2] * s0[2] * siluf_(bflo(z[m].y)), v0[3] * s0[3] * siluf_(bfhi(z[m].y)));
;           o.z = pack2(v1[0] * s1[0] * siluf_(bflo(z[m].z)), v1[1] * s1[1] * siluf_(bfhi(z[m].z)));
;           o.w = pack2(v1[2] * s1[2] * siluf_(bflo(z[m].w)), v1[3] * s1[3] * siluf_(bfhi(z[m].w)));
;           *(u32x4*)(y0 + row * DM + c) = o;
;         }
	v_mov_b32_e32 v84, v101
	v_add_f32_e32 v80, 1.0, v80
	v_rcp_f32_e32 v87, v80
	s_nop 0
	v_pk_mul_f32 v[80:81], v[86:87], v[84:85]
	s_nop 0
	v_mul_f32_e32 v80, v80, v81
	v_lshlrev_b32_e32 v85, 16, v113
	v_cvt_pk_bf16_f32 v80, v2, v80
	v_mul_f32_e32 v2, 0xbfb8aa3b, v85
	v_exp_f32_e32 v2, v2
	v_mov_b32_e32 v86, v82
	v_mov_b32_e32 v84, v102
	v_add_f32_e32 v2, 1.0, v2
	v_rcp_f32_e32 v87, v2
	s_nop 0
	v_pk_mul_f32 v[84:85], v[86:87], v[84:85]
	s_nop 0
	v_mul_f32_e32 v2, v84, v85
	v_and_b32_e32 v85, 0xffff0000, v113
	v_mul_f32_e32 v81, 0xbfb8aa3b, v85
	v_exp_f32_e32 v81, v81
	v_mov_b32_e32 v86, v83
	v_mov_b32_e32 v84, v103
	v_add_f32_e32 v81, 1.0, v81
	v_rcp_f32_e32 v87, v81
	s_nop 0
	v_pk_mul_f32 v[82:83], v[86:87], v[84:85]
	s_nop 0
	v_mul_f32_e32 v81, v82, v83
	v_lshlrev_b32_e32 v83, 16, v114
	v_cvt_pk_bf16_f32 v81, v2, v81
	v_mul_f32_e32 v2, 0xbfb8aa3b, v83
	v_exp_f32_e32 v2, v2
	v_mov_b32_e32 v84, v76
	v_mov_b32_e32 v82, v92
	v_add_f32_e32 v2, 1.0, v2
	v_rcp_f32_e32 v85, v2
	s_nop 0
	v_pk_mul_f32 v[82:83], v[84:85], v[82:83]
	s_nop 0
	v_mul_f32_e32 v2, v82, v83
	v_and_b32_e32 v83, 0xffff0000, v114
	v_mul_f32_e32 v76, 0xbfb8aa3b, v83
	v_exp_f32_e32 v76, v76
	v_mov_b32_e32 v84, v77
	v_mov_b32_e32 v82, v93
	v_add_f32_e32 v76, 1.0, v76
	v_rcp_f32_e32 v85, v76
	s_nop 0
	v_pk_mul_f32 v[76:77], v[84:85], v[82:83]
	s_nop 0
	v_mul_f32_e32 v76, v76, v77
	v_lshlrev_b32_e32 v77, 16, v115
	v_cvt_pk_bf16_f32 v82, v2, v76
	v_mul_f32_e32 v2, 0xbfb8aa3b, v77
	v_exp_f32_e32 v2, v2
	v_mov_b32_e32 v84, v78
	v_mov_b32_e32 v76, v94
	v_mov_b32_e32 v78, v72
	v_add_f32_e32 v2, 1.0, v2
	v_rcp_f32_e32 v85, v2
	s_nop 0
	v_pk_mul_f32 v[76:77], v[84:85], v[76:77]
	s_nop 0
	v_mul_f32_e32 v2, v76, v77
	v_and_b32_e32 v77, 0xffff0000, v115
	v_mul_f32_e32 v76, 0xbfb8aa3b, v77
	v_exp_f32_e32 v76, v76
	v_mov_b32_e32 v84, v79
	v_add_f32_e32 v76, 1.0, v76
	v_rcp_f32_e32 v85, v76
	v_mov_b32_e32 v76, v95
	v_pk_mul_f32 v[76:77], v[84:85], v[76:77]
	s_nop 0
	v_mul_f32_e32 v76, v76, v77
	v_cvt_pk_bf16_f32 v83, v2, v76
	v_lshlrev_b64 v[76:77], 12, v[144:145]
	v_lshl_add_u64 v[76:77], s[8:9], 0, v[76:77]
	v_lshl_add_u64 v[104:105], v[76:77], 0, v[140:141]
	v_lshlrev_b32_e32 v77, 16, v108
	v_mul_f32_e32 v2, 0xbfb8aa3b, v77
	v_exp_f32_e32 v2, v2
	v_mov_b32_e32 v76, v100
	flat_store_dwordx4 v[104:105], v[80:83]
	v_add_f32_e32 v2, 1.0, v2
	v_rcp_f32_e32 v79, v2
	s_nop 0
	v_pk_mul_f32 v[76:77], v[78:79], v[76:77]
	s_nop 0
	v_mul_f32_e32 v2, v76, v77
	v_and_b32_e32 v77, 0xffff0000, v108
	v_mul_f32_e32 v72, 0xbfb8aa3b, v77
	v_exp_f32_e32 v72, v72
	v_mov_b32_e32 v78, v73
	v_mov_b32_e32 v76, v101
	v_add_f32_e32 v72, 1.0, v72
	v_rcp_f32_e32 v79, v72
	s_nop 0
	v_pk_mul_f32 v[72:73], v[78:79], v[76:77]
	s_nop 0
	v_mul_f32_e32 v72, v72, v73
	v_lshlrev_b32_e32 v77, 16, v109
	v_cvt_pk_bf16_f32 v72, v2, v72
	v_mul_f32_e32 v2, 0xbfb8aa3b, v77
	v_exp_f32_e32 v2, v2
	v_mov_b32_e32 v78, v74
	v_mov_b32_e32 v76, v102
	v_add_f32_e32 v2, 1.0, v2
	v_rcp_f32_e32 v79, v2
	s_nop 0
	v_pk_mul_f32 v[76:77], v[78:79], v[76:77]
	s_nop 0
	v_mul_f32_e32 v2, v76, v77
	v_and_b32_e32 v77, 0xffff0000, v109
	v_mul_f32_e32 v73, 0xbfb8aa3b, v77
	v_exp_f32_e32 v73, v73
	v_mov_b32_e32 v78, v75
	v_mov_b32_e32 v76, v103
	v_add_f32_e32 v73, 1.0, v73
	v_rcp_f32_e32 v79, v73
	s_nop 0
	v_pk_mul_f32 v[74:75], v[78:79], v[76:77]
	s_nop 0
	v_mul_f32_e32 v73, v74, v75
	v_lshlrev_b32_e32 v75, 16, v110
	v_cvt_pk_bf16_f32 v73, v2, v73
	v_mul_f32_e32 v2, 0xbfb8aa3b, v75
	v_exp_f32_e32 v2, v2
	v_mov_b32_e32 v76, v68
	v_mov_b32_e32 v74, v92
	v_add_f32_e32 v2, 1.0, v2
	v_rcp_f32_e32 v77, v2
	s_nop 0
	v_pk_mul_f32 v[74:75], v[76:77], v[74:75]
	s_nop 0
	v_mul_f32_e32 v2, v74, v75
	v_and_b32_e32 v75, 0xffff0000, v110
	v_mul_f32_e32 v68, 0xbfb8aa3b, v75
	v_exp_f32_e32 v68, v68
	v_mov_b32_e32 v76, v69
	v_mov_b32_e32 v74, v93
	v_add_f32_e32 v68, 1.0, v68
	v_rcp_f32_e32 v77, v68
	s_nop 0
	v_pk_mul_f32 v[68:69], v[76:77], v[74:75]
	s_nop 0
	v_mul_f32_e32 v68, v68, v69
	v_lshlrev_b32_e32 v69, 16, v111
	v_cvt_pk_bf16_f32 v74, v2, v68
	v_mul_f32_e32 v2, 0xbfb8aa3b, v69
	v_exp_f32_e32 v2, v2
	v_mov_b32_e32 v76, v70
	v_mov_b32_e32 v68, v94
	v_add_f32_e32 v2, 1.0, v2
	v_rcp_f32_e32 v77, v2
	s_nop 0
	v_pk_mul_f32 v[68:69], v[76:77], v[68:69]
	s_nop 0
	v_mul_f32_e32 v2, v68, v69
	v_and_b32_e32 v69, 0xffff0000, v111
	v_mul_f32_e32 v68, 0xbfb8aa3b, v69
	v_exp_f32_e32 v68, v68
	v_mov_b32_e32 v76, v71
	v_add_f32_e32 v68, 1.0, v68
	v_rcp_f32_e32 v77, v68
	v_mov_b32_e32 v68, v95
	v_lshl_add_u64 v[94:95], s[2:3], 0, v[174:175]
	v_pk_mul_f32 v[68:69], v[76:77], v[68:69]
	s_nop 0
	v_mul_f32_e32 v68, v68, v69
	v_cvt_pk_bf16_f32 v75, v2, v68
	v_lshlrev_b64 v[68:69], 12, v[142:143]
	v_lshl_add_u64 v[68:69], s[8:9], 0, v[68:69]
	v_lshl_add_u64 v[92:93], v[68:69], 0, v[140:141]
	flat_store_dwordx4 v[92:93], v[72:75]
	v_lshl_add_u64 v[76:77], v[94:95], 0, v[178:179]
	global_load_dwordx4 v[68:71], v[176:177], off offset:528
	global_load_dwordx4 v[72:75], v[176:177], off offset:512
	flat_load_dwordx4 v[88:91], v[76:77]
	v_lshl_add_u64 v[76:77], v[94:95], 0, v[180:181]
	flat_load_dwordx4 v[84:87], v[76:77]
	v_lshl_add_u64 v[76:77], v[94:95], 0, v[182:183]
	flat_load_dwordx4 v[80:83], v[76:77]
	v_lshl_add_u64 v[76:77], v[94:95], 0, v[184:185]
	flat_load_dwordx4 v[76:79], v[76:77]
	s_waitcnt vmcnt(0) lgkmcnt(0)
; __device__ __forceinline__ float bflo(unsigned v) { return __uint_as_float(v << 16); }
; __device__ __forceinline__ float bfhi(unsigned v) { return __uint_as_float(v & 0xffff0000u); }
; __device__ __forceinline__ float siluf_(float x) { return x * __builtin_amdgcn_rcpf(1.0f + __expf(-x)); }
;   __device__ __forceinline__ void operator()(EPI_ARGS) const {
;     ...
;         for (int m = 0; m < 4; ++m) {
;           const size_t row = row0 + ai * HALF + m * 16;
;           const f32x4 v0 = acc[ai][bj][m][0], v1 = acc[ai][bj][m][1];
;           u32x4 o;
;           o.x = pack2(v0[0] * s0[0] * siluf_(bflo(z[m].x)), v0[1] * s0[1] * siluf_(bfhi(z[m].x)));
;           o.y = pack2(v0[2] * s0[2] * siluf_(bflo(z[m].y)), v0[3] * s0[3] * siluf_(bfhi(z[m].y)));
;           o.z = pack2(v1[0] * s1[0] * siluf_(bflo(z[m].z)), v1[1] * s1[1] * siluf_(bfhi(z[m].z)));
;           o.w = pack2(v1[2] * s1[2] * siluf_(bflo(z[m].w)), v1[3] * s1[3] * siluf_(bfhi(z[m].w)));
;           *(u32x4*)(y0 + row * DM + c) = o;
;         }
	v_lshlrev_b32_e32 v101, 16, v88
	v_mul_f32_e32 v2, 0xbfb8aa3b, v101
	v_exp_f32_e32 v2, v2
	v_mov_b32_e32 v102, v64
	v_mov_b32_e32 v100, v72
	v_add_f32_e32 v2, 1.0, v2
	v_rcp_f32_e32 v103, v2
	s_nop 0
	v_pk_mul_f32 v[100:101], v[102:103], v[100:101]
	s_nop 0
	v_mul_f32_e32 v2, v100, v101
	v_and_b32_e32 v101, 0xffff0000, v88
	v_mul_f32_e32 v64, 0xbfb8aa3b, v101
	v_exp_f32_e32 v64, v64
	v_mov_b32_e32 v102, v65
	v_mov_b32_e32 v100, v73
	v_mov_b32_e32 v88, v75
	v_add_f32_e32 v64, 1.0, v64
	v_rcp_f32_e32 v103, v64
	s_nop 0
	v_pk_mul_f32 v[64:65], v[102:103], v[100:101]
	s_nop 0
	v_mul_f32_e32 v64, v64, v65
	v_lshlrev_b32_e32 v101, 16, v89
	v_cvt_pk_bf16_f32 v64, v2, v64
	v_mul_f32_e32 v2, 0xbfb8aa3b, v101
	v_exp_f32_e32 v2, v2
	v_and_b32_e32 v89, 0xffff0000, v89
	v_mul_f32_e32 v65, 0xbfb8aa3b, v89
	v_exp_f32_e32 v65, v65
	v_add_f32_e32 v2, 1.0, v2
	v_rcp_f32_e32 v103, v2
	v_mov_b32_e32 v102, v66
	v_mov_b32_e32 v100, v74
	v_add_f32_e32 v65, 1.0, v65
	v_pk_mul_f32 v[100:101], v[102:103], v[100:101]
	s_nop 0
	v_mul_f32_e32 v2, v100, v101
	v_rcp_f32_e32 v101, v65
	v_mov_b32_e32 v100, v67
	v_pk_mul_f32 v[66:67], v[100:101], v[88:89]
	s_nop 0
	v_mul_f32_e32 v65, v66, v67
	v_lshlrev_b32_e32 v67, 16, v90
	v_cvt_pk_bf16_f32 v65, v2, v65
	v_mul_f32_e32 v2, 0xbfb8aa3b, v67
	v_exp_f32_e32 v2, v2
	v_mov_b32_e32 v88, v60
	v_mov_b32_e32 v66, v68
	v_add_f32_e32 v2, 1.0, v2
	v_rcp_f32_e32 v89, v2
	s_nop 0
	v_pk_mul_f32 v[66:67], v[88:89], v[66:67]
	s_nop 0
	v_mul_f32_e32 v2, v66, v67
	v_and_b32_e32 v67, 0xffff0000, v90
	v_mul_f32_e32 v60, 0xbfb8aa3b, v67
	v_exp_f32_e32 v60, v60
	v_mov_b32_e32 v88, v61
	v_mov_b32_e32 v66, v69
	v_add_f32_e32 v60, 1.0, v60
	v_rcp_f32_e32 v89, v60
	s_nop 0
	v_pk_mul_f32 v[60:61], v[88:89], v[66:67]
	s_nop 0
	v_mul_f32_e32 v60, v60, v61
	v_lshlrev_b32_e32 v61, 16, v91
	v_cvt_pk_bf16_f32 v66, v2, v60
	v_mul_f32_e32 v2, 0xbfb8aa3b, v61
	v_exp_f32_e32 v2, v2
	v_mov_b32_e32 v88, v62
	v_mov_b32_e32 v60, v70
	v_mov_b32_e32 v62, v56
	v_add_f32_e32 v2, 1.0, v2
	v_rcp_f32_e32 v89, v2
	s_nop 0
	v_pk_mul_f32 v[60:61], v[88:89], v[60:61]
	s_nop 0
	v_mul_f32_e32 v2, v60, v61
	v_and_b32_e32 v61, 0xffff0000, v91
	v_mul_f32_e32 v60, 0xbfb8aa3b, v61
	v_exp_f32_e32 v60, v60
	v_mov_b32_e32 v88, v63
	v_add_f32_e32 v60, 1.0, v60
	v_rcp_f32_e32 v89, v60
	v_mov_b32_e32 v60, v71
	v_pk_mul_f32 v[60:61], v[88:89], v[60:61]
	s_nop 0
	v_mul_f32_e32 v60, v60, v61
	v_lshlrev_b32_e32 v61, 16, v84
	v_cvt_pk_bf16_f32 v67, v2, v60
	v_mul_f32_e32 v2, 0xbfb8aa3b, v61
	v_exp_f32_e32 v2, v2
	v_mov_b32_e32 v60, v72
	flat_store_dwordx4 v[136:137], v[64:67] offset:256
	v_add_f32_e32 v2, 1.0, v2
	v_rcp_f32_e32 v63, v2
	s_nop 0
	v_pk_mul_f32 v[60:61], v[62:63], v[60:61]
	s_nop 0
	v_mul_f32_e32 v2, v60, v61
	v_and_b32_e32 v61, 0xffff0000, v84
	v_mul_f32_e32 v56, 0xbfb8aa3b, v61
	v_exp_f32_e32 v56, v56
	v_mov_b32_e32 v62, v57
	v_mov_b32_e32 v60, v73
	v_add_f32_e32 v56, 1.0, v56
	v_rcp_f32_e32 v63, v56
	s_nop 0
	v_pk_mul_f32 v[56:57], v[62:63], v[60:61]
	s_nop 0
	v_mul_f32_e32 v56, v56, v57
	v_lshlrev_b32_e32 v61, 16, v85
	v_cvt_pk_bf16_f32 v56, v2, v56
	v_mul_f32_e32 v2, 0xbfb8aa3b, v61
	v_exp_f32_e32 v2, v2
	v_mov_b32_e32 v62, v58
	v_mov_b32_e32 v60, v74
	v_add_f32_e32 v2, 1.0, v2
	v_rcp_f32_e32 v63, v2
	s_nop 0
	v_pk_mul_f32 v[60:61], v[62:63], v[60:61]
	s_nop 0
	v_mul_f32_e32 v2, v60, v61
	v_and_b32_e32 v61, 0xffff0000, v85
	v_mul_f32_e32 v57, 0xbfb8aa3b, v61
	v_exp_f32_e32 v57, v57
	v_mov_b32_e32 v62, v59
	v_mov_b32_e32 v60, v75
	v_add_f32_e32 v57, 1.0, v57
	v_rcp_f32_e32 v63, v57
	s_nop 0
	v_pk_mul_f32 v[58:59], v[62:63], v[60:61]
	s_nop 0
	v_mul_f32_e32 v57, v58, v59
	v_lshlrev_b32_e32 v59, 16, v86
	v_cvt_pk_bf16_f32 v57, v2, v57
	v_mul_f32_e32 v2, 0xbfb8aa3b, v59
	v_exp_f32_e32 v2, v2
	v_mov_b32_e32 v60, v52
	v_mov_b32_e32 v58, v68
	v_add_f32_e32 v2, 1.0, v2
	v_rcp_f32_e32 v61, v2
	s_nop 0
	v_pk_mul_f32 v[58:59], v[60:61], v[58:59]
	s_nop 0
	v_mul_f32_e32 v2, v58, v59
	v_and_b32_e32 v59, 0xffff0000, v86
	v_mul_f32_e32 v52, 0xbfb8aa3b, v59
	v_exp_f32_e32 v52, v52
	v_mov_b32_e32 v60, v53
	v_mov_b32_e32 v58, v69
	v_add_f32_e32 v52, 1.0, v52
	v_rcp_f32_e32 v61, v52
	s_nop 0
	v_pk_mul_f32 v[52:53], v[60:61], v[58:59]
	s_nop 0
	v_mul_f32_e32 v52, v52, v53
	v_lshlrev_b32_e32 v53, 16, v87
	v_cvt_pk_bf16_f32 v58, v2, v52
	v_mul_f32_e32 v2, 0xbfb8aa3b, v53
	v_exp_f32_e32 v2, v2
	v_mov_b32_e32 v60, v54
	v_mov_b32_e32 v52, v70
	v_mov_b32_e32 v54, v48
	v_add_f32_e32 v2, 1.0, v2
	v_rcp_f32_e32 v61, v2
	s_nop 0
	v_pk_mul_f32 v[52:53], v[60:61], v[52:53]
	s_nop 0
	v_mul_f32_e32 v2, v52, v53
	v_and_b32_e32 v53, 0xffff0000, v87
	v_mul_f32_e32 v52, 0xbfb8aa3b, v53
	v_exp_f32_e32 v52, v52
	v_mov_b32_e32 v60, v55
	v_add_f32_e32 v52, 1.0, v52
	v_rcp_f32_e32 v61, v52
	v_mov_b32_e32 v52, v71
	v_pk_mul_f32 v[52:53], v[60:61], v[52:53]
	s_nop 0
	v_mul_f32_e32 v52, v52, v53
	v_lshlrev_b32_e32 v53, 16, v80
	v_cvt_pk_bf16_f32 v59, v2, v52
	v_mul_f32_e32 v2, 0xbfb8aa3b, v53
	v_exp_f32_e32 v2, v2
	v_mov_b32_e32 v52, v72
	flat_store_dwordx4 v[124:125], v[56:59] offset:256
	v_add_f32_e32 v2, 1.0, v2
	v_rcp_f32_e32 v55, v2
	s_nop 0
	v_pk_mul_f32 v[52:53], v[54:55], v[52:53]
	s_nop 0
	v_mul_f32_e32 v2, v52, v53
	v_and_b32_e32 v53, 0xffff0000, v80
	v_mul_f32_e32 v48, 0xbfb8aa3b, v53
	v_exp_f32_e32 v48, v48
	v_mov_b32_e32 v54, v49
	v_mov_b32_e32 v52, v73
	v_add_f32_e32 v48, 1.0, v48
	v_rcp_f32_e32 v55, v48
	s_nop 0
	v_pk_mul_f32 v[48:49], v[54:55], v[52:53]
	s_nop 0
	v_mul_f32_e32 v48, v48, v49
	v_lshlrev_b32_e32 v53, 16, v81
	v_cvt_pk_bf16_f32 v48, v2, v48
	v_mul_f32_e32 v2, 0xbfb8aa3b, v53
	v_exp_f32_e32 v2, v2
	v_mov_b32_e32 v54, v50
	v_mov_b32_e32 v52, v74
	v_add_f32_e32 v2, 1.0, v2
	v_rcp_f32_e32 v55, v2
; __device__ __forceinline__ size_t pidx(size_t row, int col) { return ((size_t)(col >> 8) * MTOK + row) * PLD + (col & 255); }
; __device__ __forceinline__ float bflo(unsigned v) { return __uint_as_float(v << 16); }
; __device__ __forceinline__ float bfhi(unsigned v) { return __uint_as_float(v & 0xffff0000u); }
; __device__ __forceinline__ float siluf_(float x) { return x * __builtin_amdgcn_rcpf(1.0f + __expf(-x)); }
;   __device__ __forceinline__ void operator()(EPI_ARGS) const {
;     ...
;         for (int m = 0; m < 4; ++m) z[m] = *(const u32x4*)(proj + pidx(row0 + ai * HALF + m * 16, PZ + c));
;         __builtin_amdgcn_sched_barrier(0);
; #pragma unroll
;         for (int m = 0; m < 4; ++m) {
;           const size_t row = row0 + ai * HALF + m * 16;
;           const f32x4 v0 = acc[ai][bj][m][0], v1 = acc[ai][bj][m][1];
;           u32x4 o;
;           o.x = pack2(v0[0] * s0[0] * siluf_(bflo(z[m].x)), v0[1] * s0[1] * siluf_(bfhi(z[m].x)));
;           o.y = pack2(v0[2] * s0[2] * siluf_(bflo(z[m].y)), v0[3] * s0[3] * siluf_(bfhi(z[m].y)));
;           o.z = pack2(v1[0] * s1[0] * siluf_(bflo(z[m].z)), v1[1] * s1[1] * siluf_(bfhi(z[m].z)));
;           o.w = pack2(v1[2] * s1[2] * siluf_(bflo(z[m].w)), v1[3] * s1[3] * siluf_(bfhi(z[m].w)));
;           *(u32x4*)(y0 + row * DM + c) = o;
;         }
	s_nop 0
	v_pk_mul_f32 v[52:53], v[54:55], v[52:53]
	s_nop 0
	v_mul_f32_e32 v2, v52, v53
	v_and_b32_e32 v53, 0xffff0000, v81
	v_mul_f32_e32 v49, 0xbfb8aa3b, v53
	v_exp_f32_e32 v49, v49
	v_mov_b32_e32 v54, v51
	v_mov_b32_e32 v52, v75
	v_add_f32_e32 v49, 1.0, v49
	v_rcp_f32_e32 v55, v49
	s_nop 0
	v_pk_mul_f32 v[50:51], v[54:55], v[52:53]
	s_nop 0
	v_mul_f32_e32 v49, v50, v51
	v_lshlrev_b32_e32 v51, 16, v82
	v_cvt_pk_bf16_f32 v49, v2, v49
	v_mul_f32_e32 v2, 0xbfb8aa3b, v51
	v_exp_f32_e32 v2, v2
	v_mov_b32_e32 v52, v44
	v_mov_b32_e32 v50, v68
	v_add_f32_e32 v2, 1.0, v2
	v_rcp_f32_e32 v53, v2
	s_nop 0
	v_pk_mul_f32 v[50:51], v[52:53], v[50:51]
	s_nop 0
	v_mul_f32_e32 v2, v50, v51
	v_and_b32_e32 v51, 0xffff0000, v82
	v_mul_f32_e32 v44, 0xbfb8aa3b, v51
	v_exp_f32_e32 v44, v44
	v_mov_b32_e32 v52, v45
	v_mov_b32_e32 v50, v69
	v_add_f32_e32 v44, 1.0, v44
	v_rcp_f32_e32 v53, v44
	s_nop 0
	v_pk_mul_f32 v[44:45], v[52:53], v[50:51]
	s_nop 0
	v_mul_f32_e32 v44, v44, v45
	v_lshlrev_b32_e32 v45, 16, v83
	v_cvt_pk_bf16_f32 v50, v2, v44
	v_mul_f32_e32 v2, 0xbfb8aa3b, v45
	v_exp_f32_e32 v2, v2
	v_mov_b32_e32 v52, v46
	v_mov_b32_e32 v44, v70
	v_mov_b32_e32 v46, v40
	v_add_f32_e32 v2, 1.0, v2
	v_rcp_f32_e32 v53, v2
	s_nop 0
	v_pk_mul_f32 v[44:45], v[52:53], v[44:45]
	s_nop 0
	v_mul_f32_e32 v2, v44, v45
	v_and_b32_e32 v45, 0xffff0000, v83
	v_mul_f32_e32 v44, 0xbfb8aa3b, v45
	v_exp_f32_e32 v44, v44
	v_mov_b32_e32 v52, v47
	v_add_f32_e32 v44, 1.0, v44
	v_rcp_f32_e32 v53, v44
	v_mov_b32_e32 v44, v71
	v_pk_mul_f32 v[44:45], v[52:53], v[44:45]
	s_nop 0
	v_mul_f32_e32 v44, v44, v45
	v_lshlrev_b32_e32 v45, 16, v76
	v_cvt_pk_bf16_f32 v51, v2, v44
	v_mul_f32_e32 v2, 0xbfb8aa3b, v45
	v_exp_f32_e32 v2, v2
	v_mov_b32_e32 v44, v72
	flat_store_dwordx4 v[128:129], v[48:51] offset:256
	v_add_f32_e32 v2, 1.0, v2
	v_rcp_f32_e32 v47, v2
	s_nop 0
	v_pk_mul_f32 v[44:45], v[46:47], v[44:45]
	s_nop 0
	v_mul_f32_e32 v2, v44, v45
	v_and_b32_e32 v45, 0xffff0000, v76
	v_mul_f32_e32 v40, 0xbfb8aa3b, v45
	v_exp_f32_e32 v40, v40
	v_mov_b32_e32 v46, v41
	v_mov_b32_e32 v44, v73
	v_add_f32_e32 v40, 1.0, v40
	v_rcp_f32_e32 v47, v40
	s_nop 0
	v_pk_mul_f32 v[40:41], v[46:47], v[44:45]
	s_nop 0
	v_mul_f32_e32 v40, v40, v41
	v_lshlrev_b32_e32 v45, 16, v77
	v_cvt_pk_bf16_f32 v40, v2, v40
	v_mul_f32_e32 v2, 0xbfb8aa3b, v45
	v_exp_f32_e32 v2, v2
	v_mov_b32_e32 v46, v42
	v_mov_b32_e32 v44, v74
	v_add_f32_e32 v2, 1.0, v2
	v_rcp_f32_e32 v47, v2
	s_nop 0
	v_pk_mul_f32 v[44:45], v[46:47], v[44:45]
	s_nop 0
	v_mul_f32_e32 v2, v44, v45
	v_and_b32_e32 v45, 0xffff0000, v77
	v_mul_f32_e32 v41, 0xbfb8aa3b, v45
	v_exp_f32_e32 v41, v41
	v_mov_b32_e32 v46, v43
	v_mov_b32_e32 v44, v75
	v_add_f32_e32 v41, 1.0, v41
	v_rcp_f32_e32 v47, v41
	s_nop 0
	v_pk_mul_f32 v[42:43], v[46:47], v[44:45]
	s_nop 0
	v_mul_f32_e32 v41, v42, v43
	v_lshlrev_b32_e32 v43, 16, v78
	v_cvt_pk_bf16_f32 v41, v2, v41
	v_mul_f32_e32 v2, 0xbfb8aa3b, v43
	v_exp_f32_e32 v2, v2
	v_mov_b32_e32 v44, v36
	v_mov_b32_e32 v42, v68
	v_add_f32_e32 v2, 1.0, v2
	v_rcp_f32_e32 v45, v2
	s_nop 0
	v_pk_mul_f32 v[42:43], v[44:45], v[42:43]
	s_nop 0
	v_mul_f32_e32 v2, v42, v43
	v_and_b32_e32 v43, 0xffff0000, v78
	v_mul_f32_e32 v36, 0xbfb8aa3b, v43
	v_exp_f32_e32 v36, v36
	v_mov_b32_e32 v44, v37
	v_mov_b32_e32 v42, v69
	v_add_f32_e32 v36, 1.0, v36
	v_rcp_f32_e32 v45, v36
	s_nop 0
	v_pk_mul_f32 v[36:37], v[44:45], v[42:43]
	s_nop 0
	v_mul_f32_e32 v36, v36, v37
	v_lshlrev_b32_e32 v37, 16, v79
	v_cvt_pk_bf16_f32 v42, v2, v36
	v_mul_f32_e32 v2, 0xbfb8aa3b, v37
	v_exp_f32_e32 v2, v2
	v_mov_b32_e32 v44, v38
	v_mov_b32_e32 v36, v70
	v_add_f32_e32 v2, 1.0, v2
	v_rcp_f32_e32 v45, v2
	s_nop 0
	v_pk_mul_f32 v[36:37], v[44:45], v[36:37]
	s_nop 0
	v_mul_f32_e32 v2, v36, v37
	v_and_b32_e32 v37, 0xffff0000, v79
	v_mul_f32_e32 v36, 0xbfb8aa3b, v37
	v_exp_f32_e32 v36, v36
	v_mov_b32_e32 v44, v39
	v_add_f32_e32 v36, 1.0, v36
	v_rcp_f32_e32 v45, v36
	v_mov_b32_e32 v36, v71
	v_pk_mul_f32 v[36:37], v[44:45], v[36:37]
	s_nop 0
	v_mul_f32_e32 v36, v36, v37
	v_cvt_pk_bf16_f32 v43, v2, v36
	flat_store_dwordx4 v[126:127], v[40:43] offset:256
	v_lshl_add_u64 v[36:37], v[94:95], 0, v[130:131]
	flat_load_dwordx4 v[48:51], v[36:37]
	v_lshl_add_u64 v[36:37], v[94:95], 0, v[132:133]
	flat_load_dwordx4 v[44:47], v[36:37]
	v_lshl_add_u64 v[36:37], v[94:95], 0, v[134:135]
	flat_load_dwordx4 v[40:43], v[36:37]
	v_lshl_add_u64 v[36:37], v[94:95], 0, v[138:139]
	flat_load_dwordx4 v[36:39], v[36:37]
	s_waitcnt vmcnt(0) lgkmcnt(0)
; __device__ __forceinline__ float bflo(unsigned v) { return __uint_as_float(v << 16); }
; __device__ __forceinline__ float bfhi(unsigned v) { return __uint_as_float(v & 0xffff0000u); }
; __device__ __forceinline__ float siluf_(float x) { return x * __builtin_amdgcn_rcpf(1.0f + __expf(-x)); }
;   __device__ __forceinline__ void operator()(EPI_ARGS) const {
;     ...
;         for (int m = 0; m < 4; ++m) {
;           const size_t row = row0 + ai * HALF + m * 16;
;           const f32x4 v0 = acc[ai][bj][m][0], v1 = acc[ai][bj][m][1];
;           u32x4 o;
;           o.x = pack2(v0[0] * s0[0] * siluf_(bflo(z[m].x)), v0[1] * s0[1] * siluf_(bfhi(z[m].x)));
;           o.y = pack2(v0[2] * s0[2] * siluf_(bflo(z[m].y)), v0[3] * s0[3] * siluf_(bfhi(z[m].y)));
;           o.z = pack2(v1[0] * s1[0] * siluf_(bflo(z[m].z)), v1[1] * s1[1] * siluf_(bfhi(z[m].z)));
;           o.w = pack2(v1[2] * s1[2] * siluf_(bflo(z[m].w)), v1[3] * s1[3] * siluf_(bfhi(z[m].w)));
;           *(u32x4*)(y0 + row * DM + c) = o;
;         }
	v_lshlrev_b32_e32 v53, 16, v48
	v_mul_f32_e32 v2, 0xbfb8aa3b, v53
	v_exp_f32_e32 v2, v2
	v_mov_b32_e32 v54, v32
	v_mov_b32_e32 v52, v72
	s_and_b64 vcc, exec, s[18:19]
	v_add_f32_e32 v2, 1.0, v2
	v_rcp_f32_e32 v55, v2
	s_mov_b32 s33, s16
	s_mov_b32 s2, s14
	s_mov_b64 s[4:5], s[22:23]
	v_pk_mul_f32 v[52:53], v[54:55], v[52:53]
	v_mov_b32_e32 v54, v33
	v_mul_f32_e32 v2, v52, v53
	v_and_b32_e32 v53, 0xffff0000, v48
	v_mul_f32_e32 v32, 0xbfb8aa3b, v53
	v_exp_f32_e32 v32, v32
	v_mov_b32_e32 v52, v73
	v_mov_b32_e32 v48, v75
	s_mov_b64 s[6:7], s[20:21]
	v_add_f32_e32 v32, 1.0, v32
	v_rcp_f32_e32 v55, v32
	s_nop 0
	v_pk_mul_f32 v[32:33], v[54:55], v[52:53]
	s_nop 0
	v_mul_f32_e32 v32, v32, v33
	v_lshlrev_b32_e32 v53, 16, v49
	v_cvt_pk_bf16_f32 v32, v2, v32
	v_mul_f32_e32 v2, 0xbfb8aa3b, v53
	v_exp_f32_e32 v2, v2
	v_and_b32_e32 v49, 0xffff0000, v49
	v_mul_f32_e32 v33, 0xbfb8aa3b, v49
	v_exp_f32_e32 v33, v33
	v_add_f32_e32 v2, 1.0, v2
	v_rcp_f32_e32 v55, v2
	v_mov_b32_e32 v54, v34
	v_mov_b32_e32 v52, v74
	v_add_f32_e32 v33, 1.0, v33
	v_pk_mul_f32 v[52:53], v[54:55], v[52:53]
	s_nop 0
	v_mul_f32_e32 v2, v52, v53
	v_rcp_f32_e32 v53, v33
	v_mov_b32_e32 v52, v35
	v_pk_mul_f32 v[34:35], v[52:53], v[48:49]
	s_nop 0
	v_mul_f32_e32 v33, v34, v35
	v_lshlrev_b32_e32 v35, 16, v50
	v_cvt_pk_bf16_f32 v33, v2, v33
	v_mul_f32_e32 v2, 0xbfb8aa3b, v35
	v_exp_f32_e32 v2, v2
	v_mov_b32_e32 v48, v28
	v_mov_b32_e32 v34, v68
	v_add_f32_e32 v2, 1.0, v2
	v_rcp_f32_e32 v49, v2
	s_nop 0
	v_pk_mul_f32 v[34:35], v[48:49], v[34:35]
	s_nop 0
	v_mul_f32_e32 v2, v34, v35
	v_and_b32_e32 v35, 0xffff0000, v50
	v_mul_f32_e32 v28, 0xbfb8aa3b, v35
	v_exp_f32_e32 v28, v28
	v_mov_b32_e32 v48, v29
	v_mov_b32_e32 v34, v69
	v_add_f32_e32 v28, 1.0, v28
	v_rcp_f32_e32 v49, v28
	s_nop 0
	v_pk_mul_f32 v[28:29], v[48:49], v[34:35]
	s_nop 0
	v_mul_f32_e32 v28, v28, v29
	v_lshlrev_b32_e32 v29, 16, v51
	v_cvt_pk_bf16_f32 v34, v2, v28
	v_mul_f32_e32 v2, 0xbfb8aa3b, v29
	v_exp_f32_e32 v2, v2
	v_mov_b32_e32 v48, v30
	v_mov_b32_e32 v28, v70
	v_mov_b32_e32 v30, v24
	v_add_f32_e32 v2, 1.0, v2
	v_rcp_f32_e32 v49, v2
	s_nop 0
	v_pk_mul_f32 v[28:29], v[48:49], v[28:29]
	s_nop 0
	v_mul_f32_e32 v2, v28, v29
	v_and_b32_e32 v29, 0xffff0000, v51
	v_mul_f32_e32 v28, 0xbfb8aa3b, v29
	v_exp_f32_e32 v28, v28
	v_mov_b32_e32 v48, v31
	v_add_f32_e32 v28, 1.0, v28
	v_rcp_f32_e32 v49, v28
	v_mov_b32_e32 v28, v71
	v_pk_mul_f32 v[28:29], v[48:49], v[28:29]
	s_nop 0
	v_mul_f32_e32 v28, v28, v29
	v_lshlrev_b32_e32 v29, 16, v44
	v_cvt_pk_bf16_f32 v35, v2, v28
	v_mul_f32_e32 v2, 0xbfb8aa3b, v29
	v_exp_f32_e32 v2, v2
	v_mov_b32_e32 v28, v72
	flat_store_dwordx4 v[96:97], v[32:35] offset:256
	v_add_f32_e32 v2, 1.0, v2
	v_rcp_f32_e32 v31, v2
	s_nop 0
	v_pk_mul_f32 v[28:29], v[30:31], v[28:29]
	s_nop 0
	v_mul_f32_e32 v2, v28, v29
	v_and_b32_e32 v29, 0xffff0000, v44
	v_mul_f32_e32 v24, 0xbfb8aa3b, v29
	v_exp_f32_e32 v24, v24
	v_mov_b32_e32 v30, v25
	v_mov_b32_e32 v28, v73
	v_add_f32_e32 v24, 1.0, v24
	v_rcp_f32_e32 v31, v24
	s_nop 0
	v_pk_mul_f32 v[24:25], v[30:31], v[28:29]
	s_nop 0
	v_mul_f32_e32 v24, v24, v25
	v_lshlrev_b32_e32 v29, 16, v45
	v_cvt_pk_bf16_f32 v24, v2, v24
	v_mul_f32_e32 v2, 0xbfb8aa3b, v29
	v_exp_f32_e32 v2, v2
	v_mov_b32_e32 v30, v26
	v_mov_b32_e32 v28, v74
	v_add_f32_e32 v2, 1.0, v2
	v_rcp_f32_e32 v31, v2
	s_nop 0
	v_pk_mul_f32 v[28:29], v[30:31], v[28:29]
	s_nop 0
	v_mul_f32_e32 v2, v28, v29
	v_and_b32_e32 v29, 0xffff0000, v45
	v_mul_f32_e32 v25, 0xbfb8aa3b, v29
	v_exp_f32_e32 v25, v25
	v_mov_b32_e32 v30, v27
	v_mov_b32_e32 v28, v75
	v_add_f32_e32 v25, 1.0, v25
	v_rcp_f32_e32 v31, v25
	s_nop 0
	v_pk_mul_f32 v[26:27], v[30:31], v[28:29]
	s_nop 0
	v_mul_f32_e32 v25, v26, v27
	v_lshlrev_b32_e32 v27, 16, v46
	v_cvt_pk_bf16_f32 v25, v2, v25
	v_mul_f32_e32 v2, 0xbfb8aa3b, v27
	v_exp_f32_e32 v2, v2
	v_mov_b32_e32 v28, v20
	v_mov_b32_e32 v26, v68
	v_add_f32_e32 v2, 1.0, v2
	v_rcp_f32_e32 v29, v2
	s_nop 0
	v_pk_mul_f32 v[26:27], v[28:29], v[26:27]
	s_nop 0
	v_mul_f32_e32 v2, v26, v27
	v_and_b32_e32 v27, 0xffff0000, v46
	v_mul_f32_e32 v20, 0xbfb8aa3b, v27
	v_exp_f32_e32 v20, v20
	v_mov_b32_e32 v28, v21
	v_mov_b32_e32 v26, v69
	v_add_f32_e32 v20, 1.0, v20
	v_rcp_f32_e32 v29, v20
	s_nop 0
	v_pk_mul_f32 v[20:21], v[28:29], v[26:27]
	s_nop 0
	v_mul_f32_e32 v20, v20, v21
	v_lshlrev_b32_e32 v21, 16, v47
	v_cvt_pk_bf16_f32 v26, v2, v20
	v_mul_f32_e32 v2, 0xbfb8aa3b, v21
	v_exp_f32_e32 v2, v2
	v_mov_b32_e32 v28, v22
	v_mov_b32_e32 v20, v70
	v_mov_b32_e32 v22, v16
	v_add_f32_e32 v2, 1.0, v2
	v_rcp_f32_e32 v29, v2
	s_nop 0
	v_pk_mul_f32 v[20:21], v[28:29], v[20:21]
	s_nop 0
	v_mul_f32_e32 v2, v20, v21
	v_and_b32_e32 v21, 0xffff0000, v47
	v_mul_f32_e32 v20, 0xbfb8aa3b, v21
	v_exp_f32_e32 v20, v20
	v_mov_b32_e32 v28, v23
	v_add_f32_e32 v20, 1.0, v20
	v_rcp_f32_e32 v29, v20
	v_mov_b32_e32 v20, v71
	v_pk_mul_f32 v[20:21], v[28:29], v[20:21]
	s_nop 0
	v_mul_f32_e32 v20, v20, v21
	v_lshlrev_b32_e32 v21, 16, v40
	v_cvt_pk_bf16_f32 v27, v2, v20
	v_mul_f32_e32 v2, 0xbfb8aa3b, v21
	v_exp_f32_e32 v2, v2
	v_mov_b32_e32 v20, v72
	flat_store_dwordx4 v[98:99], v[24:27] offset:256
; __device__ __forceinline__ float bflo(unsigned v) { return __uint_as_float(v << 16); }
; __device__ __forceinline__ float bfhi(unsigned v) { return __uint_as_float(v & 0xffff0000u); }
; __device__ __forceinline__ float siluf_(float x) { return x * __builtin_amdgcn_rcpf(1.0f + __expf(-x)); }
; #define PG8_WAIT_V(n) asm volatile("s_waitcnt vmcnt(" #n ")" ::: "memory")
; #define PG8_BAR __builtin_amdgcn_s_barrier()
; template <class Epi, class AddrA, class AddrB>
; __device__ __forceinline__ void gemm_phase(const Sched S, const int lda, const int ldb, const int K, const AddrA addrA,
;                                            const AddrB addrB, const Epi E) {
;     ...
;     E(acc, cur, wr, wc, fr, fq);
;     if (!has_next) break;
;     if (!(Epi::KEEP && cur.br + 1 < S.nbr)) {
; #pragma unroll
;       for (int a = 0; a < 2; ++a)
; #pragma unroll
;         for (int b = 0; b < 2; ++b)
; #pragma unroll
;           for (int m = 0; m < 4; ++m)
; #pragma unroll
;             for (int n = 0; n < 2; ++n) acc[a][b][m][n] = (f32x4){0.f, 0.f, 0.f, 0.f};
;     }
;     cur = nxt; cA = nA; cB = nB; ++ui;
;   }
;   PG8_WAIT_V(0);
;   if (wr == 0) PG8_BAR;
;   PG8_BAR;
;   __device__ __forceinline__ void operator()(EPI_ARGS) const {
;     ...
;         for (int m = 0; m < 4; ++m) {
;           const size_t row = row0 + ai * HALF + m * 16;
;           const f32x4 v0 = acc[ai][bj][m][0], v1 = acc[ai][bj][m][1];
;           u32x4 o;
;           o.x = pack2(v0[0] * s0[0] * siluf_(bflo(z[m].x)), v0[1] * s0[1] * siluf_(bfhi(z[m].x)));
;           o.y = pack2(v0[2] * s0[2] * siluf_(bflo(z[m].y)), v0[3] * s0[3] * siluf_(bfhi(z[m].y)));
;           o.z = pack2(v1[0] * s1[0] * siluf_(bflo(z[m].z)), v1[1] * s1[1] * siluf_(bfhi(z[m].z)));
;           o.w = pack2(v1[2] * s1[2] * siluf_(bflo(z[m].w)), v1[3] * s1[3] * siluf_(bfhi(z[m].w)));
;           *(u32x4*)(y0 + row * DM + c) = o;
;         }
	v_add_f32_e32 v2, 1.0, v2
	v_rcp_f32_e32 v23, v2
	s_nop 0
	v_pk_mul_f32 v[20:21], v[22:23], v[20:21]
	s_nop 0
	v_mul_f32_e32 v2, v20, v21
	v_and_b32_e32 v21, 0xffff0000, v40
	v_mul_f32_e32 v16, 0xbfb8aa3b, v21
	v_exp_f32_e32 v16, v16
	v_mov_b32_e32 v22, v17
	v_mov_b32_e32 v20, v73
	v_add_f32_e32 v16, 1.0, v16
	v_rcp_f32_e32 v23, v16
	s_nop 0
	v_pk_mul_f32 v[16:17], v[22:23], v[20:21]
	s_nop 0
	v_mul_f32_e32 v16, v16, v17
	v_lshlrev_b32_e32 v21, 16, v41
	v_cvt_pk_bf16_f32 v16, v2, v16
	v_mul_f32_e32 v2, 0xbfb8aa3b, v21
	v_exp_f32_e32 v2, v2
	v_mov_b32_e32 v22, v18
	v_mov_b32_e32 v20, v74
	v_add_f32_e32 v2, 1.0, v2
	v_rcp_f32_e32 v23, v2
	s_nop 0
	v_pk_mul_f32 v[20:21], v[22:23], v[20:21]
	s_nop 0
	v_mul_f32_e32 v2, v20, v21
	v_and_b32_e32 v21, 0xffff0000, v41
	v_mul_f32_e32 v17, 0xbfb8aa3b, v21
	v_exp_f32_e32 v17, v17
	v_mov_b32_e32 v22, v19
	v_mov_b32_e32 v20, v75
	v_add_f32_e32 v17, 1.0, v17
	v_rcp_f32_e32 v23, v17
	s_nop 0
	v_pk_mul_f32 v[18:19], v[22:23], v[20:21]
	s_nop 0
	v_mul_f32_e32 v17, v18, v19
	v_lshlrev_b32_e32 v19, 16, v42
	v_cvt_pk_bf16_f32 v17, v2, v17
	v_mul_f32_e32 v2, 0xbfb8aa3b, v19
	v_exp_f32_e32 v2, v2
	v_mov_b32_e32 v20, v12
	v_mov_b32_e32 v18, v68
	v_add_f32_e32 v2, 1.0, v2
	v_rcp_f32_e32 v21, v2
	s_nop 0
	v_pk_mul_f32 v[18:19], v[20:21], v[18:19]
	s_nop 0
	v_mul_f32_e32 v2, v18, v19
	v_and_b32_e32 v19, 0xffff0000, v42
	v_mul_f32_e32 v12, 0xbfb8aa3b, v19
	v_exp_f32_e32 v12, v12
	v_mov_b32_e32 v20, v13
	v_mov_b32_e32 v18, v69
	v_add_f32_e32 v12, 1.0, v12
	v_rcp_f32_e32 v21, v12
	s_nop 0
	v_pk_mul_f32 v[12:13], v[20:21], v[18:19]
	s_nop 0
	v_mul_f32_e32 v12, v12, v13
	v_lshlrev_b32_e32 v13, 16, v43
	v_cvt_pk_bf16_f32 v18, v2, v12
	v_mul_f32_e32 v2, 0xbfb8aa3b, v13
	v_exp_f32_e32 v2, v2
	v_mov_b32_e32 v20, v14
	v_mov_b32_e32 v12, v70
	v_mov_b32_e32 v14, v8
	v_add_f32_e32 v2, 1.0, v2
	v_rcp_f32_e32 v21, v2
	s_nop 0
	v_pk_mul_f32 v[12:13], v[20:21], v[12:13]
	s_nop 0
	v_mul_f32_e32 v2, v12, v13
	v_and_b32_e32 v13, 0xffff0000, v43
	v_mul_f32_e32 v12, 0xbfb8aa3b, v13
	v_exp_f32_e32 v12, v12
	v_mov_b32_e32 v20, v15
	v_add_f32_e32 v12, 1.0, v12
	v_rcp_f32_e32 v21, v12
	v_mov_b32_e32 v12, v71
	v_pk_mul_f32 v[12:13], v[20:21], v[12:13]
	s_nop 0
	v_mul_f32_e32 v12, v12, v13
	v_lshlrev_b32_e32 v13, 16, v36
	v_cvt_pk_bf16_f32 v19, v2, v12
	v_mul_f32_e32 v2, 0xbfb8aa3b, v13
	v_exp_f32_e32 v2, v2
	v_mov_b32_e32 v12, v72
	flat_store_dwordx4 v[104:105], v[16:19] offset:256
	v_add_f32_e32 v2, 1.0, v2
	v_rcp_f32_e32 v15, v2
	s_nop 0
	v_pk_mul_f32 v[12:13], v[14:15], v[12:13]
	s_nop 0
	v_mul_f32_e32 v2, v12, v13
	v_and_b32_e32 v13, 0xffff0000, v36
	v_mul_f32_e32 v8, 0xbfb8aa3b, v13
	v_exp_f32_e32 v8, v8
	v_mov_b32_e32 v14, v9
	v_mov_b32_e32 v12, v73
	v_add_f32_e32 v8, 1.0, v8
	v_rcp_f32_e32 v15, v8
	s_nop 0
	v_pk_mul_f32 v[8:9], v[14:15], v[12:13]
	s_nop 0
	v_mul_f32_e32 v8, v8, v9
	v_lshlrev_b32_e32 v13, 16, v37
	v_cvt_pk_bf16_f32 v8, v2, v8
	v_mul_f32_e32 v2, 0xbfb8aa3b, v13
	v_exp_f32_e32 v2, v2
	v_mov_b32_e32 v14, v10
	v_mov_b32_e32 v12, v74
	v_add_f32_e32 v2, 1.0, v2
	v_rcp_f32_e32 v15, v2
	s_nop 0
	v_pk_mul_f32 v[12:13], v[14:15], v[12:13]
	s_nop 0
	v_mul_f32_e32 v2, v12, v13
	v_and_b32_e32 v13, 0xffff0000, v37
	v_mul_f32_e32 v9, 0xbfb8aa3b, v13
	v_exp_f32_e32 v9, v9
	v_mov_b32_e32 v14, v11
	v_mov_b32_e32 v12, v75
	v_add_f32_e32 v9, 1.0, v9
	v_rcp_f32_e32 v15, v9
	s_nop 0
	v_pk_mul_f32 v[10:11], v[14:15], v[12:13]
	s_nop 0
	v_mul_f32_e32 v9, v10, v11
	v_lshlrev_b32_e32 v11, 16, v38
	v_cvt_pk_bf16_f32 v9, v2, v9
	v_mul_f32_e32 v2, 0xbfb8aa3b, v11
	v_exp_f32_e32 v2, v2
	v_mov_b32_e32 v12, v4
	v_mov_b32_e32 v10, v68
	v_add_f32_e32 v2, 1.0, v2
	v_rcp_f32_e32 v13, v2
	s_nop 0
	v_pk_mul_f32 v[10:11], v[12:13], v[10:11]
	s_nop 0
	v_mul_f32_e32 v2, v10, v11
	v_and_b32_e32 v11, 0xffff0000, v38
	v_mul_f32_e32 v4, 0xbfb8aa3b, v11
	v_exp_f32_e32 v4, v4
	v_mov_b32_e32 v12, v5
	v_mov_b32_e32 v10, v69
	v_add_f32_e32 v4, 1.0, v4
	v_rcp_f32_e32 v13, v4
	s_nop 0
	v_pk_mul_f32 v[4:5], v[12:13], v[10:11]
	s_nop 0
	v_mul_f32_e32 v4, v4, v5
	v_lshlrev_b32_e32 v5, 16, v39
	v_cvt_pk_bf16_f32 v10, v2, v4
	v_mul_f32_e32 v2, 0xbfb8aa3b, v5
	v_exp_f32_e32 v2, v2
	v_mov_b32_e32 v12, v6
	v_mov_b32_e32 v4, v70
	v_add_f32_e32 v2, 1.0, v2
	v_rcp_f32_e32 v13, v2
	s_nop 0
	v_pk_mul_f32 v[4:5], v[12:13], v[4:5]
	s_nop 0
	v_mul_f32_e32 v2, v4, v5
	v_and_b32_e32 v5, 0xffff0000, v39
	v_mul_f32_e32 v4, 0xbfb8aa3b, v5
	v_exp_f32_e32 v4, v4
	v_mov_b32_e32 v12, v7
	v_add_f32_e32 v4, 1.0, v4
	v_rcp_f32_e32 v13, v4
	v_mov_b32_e32 v4, v71
	v_pk_mul_f32 v[4:5], v[12:13], v[4:5]
	s_nop 0
	v_mul_f32_e32 v4, v4, v5
	v_cvt_pk_bf16_f32 v11, v2, v4
	flat_store_dwordx4 v[92:93], v[8:11] offset:256
	s_cbranch_vccz .LBB0_482
	s_waitcnt vmcnt(0)
	v_readlane_b32 s44, v244, 59
	v_readlane_b32 s40, v243, 18
	s_cmpk_gt_u32 s24, 0xff
	s_mov_b32 s43, 0x800000
	v_readlane_b32 s45, v244, 60
	v_readlane_b32 s46, v244, 61
	v_readlane_b32 s47, v244, 62
	v_readlane_b32 s48, v244, 63
	v_readlane_b32 s49, v243, 0
	v_readlane_b32 s50, v243, 1
	v_readlane_b32 s51, v243, 2
	v_readlane_b32 s41, v243, 19
	s_cbranch_scc1 .LBB0_489
	s_barrier

; #define PG8_WAIT_V(n) asm volatile("s_waitcnt vmcnt(" #n ")" ::: "memory")
; #define PG8_WAIT_L(n) asm volatile("s_waitcnt lgkmcnt(" #n ")" ::: "memory")
; #define PG8_BAR __builtin_amdgcn_s_barrier()
; #define PG8_SCHED __builtin_amdgcn_sched_barrier(0)
; template <class Epi, class AddrA, class AddrB>
; __device__ __forceinline__ void gemm_phase(const Sched S, const int lda, const int ldb, const int K, const AddrA addrA,
;                                            const AddrB addrB, const Epi E) {
;     ...
;       const char* a1 = cA + (size_t)(t + 1) * kstep;
;       const char* a2 = last ? nA : cA + (size_t)(t + 2) * kstep;
;       const char* b2 = last ? nB : cB + (size_t)(t + 2) * kstep;
;       const char* a3 = a2 + kstep;
;       const char* b3 = b2 + kstep;
;       PG8_LDB(B0, 0, 0); PG8_SCHED; PG8_LDA(At, 0, 0); PG8_STAGE(PG8_SA(1, 1), a1 + hstepA, voffA);
;       PG8_WAIT_L(8); PG8_BAR; PG8_WAIT_L(0); PG8_MMA(0, 0, At, B0); PG8_BAR; PG8_SCHED;
;       PG8_LDB(B1, 0, 1); PG8_STAGE(PG8_SB(0, 0), b2, voffB);
;       PG8_BAR; PG8_WAIT_L(0); PG8_MMA(0, 1, At, B1); PG8_BAR;
;       PG8_LDA(At, 0, 1); PG8_STAGE(PG8_SA(0, 0), a2, voffA);
;       PG8_BAR; PG8_WAIT_L(0); PG8_MMA(1, 0, At, B0); PG8_BAR; PG8_SCHED;
;       PG8_STAGE(PG8_SB(0, 1), b2 + hstepB, voffB);
;       PG8_WAIT_V(6); PG8_BAR; PG8_MMA(1, 1, At, B1); PG8_BAR;
.LBB0_543:
	s_add_u32 s4, s2, 0xfff80080
	s_addc_u32 s5, s3, -1
	s_add_i32 s43, 0, 0x10000
	v_add_u32_e32 v0, s43, v167
	ds_read_b128 v[132:135], v0
	ds_read_b128 v[136:139], v0 offset:1024
	ds_read_b128 v[140:143], v0 offset:2048
	ds_read_b128 v[144:147], v0 offset:3072
	s_cmp_eq_u32 s42, 28
	s_cselect_b32 s7, s1, s5
	s_cselect_b32 s6, s9, s4
	s_cselect_b32 s5, s13, s41
	s_cselect_b32 s4, s15, s33
	v_lshl_add_u64 v[0:1], s[2:3], 0, v[180:181]
	s_add_i32 m0, s28, 0xc000
	ds_read_b128 v[148:151], v188
	ds_read_b128 v[152:155], v188 offset:1024
	ds_read_b128 v[156:159], v188 offset:2048
	ds_read_b128 v[160:163], v188 offset:3072
	ds_read_b128 v[182:185], v188 offset:4096
	ds_read_b128 v[190:193], v188 offset:5120
	ds_read_b128 v[194:197], v188 offset:6144
	ds_read_b128 v[212:215], v188 offset:7168
	global_load_lds_dwordx4 v[0:1], off
	v_lshl_add_u64 v[0:1], s[2:3], 0, v[178:179]
	s_add_i32 m0, s28, 0xe000
	s_nop 0
	global_load_lds_dwordx4 v[0:1], off
	s_waitcnt lgkmcnt(8)
	s_barrier
	s_waitcnt lgkmcnt(0)
	s_setprio 1
	s_waitcnt lgkmcnt(0)
	v_mfma_f32_16x16x32_bf16 v[128:131], v[132:135], v[148:151], v[128:131]
	v_mfma_f32_16x16x32_bf16 v[128:131], v[136:139], v[152:155], v[128:131]
	v_mfma_f32_16x16x32_bf16 v[124:127], v[140:143], v[148:151], v[124:127]
	v_mfma_f32_16x16x32_bf16 v[124:127], v[144:147], v[152:155], v[124:127]
	v_mfma_f32_16x16x32_bf16 v[120:123], v[132:135], v[156:159], v[120:123]
	v_mfma_f32_16x16x32_bf16 v[120:123], v[136:139], v[160:163], v[120:123]
	v_mfma_f32_16x16x32_bf16 v[116:119], v[140:143], v[156:159], v[116:119]
	v_mfma_f32_16x16x32_bf16 v[116:119], v[144:147], v[160:163], v[116:119]
	v_mfma_f32_16x16x32_bf16 v[112:115], v[132:135], v[182:185], v[112:115]
	v_mfma_f32_16x16x32_bf16 v[112:115], v[136:139], v[190:193], v[112:115]
	v_mfma_f32_16x16x32_bf16 v[108:111], v[140:143], v[182:185], v[108:111]
	v_mfma_f32_16x16x32_bf16 v[108:111], v[144:147], v[190:193], v[108:111]
	v_mfma_f32_16x16x32_bf16 v[104:107], v[132:135], v[194:197], v[104:107]
	v_mfma_f32_16x16x32_bf16 v[104:107], v[136:139], v[212:215], v[104:107]
	v_mfma_f32_16x16x32_bf16 v[100:103], v[140:143], v[194:197], v[100:103]
	v_mfma_f32_16x16x32_bf16 v[100:103], v[144:147], v[212:215], v[100:103]
	s_setprio 0
	s_barrier
	s_add_i32 s46, 0, 0x14000
	v_add_u32_e32 v0, s46, v167
	s_add_i32 s43, s43, s27
	ds_read_b128 v[216:219], v0
	ds_read_b128 v[220:223], v0 offset:1024
	ds_read_b128 v[224:227], v0 offset:2048
	ds_read_b128 v[228:231], v0 offset:3072
	v_lshl_add_u64 v[0:1], s[4:5], 0, v[172:173]
	s_mov_b32 m0, s43
	v_lshl_add_u64 v[232:233], s[4:5], 0, v[168:169]
	global_load_lds_dwordx4 v[0:1], off
	s_add_i32 m0, s43, 0x2000
	s_nop 0
	global_load_lds_dwordx4 v[232:233], off
	s_barrier
	s_waitcnt lgkmcnt(0)
	s_setprio 1
	s_waitcnt lgkmcnt(0)
	v_mfma_f32_16x16x32_bf16 v[96:99], v[216:219], v[148:151], v[96:99]
	v_mfma_f32_16x16x32_bf16 v[96:99], v[220:223], v[152:155], v[96:99]
	v_mfma_f32_16x16x32_bf16 v[92:95], v[224:227], v[148:151], v[92:95]
	v_mfma_f32_16x16x32_bf16 v[92:95], v[228:231], v[152:155], v[92:95]
	v_mfma_f32_16x16x32_bf16 v[88:91], v[216:219], v[156:159], v[88:91]
	v_mfma_f32_16x16x32_bf16 v[88:91], v[220:223], v[160:163], v[88:91]
	v_mfma_f32_16x16x32_bf16 v[84:87], v[224:227], v[156:159], v[84:87]
	v_mfma_f32_16x16x32_bf16 v[84:87], v[228:231], v[160:163], v[84:87]
	v_mfma_f32_16x16x32_bf16 v[80:83], v[216:219], v[182:185], v[80:83]
	v_mfma_f32_16x16x32_bf16 v[80:83], v[220:223], v[190:193], v[80:83]
	v_mfma_f32_16x16x32_bf16 v[76:79], v[224:227], v[182:185], v[76:79]
	v_mfma_f32_16x16x32_bf16 v[76:79], v[228:231], v[190:193], v[76:79]
	v_mfma_f32_16x16x32_bf16 v[72:75], v[216:219], v[194:197], v[72:75]
	v_mfma_f32_16x16x32_bf16 v[72:75], v[220:223], v[212:215], v[72:75]
	v_mfma_f32_16x16x32_bf16 v[68:71], v[224:227], v[194:197], v[68:71]
	v_mfma_f32_16x16x32_bf16 v[68:71], v[228:231], v[212:215], v[68:71]
	s_setprio 0
	s_mov_b32 m0, s28
	v_lshl_add_u64 v[234:235], s[6:7], 0, v[174:175]
	s_barrier
	ds_read_b128 v[148:151], v188 offset:16384
	ds_read_b128 v[152:155], v188 offset:17408
	ds_read_b128 v[156:159], v188 offset:18432
	ds_read_b128 v[160:163], v188 offset:19456
	ds_read_b128 v[182:185], v188 offset:20480
	ds_read_b128 v[190:193], v188 offset:21504
	ds_read_b128 v[194:197], v188 offset:22528
	ds_read_b128 v[212:215], v188 offset:23552
	global_load_lds_dwordx4 v[234:235], off
	v_lshl_add_u64 v[236:237], s[6:7], 0, v[170:171]
	s_mov_b32 m0, s29
	s_nop 0
	global_load_lds_dwordx4 v[236:237], off
	s_barrier
	s_waitcnt lgkmcnt(0)
	s_setprio 1
	s_waitcnt lgkmcnt(0)
	v_mfma_f32_16x16x32_bf16 v[64:67], v[132:135], v[148:151], v[64:67]
	v_mfma_f32_16x16x32_bf16 v[64:67], v[136:139], v[152:155], v[64:67]
	v_mfma_f32_16x16x32_bf16 v[60:63], v[140:143], v[148:151], v[60:63]
	v_mfma_f32_16x16x32_bf16 v[60:63], v[144:147], v[152:155], v[60:63]
	v_mfma_f32_16x16x32_bf16 v[56:59], v[132:135], v[156:159], v[56:59]
	v_mfma_f32_16x16x32_bf16 v[56:59], v[136:139], v[160:163], v[56:59]
	v_mfma_f32_16x16x32_bf16 v[52:55], v[140:143], v[156:159], v[52:55]
	v_mfma_f32_16x16x32_bf16 v[52:55], v[144:147], v[160:163], v[52:55]
	v_mfma_f32_16x16x32_bf16 v[48:51], v[132:135], v[182:185], v[48:51]
	v_mfma_f32_16x16x32_bf16 v[48:51], v[136:139], v[190:193], v[48:51]
	v_mfma_f32_16x16x32_bf16 v[44:47], v[140:143], v[182:185], v[44:47]
	v_mfma_f32_16x16x32_bf16 v[44:47], v[144:147], v[190:193], v[44:47]
	v_mfma_f32_16x16x32_bf16 v[40:43], v[132:135], v[194:197], v[40:43]
	v_mfma_f32_16x16x32_bf16 v[40:43], v[136:139], v[212:215], v[40:43]
	v_mfma_f32_16x16x32_bf16 v[36:39], v[140:143], v[194:197], v[36:39]
	v_mfma_f32_16x16x32_bf16 v[36:39], v[144:147], v[212:215], v[36:39]
	s_setprio 0
	s_barrier
; #define PG8_WAIT_V(n) asm volatile("s_waitcnt vmcnt(" #n ")" ::: "memory")
; #define PG8_WAIT_L(n) asm volatile("s_waitcnt lgkmcnt(" #n ")" ::: "memory")
; #define PG8_BAR __builtin_amdgcn_s_barrier()
; #define PG8_SCHED __builtin_amdgcn_sched_barrier(0)
; template <class Epi, class AddrA, class AddrB>
; __device__ __forceinline__ void gemm_phase(const Sched S, const int lda, const int ldb, const int K, const AddrA addrA,
;                                            const AddrB addrB, const Epi E) {
;     ...
;       PG8_WAIT_V(6); PG8_BAR; PG8_MMA(1, 1, At, B1); PG8_BAR;
;       PG8_LDB(B0, 1, 0); PG8_SCHED; PG8_LDA(At, 1, 0); PG8_STAGE(PG8_SA(0, 1), a2 + hstepA, voffA);
;       PG8_WAIT_L(8); PG8_BAR; PG8_WAIT_L(0); PG8_MMA(0, 0, At, B0); PG8_BAR; PG8_SCHED;
;       PG8_LDB(B1, 1, 1); PG8_STAGE(PG8_SB(1, 0), b3, voffB);
;       PG8_BAR; PG8_WAIT_L(0); PG8_MMA(0, 1, At, B1); PG8_BAR;
;       PG8_LDA(At, 1, 1); PG8_STAGE(PG8_SA(1, 0), a3, voffA);
;       PG8_BAR; PG8_WAIT_L(0); PG8_MMA(1, 0, At, B0); PG8_BAR; PG8_SCHED;
	s_add_u32 s44, s4, 0x80000
	s_addc_u32 s45, s5, 0
	s_add_i32 s43, s46, s27
	v_lshl_add_u64 v[132:133], s[44:45], 0, v[172:173]
	s_mov_b32 m0, s43
	s_nop 0
	global_load_lds_dwordx4 v[132:133], off
	v_lshl_add_u64 v[132:133], s[44:45], 0, v[168:169]
	s_add_i32 m0, s43, 0x2000
	s_nop 0
	global_load_lds_dwordx4 v[132:133], off
	s_waitcnt vmcnt(6)
	s_barrier
	s_setprio 1
	v_mfma_f32_16x16x32_bf16 v[32:35], v[216:219], v[148:151], v[32:35]
	v_mfma_f32_16x16x32_bf16 v[32:35], v[220:223], v[152:155], v[32:35]
	v_mfma_f32_16x16x32_bf16 v[28:31], v[224:227], v[148:151], v[28:31]
	v_mfma_f32_16x16x32_bf16 v[28:31], v[228:231], v[152:155], v[28:31]
	v_mfma_f32_16x16x32_bf16 v[24:27], v[216:219], v[156:159], v[24:27]
	v_mfma_f32_16x16x32_bf16 v[24:27], v[220:223], v[160:163], v[24:27]
	v_mfma_f32_16x16x32_bf16 v[20:23], v[224:227], v[156:159], v[20:23]
	v_mfma_f32_16x16x32_bf16 v[20:23], v[228:231], v[160:163], v[20:23]
	v_mfma_f32_16x16x32_bf16 v[16:19], v[216:219], v[182:185], v[16:19]
	v_mfma_f32_16x16x32_bf16 v[16:19], v[220:223], v[190:193], v[16:19]
	v_mfma_f32_16x16x32_bf16 v[12:15], v[224:227], v[182:185], v[12:15]
	v_mfma_f32_16x16x32_bf16 v[12:15], v[228:231], v[190:193], v[12:15]
	v_mfma_f32_16x16x32_bf16 v[8:11], v[216:219], v[194:197], v[8:11]
	v_mfma_f32_16x16x32_bf16 v[8:11], v[220:223], v[212:215], v[8:11]
	v_mfma_f32_16x16x32_bf16 v[4:7], v[224:227], v[194:197], v[4:7]
	v_mfma_f32_16x16x32_bf16 v[4:7], v[228:231], v[212:215], v[4:7]
	s_setprio 0
	s_add_i32 s43, 0, 0x18000
	v_add_u32_e32 v2, s43, v167
	s_barrier
	ds_read_b128 v[132:135], v2
	ds_read_b128 v[136:139], v2 offset:1024
	ds_read_b128 v[140:143], v2 offset:2048
	ds_read_b128 v[144:147], v2 offset:3072
	s_add_u32 s6, s6, 0x80000
	s_addc_u32 s7, s7, 0
	s_mov_b32 m0, s30
	v_lshl_add_u64 v[216:217], s[6:7], 0, v[174:175]
	ds_read_b128 v[148:151], v188 offset:32768
	ds_read_b128 v[152:155], v188 offset:33792
	ds_read_b128 v[156:159], v188 offset:34816
	ds_read_b128 v[160:163], v188 offset:35840
	ds_read_b128 v[182:185], v188 offset:36864
	ds_read_b128 v[190:193], v188 offset:37888
	ds_read_b128 v[194:197], v188 offset:38912
	ds_read_b128 v[212:215], v188 offset:39936
	global_load_lds_dwordx4 v[216:217], off
	v_lshl_add_u64 v[216:217], s[6:7], 0, v[170:171]
	s_mov_b32 m0, s31
	s_nop 0
	global_load_lds_dwordx4 v[216:217], off
	s_waitcnt lgkmcnt(8)
	s_barrier
	s_waitcnt lgkmcnt(0)
	s_setprio 1
	s_waitcnt lgkmcnt(0)
	v_mfma_f32_16x16x32_bf16 v[128:131], v[132:135], v[148:151], v[128:131]
	v_mfma_f32_16x16x32_bf16 v[128:131], v[136:139], v[152:155], v[128:131]
	v_mfma_f32_16x16x32_bf16 v[124:127], v[140:143], v[148:151], v[124:127]
	v_mfma_f32_16x16x32_bf16 v[124:127], v[144:147], v[152:155], v[124:127]
	v_mfma_f32_16x16x32_bf16 v[120:123], v[132:135], v[156:159], v[120:123]
	v_mfma_f32_16x16x32_bf16 v[120:123], v[136:139], v[160:163], v[120:123]
	v_mfma_f32_16x16x32_bf16 v[116:119], v[140:143], v[156:159], v[116:119]
	v_mfma_f32_16x16x32_bf16 v[116:119], v[144:147], v[160:163], v[116:119]
	v_mfma_f32_16x16x32_bf16 v[112:115], v[132:135], v[182:185], v[112:115]
	v_mfma_f32_16x16x32_bf16 v[112:115], v[136:139], v[190:193], v[112:115]
	v_mfma_f32_16x16x32_bf16 v[108:111], v[140:143], v[182:185], v[108:111]
	v_mfma_f32_16x16x32_bf16 v[108:111], v[144:147], v[190:193], v[108:111]
	v_mfma_f32_16x16x32_bf16 v[104:107], v[132:135], v[194:197], v[104:107]
	v_mfma_f32_16x16x32_bf16 v[104:107], v[136:139], v[212:215], v[104:107]
	v_mfma_f32_16x16x32_bf16 v[100:103], v[140:143], v[194:197], v[100:103]
	v_mfma_f32_16x16x32_bf16 v[100:103], v[144:147], v[212:215], v[100:103]
	s_setprio 0
	s_barrier
	s_add_i32 s6, 0, 0x1c000
	s_add_i32 s7, s43, s27
	v_add_u32_e32 v2, s6, v167
	v_lshl_add_u64 v[0:1], v[0:1], 0, s[52:53]
	s_mov_b32 m0, s7
	ds_read_b128 v[216:219], v2
	ds_read_b128 v[220:223], v2 offset:1024
	ds_read_b128 v[224:227], v2 offset:2048
	ds_read_b128 v[228:231], v2 offset:3072
	global_load_lds_dwordx4 v[0:1], off
	v_lshl_add_u64 v[0:1], v[232:233], 0, s[52:53]
	s_add_i32 m0, s7, 0x2000
	s_nop 0
	global_load_lds_dwordx4 v[0:1], off
	s_barrier
	s_waitcnt lgkmcnt(0)
	s_setprio 1
	s_waitcnt lgkmcnt(0)
	v_mfma_f32_16x16x32_bf16 v[96:99], v[216:219], v[148:151], v[96:99]
	v_mfma_f32_16x16x32_bf16 v[96:99], v[220:223], v[152:155], v[96:99]
	v_mfma_f32_16x16x32_bf16 v[92:95], v[224:227], v[148:151], v[92:95]
	v_mfma_f32_16x16x32_bf16 v[92:95], v[228:231], v[152:155], v[92:95]
	v_mfma_f32_16x16x32_bf16 v[88:91], v[216:219], v[156:159], v[88:91]
	v_mfma_f32_16x16x32_bf16 v[88:91], v[220:223], v[160:163], v[88:91]
	v_mfma_f32_16x16x32_bf16 v[84:87], v[224:227], v[156:159], v[84:87]
	v_mfma_f32_16x16x32_bf16 v[84:87], v[228:231], v[160:163], v[84:87]
	v_mfma_f32_16x16x32_bf16 v[80:83], v[216:219], v[182:185], v[80:83]
	v_mfma_f32_16x16x32_bf16 v[80:83], v[220:223], v[190:193], v[80:83]
	v_mfma_f32_16x16x32_bf16 v[76:79], v[224:227], v[182:185], v[76:79]
	v_mfma_f32_16x16x32_bf16 v[76:79], v[228:231], v[190:193], v[76:79]
	v_mfma_f32_16x16x32_bf16 v[72:75], v[216:219], v[194:197], v[72:75]
	v_mfma_f32_16x16x32_bf16 v[72:75], v[220:223], v[212:215], v[72:75]
	v_mfma_f32_16x16x32_bf16 v[68:71], v[224:227], v[194:197], v[68:71]
	v_mfma_f32_16x16x32_bf16 v[68:71], v[228:231], v[212:215], v[68:71]
	s_setprio 0
	s_mov_b32 m0, s38
	v_lshl_add_u64 v[0:1], v[234:235], 0, s[52:53]
	s_barrier
	ds_read_b128 v[148:151], v188 offset:49152
	ds_read_b128 v[152:155], v188 offset:50176
	ds_read_b128 v[156:159], v188 offset:51200
	ds_read_b128 v[160:163], v188 offset:52224
	ds_read_b128 v[182:185], v188 offset:53248
	ds_read_b128 v[190:193], v188 offset:54272
	ds_read_b128 v[194:197], v188 offset:55296
	ds_read_b128 v[212:215], v188 offset:56320
	global_load_lds_dwordx4 v[0:1], off
	v_lshl_add_u64 v[0:1], v[236:237], 0, s[52:53]
	s_mov_b32 m0, s39
	s_nop 0
	global_load_lds_dwordx4 v[0:1], off
	s_barrier
; #define PG8_WAIT_V(n) asm volatile("s_waitcnt vmcnt(" #n ")" ::: "memory")
; #define PG8_WAIT_L(n) asm volatile("s_waitcnt lgkmcnt(" #n ")" ::: "memory")
; #define PG8_BAR __builtin_amdgcn_s_barrier()
; #define PG8_SCHED __builtin_amdgcn_sched_barrier(0)
; template <class Epi, class AddrA, class AddrB>
; __device__ __forceinline__ void gemm_phase(const Sched S, const int lda, const int ldb, const int K, const AddrA addrA,
;                                            const AddrB addrB, const Epi E) {
;     ...
;       PG8_BAR; PG8_WAIT_L(0); PG8_MMA(1, 0, At, B0); PG8_BAR; PG8_SCHED;
;       PG8_STAGE(PG8_SB(1, 1), b3 + hstepB, voffB);
;       PG8_WAIT_V(6); PG8_BAR; PG8_MMA(1, 1, At, B1); PG8_BAR;
;   __device__ __forceinline__ void operator()(EPI_ARGS) const {
;     const int col0 = u.pn * 256 + wc * 32 + 8 * fq;
;     const int br = u.br, brn = br < 2 ? br + 1 : 2;
;     const unsigned loff0 = (unsigned)((wr * 64 + fr) * PLD + wc * 32 + 8 * fq);
;     const bf16_t* pc = proj + ((size_t)((GT + br * DM) / 256 + u.pn) * MTOK + (size_t)u.pm * 256) * PLD;
;     const bf16_t* pn_ = proj + ((size_t)((GT + brn * DM) / 256 + u.pn) * MTOK + (size_t)u.pm * 256) * PLD;
;     bf16_t* mrow = merged + ((size_t)u.pm * 256 + wr * 64 + fr) * DM + col0;
; #pragma unroll
;     for (int bj = 0; bj < 2; ++bj) {
;       const int c = col0 + bj * HALF;
;       float gc[8], gn[8];
;       {
;         const f32x4 a0 = *(const f32x4*)(bg + br * DM + c), a1 = *(const f32x4*)(bg + br * DM + c + 4);
;         const f32x4 b0 = *(const f32x4*)(bg + brn * DM + c), b1 = *(const f32x4*)(bg + brn * DM + c + 4);
; #pragma unroll
;         for (int k = 0; k < 4; ++k) { gc[k] = a0[k]; gc[4 + k] = a1[k]; gn[k] = b0[k]; gn[4 + k] = b1[k]; }
;       }
; #pragma unroll
;       for (int ai = 0; ai < 2; ++ai) {
;         unsigned loff = loff0;
;         asm volatile("" : "+v"(loff));
;         u32x4 zc[4], zn[4];
; #pragma unroll
;         for (int m = 0; m < 4; ++m) {
;           const unsigned o = loff + (unsigned)((ai * HALF + m * 16) * PLD + bj * HALF);
;           zc[m] = *(const u32x4*)(pc + o);
;           zn[m] = *(const u32x4*)(pn_ + o);
;         }
	s_waitcnt lgkmcnt(0)
	s_setprio 1
	s_waitcnt lgkmcnt(0)
	v_mfma_f32_16x16x32_bf16 v[64:67], v[132:135], v[148:151], v[64:67]
	v_mfma_f32_16x16x32_bf16 v[64:67], v[136:139], v[152:155], v[64:67]
	v_mfma_f32_16x16x32_bf16 v[60:63], v[140:143], v[148:151], v[60:63]
	v_mfma_f32_16x16x32_bf16 v[60:63], v[144:147], v[152:155], v[60:63]
	v_mfma_f32_16x16x32_bf16 v[56:59], v[132:135], v[156:159], v[56:59]
	v_mfma_f32_16x16x32_bf16 v[56:59], v[136:139], v[160:163], v[56:59]
	v_mfma_f32_16x16x32_bf16 v[52:55], v[140:143], v[156:159], v[52:55]
	v_mfma_f32_16x16x32_bf16 v[52:55], v[144:147], v[160:163], v[52:55]
	v_mfma_f32_16x16x32_bf16 v[48:51], v[132:135], v[182:185], v[48:51]
	v_mfma_f32_16x16x32_bf16 v[48:51], v[136:139], v[190:193], v[48:51]
	v_mfma_f32_16x16x32_bf16 v[44:47], v[140:143], v[182:185], v[44:47]
	v_mfma_f32_16x16x32_bf16 v[44:47], v[144:147], v[190:193], v[44:47]
	v_mfma_f32_16x16x32_bf16 v[40:43], v[132:135], v[194:197], v[40:43]
	v_mfma_f32_16x16x32_bf16 v[40:43], v[136:139], v[212:215], v[40:43]
	v_mfma_f32_16x16x32_bf16 v[36:39], v[140:143], v[194:197], v[36:39]
	v_mfma_f32_16x16x32_bf16 v[36:39], v[144:147], v[212:215], v[36:39]
	s_setprio 0
	s_barrier
	s_add_u32 s4, s4, 0x80080
	s_addc_u32 s5, s5, 0
	s_add_i32 s6, s6, s27
	v_lshl_add_u64 v[0:1], s[4:5], 0, v[172:173]
	s_mov_b32 m0, s6
	s_nop 0
	global_load_lds_dwordx4 v[0:1], off
	v_lshl_add_u64 v[0:1], s[4:5], 0, v[168:169]
	s_add_i32 m0, s6, 0x2000
	s_nop 0
	global_load_lds_dwordx4 v[0:1], off
	s_waitcnt vmcnt(6)
	s_barrier
	s_setprio 1
	v_mfma_f32_16x16x32_bf16 v[32:35], v[216:219], v[148:151], v[32:35]
	v_mfma_f32_16x16x32_bf16 v[32:35], v[220:223], v[152:155], v[32:35]
	v_mfma_f32_16x16x32_bf16 v[28:31], v[224:227], v[148:151], v[28:31]
	v_mfma_f32_16x16x32_bf16 v[28:31], v[228:231], v[152:155], v[28:31]
	v_mfma_f32_16x16x32_bf16 v[24:27], v[216:219], v[156:159], v[24:27]
	v_mfma_f32_16x16x32_bf16 v[24:27], v[220:223], v[160:163], v[24:27]
	v_mfma_f32_16x16x32_bf16 v[20:23], v[224:227], v[156:159], v[20:23]
	v_mfma_f32_16x16x32_bf16 v[20:23], v[228:231], v[160:163], v[20:23]
	v_mfma_f32_16x16x32_bf16 v[16:19], v[216:219], v[182:185], v[16:19]
	v_mfma_f32_16x16x32_bf16 v[16:19], v[220:223], v[190:193], v[16:19]
	v_mfma_f32_16x16x32_bf16 v[12:15], v[224:227], v[182:185], v[12:15]
	v_mfma_f32_16x16x32_bf16 v[12:15], v[228:231], v[190:193], v[12:15]
	v_mfma_f32_16x16x32_bf16 v[8:11], v[216:219], v[194:197], v[8:11]
	v_mfma_f32_16x16x32_bf16 v[8:11], v[220:223], v[212:215], v[8:11]
	v_mfma_f32_16x16x32_bf16 v[4:7], v[224:227], v[194:197], v[4:7]
	v_mfma_f32_16x16x32_bf16 v[4:7], v[228:231], v[212:215], v[4:7]
	s_setprio 0
	s_add_i32 s42, s42, 2
	s_add_u32 s33, s33, 0x100
	s_addc_u32 s41, s41, 0
	s_add_u32 s2, s2, 0x100
	s_addc_u32 s3, s3, 0
	s_cmp_gt_u32 s42, 29
	s_barrier
	s_cbranch_scc0 .LBB0_543
	s_cmp_gt_i32 s10, 1
	s_cselect_b64 s[6:7], -1, 0
	s_lshl_b32 s42, s10, 11
	s_add_i32 s2, s42, 0x4c00
	s_ashr_i32 s2, s2, 8
	s_add_i32 s2, s2, s11
	s_ashr_i32 s3, s2, 31
	s_min_i32 s1, s10, 1
	s_ashr_i32 s9, s8, 31
	s_lshl_b64 s[2:3], s[2:3], 23
	s_add_u32 s2, s34, s2
	s_addc_u32 s3, s35, s3
	s_lshl_b64 s[4:5], s[8:9], 17
	s_add_u32 s2, s2, s4
	s_addc_u32 s3, s3, s5
	s_lshl_b32 s1, s1, 11
	s_add_i32 s44, s1, 0x800
	s_addk_i32 s1, 0x5400
	s_ashr_i32 s1, s1, 8
	s_add_i32 s46, s1, s11
	s_ashr_i32 s47, s46, 31
	s_lshl_b64 s[46:47], s[46:47], 23
	s_add_u32 s1, s34, s46
	v_lshl_or_b32 v132, s11, 8, v187
	s_addc_u32 s11, s35, s47
	s_add_u32 s4, s1, s4
	s_addc_u32 s5, s11, s5
	s_ashr_i32 s43, s42, 31
	s_lshl_b64 s[8:9], s[8:9], 20
	s_ashr_i32 s45, s44, 31
	s_lshl_b64 s[42:43], s[42:43], 2
	s_add_u32 s42, s36, s42
	s_addc_u32 s43, s37, s43
	s_lshl_b64 s[44:45], s[44:45], 2
	s_add_u32 s44, s36, s44
	v_lshl_add_u64 v[0:1], v[176:177], 0, s[8:9]
	v_ashrrev_i32_e32 v133, 31, v132
	s_addc_u32 s45, s37, s45
	v_lshl_add_u64 v[0:1], v[132:133], 1, v[0:1]
	v_lshlrev_b64 v[132:133], 2, v[132:133]
	v_lshl_add_u64 v[182:183], s[42:43], 0, v[132:133]
	v_lshl_add_u64 v[184:185], s[44:45], 0, v[132:133]
	v_mov_b32_e32 v2, v186
	global_load_dwordx4 v[144:147], v[182:183], off
	global_load_dwordx4 v[136:139], v[182:183], off offset:16
	global_load_dwordx4 v[140:143], v[184:185], off
	global_load_dwordx4 v[132:135], v[184:185], off offset:16
	s_cmp_lt_i32 s10, 2
	v_lshlrev_b64 v[148:149], 1, v[2:3]
	v_lshl_add_u64 v[150:151], s[2:3], 0, v[148:149]
	v_lshl_add_u64 v[148:149], s[4:5], 0, v[148:149]
	flat_load_dwordx4 v[190:193], v[150:151]
	flat_load_dwordx4 v[160:163], v[148:149]
	v_add_u32_e32 v148, 0x1000, v2
	v_mov_b32_e32 v149, v3
	v_lshlrev_b64 v[148:149], 1, v[148:149]
	v_lshl_add_u64 v[150:151], s[2:3], 0, v[148:149]
	v_lshl_add_u64 v[148:149], s[4:5], 0, v[148:149]
	flat_load_dwordx4 v[194:197], v[150:151]
	flat_load_dwordx4 v[156:159], v[148:149]
	v_add_u32_e32 v148, 0x2000, v2
	v_mov_b32_e32 v149, v3
	v_lshlrev_b64 v[148:149], 1, v[148:149]
	v_lshl_add_u64 v[150:151], s[2:3], 0, v[148:149]
	v_lshl_add_u64 v[148:149], s[4:5], 0, v[148:149]
	v_add_u32_e32 v2, 0x3000, v2
	flat_load_dwordx4 v[234:237], v[150:151]
	flat_load_dwordx4 v[152:155], v[148:149]
	v_lshlrev_b64 v[148:149], 1, v[2:3]
	v_lshl_add_u64 v[150:151], s[2:3], 0, v[148:149]
	v_lshl_add_u64 v[148:149], s[4:5], 0, v[148:149]
	flat_load_dwordx4 v[238:241], v[150:151]
	s_nop 0
	flat_load_dwordx4 v[148:151], v[148:149]
	s_waitcnt vmcnt(0) lgkmcnt(0)
; __device__ __forceinline__ float sigmoidf_(float x) { return __builtin_amdgcn_rcpf(1.0f + __expf(-x)); }
;   __device__ __forceinline__ void operator()(EPI_ARGS) const {
;     ...
;             unpack8(zc[m], xc);
;             unpack8(zn[m], xn);
; #pragma unroll
;             for (int k = 0; k < 8; ++k) {
;               const float ec = __expf(-fmaxf(xc[k] + gc[k], -40.f)), en = __expf(-fmaxf(xn[k] + gn[k], -40.f));
;               const float f = (1.0f + en) * __builtin_amdgcn_rcpf(1.0f + ec);
;               acc[ai][bj][m][k >> 2][k & 3] *= f;
;             }
;           }
;         } else {
; #pragma unroll
;           for (int m = 0; m < 4; ++m) {
;             float xc[8], y[8];
;             unpack8(zc[m], xc);
; #pragma unroll
;             for (int k = 0; k < 8; ++k) y[k] = acc[ai][bj][m][k >> 2][k & 3] * sigmoidf_(fmaxf(xc[k] + gc[k], -40.f));
;             u32x4 o;
;             o.x = pack2(y[0], y[1]); o.y = pack2(y[2], y[3]); o.z = pack2(y[4], y[5]); o.w = pack2(y[6], y[7]);
;             *(u32x4*)(mrow + (size_t)(ai * HALF + m * 16) * DM + bj * HALF) = o;
	v_lshlrev_b32_e32 v2, 16, v190
	v_and_b32_e32 v189, 0xffff0000, v190
	v_lshlrev_b32_e32 v190, 16, v191
	v_and_b32_e32 v191, 0xffff0000, v191
	v_lshlrev_b32_e32 v212, 16, v192
	v_and_b32_e32 v192, 0xffff0000, v192
	v_lshlrev_b32_e32 v213, 16, v193
	v_and_b32_e32 v193, 0xffff0000, v193
	v_add_f32_e32 v2, v144, v2
	v_add_f32_e32 v189, v145, v189
	v_add_f32_e32 v190, v146, v190
	v_add_f32_e32 v191, v147, v191
	v_add_f32_e32 v212, v136, v212
	v_add_f32_e32 v192, v137, v192
	v_add_f32_e32 v213, v138, v213
	v_add_f32_e32 v193, v139, v193
	s_mov_b64 s[8:9], -1
	v_max_f32_e32 v233, 0xc2200000, v2
	v_max_f32_e32 v232, 0xc2200000, v189
	v_max_f32_e32 v231, 0xc2200000, v190
	v_max_f32_e32 v230, 0xc2200000, v191
	v_max_f32_e32 v229, 0xc2200000, v212
	v_max_f32_e32 v228, 0xc2200000, v192
	v_max_f32_e32 v227, 0xc2200000, v213
	v_max_f32_e32 v226, 0xc2200000, v193
	v_lshlrev_b32_e32 v225, 16, v194
	v_and_b32_e32 v224, 0xffff0000, v194
	v_lshlrev_b32_e32 v223, 16, v195
	v_and_b32_e32 v222, 0xffff0000, v195
	v_lshlrev_b32_e32 v221, 16, v196
	v_and_b32_e32 v220, 0xffff0000, v196
	v_lshlrev_b32_e32 v219, 16, v197
	v_and_b32_e32 v218, 0xffff0000, v197
	v_lshlrev_b32_e32 v217, 16, v234
	v_and_b32_e32 v216, 0xffff0000, v234
	v_lshlrev_b32_e32 v215, 16, v235
	v_and_b32_e32 v214, 0xffff0000, v235
	v_lshlrev_b32_e32 v213, 16, v236
	v_and_b32_e32 v212, 0xffff0000, v236
	v_lshlrev_b32_e32 v197, 16, v237
	v_and_b32_e32 v196, 0xffff0000, v237
	v_lshlrev_b32_e32 v195, 16, v238
	v_and_b32_e32 v194, 0xffff0000, v238
	v_lshlrev_b32_e32 v193, 16, v239
	v_and_b32_e32 v192, 0xffff0000, v239
	v_lshlrev_b32_e32 v191, 16, v240
	v_and_b32_e32 v190, 0xffff0000, v240
	v_lshlrev_b32_e32 v189, 16, v241
	v_and_b32_e32 v2, 0xffff0000, v241
	s_cbranch_scc1 .LBB0_546
	v_mul_f32_e32 v234, 0xbfb8aa3b, v233
	v_mul_f32_e32 v235, 0xbfb8aa3b, v232
	v_mul_f32_e32 v236, 0xbfb8aa3b, v231
	v_exp_f32_e32 v234, v234
	v_exp_f32_e32 v235, v235
	v_exp_f32_e32 v236, v236
	v_mul_f32_e32 v237, 0xbfb8aa3b, v230
	v_exp_f32_e32 v237, v237
	v_mul_f32_e32 v238, 0xbfb8aa3b, v229
	v_mul_f32_e32 v239, 0xbfb8aa3b, v228
	v_add_f32_e32 v234, 1.0, v234
	v_add_f32_e32 v235, 1.0, v235
	v_add_f32_e32 v236, 1.0, v236
	v_exp_f32_e32 v238, v238
	v_exp_f32_e32 v239, v239
	v_mul_f32_e32 v240, 0xbfb8aa3b, v227
	v_mul_f32_e32 v241, 0xbfb8aa3b, v226
	v_rcp_f32_e32 v234, v234
	v_rcp_f32_e32 v235, v235
	v_rcp_f32_e32 v236, v236
	v_add_f32_e32 v237, 1.0, v237
	v_exp_f32_e32 v240, v240
	v_exp_f32_e32 v241, v241
	v_rcp_f32_e32 v237, v237
	v_add_f32_e32 v238, 1.0, v238
	v_add_f32_e32 v239, 1.0, v239
	v_mul_f32_e32 v234, v128, v234
	v_mul_f32_e32 v235, v129, v235
	v_mul_f32_e32 v236, v130, v236
	v_rcp_f32_e32 v238, v238
	v_rcp_f32_e32 v239, v239
	v_add_f32_e32 v240, 1.0, v240
	v_add_f32_e32 v241, 1.0, v241
	v_mul_f32_e32 v237, v131, v237
	v_rcp_f32_e32 v240, v240
	v_rcp_f32_e32 v241, v241
	v_cvt_pk_bf16_f32 v234, v234, v235
	v_cvt_pk_bf16_f32 v235, v236, v237
	v_add_f32_e32 v236, v144, v225
	v_max_f32_e32 v236, 0xc2200000, v236
	v_mul_f32_e32 v236, 0xbfb8aa3b, v236
	v_mul_f32_e32 v238, v124, v238
	v_mul_f32_e32 v239, v125, v239
	v_exp_f32_e32 v242, v236
	v_cvt_pk_bf16_f32 v236, v238, v239
	v_mul_f32_e32 v240, v126, v240
	v_mul_f32_e32 v241, v127, v241
	v_cvt_pk_bf16_f32 v237, v240, v241
	flat_store_dwordx4 v[0:1], v[234:237]
	v_add_f32_e32 v238, v136, v221
	v_max_f32_e32 v238, 0xc2200000, v238
	v_add_f32_e32 v235, v145, v224
	v_add_f32_e32 v236, v146, v223
	v_max_f32_e32 v235, 0xc2200000, v235
	v_max_f32_e32 v236, 0xc2200000, v236
	v_add_f32_e32 v237, v147, v222
	v_add_f32_e32 v239, v137, v220
	v_mul_f32_e32 v235, 0xbfb8aa3b, v235
	v_mul_f32_e32 v236, 0xbfb8aa3b, v236
	v_max_f32_e32 v237, 0xc2200000, v237
	v_mul_f32_e32 v238, 0xbfb8aa3b, v238
	v_max_f32_e32 v239, 0xc2200000, v239
	v_exp_f32_e32 v235, v235
	v_exp_f32_e32 v236, v236
	v_mul_f32_e32 v237, 0xbfb8aa3b, v237
	v_exp_f32_e32 v238, v238
	v_mul_f32_e32 v239, 0xbfb8aa3b, v239
	v_add_f32_e32 v240, v138, v219
	v_exp_f32_e32 v237, v237
	v_exp_f32_e32 v239, v239
	v_max_f32_e32 v240, 0xc2200000, v240
	v_add_f32_e32 v241, v139, v218
	v_mul_f32_e32 v240, 0xbfb8aa3b, v240
	v_max_f32_e32 v241, 0xc2200000, v241
	v_exp_f32_e32 v240, v240
	v_mul_f32_e32 v241, 0xbfb8aa3b, v241
	v_add_f32_e32 v234, 1.0, v242
	v_add_f32_e32 v235, 1.0, v235
	v_add_f32_e32 v236, 1.0, v236
	v_add_f32_e32 v238, 1.0, v238
	v_exp_f32_e32 v241, v241
	v_rcp_f32_e32 v234, v234
	v_rcp_f32_e32 v235, v235
	v_rcp_f32_e32 v236, v236
	v_add_f32_e32 v237, 1.0, v237
	v_rcp_f32_e32 v238, v238
	v_add_f32_e32 v239, 1.0, v239
	v_rcp_f32_e32 v237, v237
	v_rcp_f32_e32 v239, v239
	v_add_f32_e32 v240, 1.0, v240
	v_rcp_f32_e32 v240, v240
	v_add_f32_e32 v241, 1.0, v241
	v_mul_f32_e32 v234, v120, v234
; __device__ __forceinline__ float sigmoidf_(float x) { return __builtin_amdgcn_rcpf(1.0f + __expf(-x)); }
;   __device__ __forceinline__ void operator()(EPI_ARGS) const {
;     ...
;           for (int m = 0; m < 4; ++m) {
;             float xc[8], y[8];
;             unpack8(zc[m], xc);
; #pragma unroll
;             for (int k = 0; k < 8; ++k) y[k] = acc[ai][bj][m][k >> 2][k & 3] * sigmoidf_(fmaxf(xc[k] + gc[k], -40.f));
;             u32x4 o;
;             o.x = pack2(y[0], y[1]); o.y = pack2(y[2], y[3]); o.z = pack2(y[4], y[5]); o.w = pack2(y[6], y[7]);
;             *(u32x4*)(mrow + (size_t)(ai * HALF + m * 16) * DM + bj * HALF) = o;
;           }
	v_mul_f32_e32 v235, v121, v235
	v_mul_f32_e32 v236, v122, v236
	v_rcp_f32_e32 v241, v241
	v_mul_f32_e32 v238, v116, v238
	v_mul_f32_e32 v237, v123, v237
	v_mul_f32_e32 v239, v117, v239
	v_cvt_pk_bf16_f32 v234, v234, v235
	v_cvt_pk_bf16_f32 v235, v236, v237
	v_cvt_pk_bf16_f32 v236, v238, v239
	v_add_f32_e32 v238, v144, v217
	v_max_f32_e32 v238, 0xc2200000, v238
	v_mul_f32_e32 v240, v118, v240
	v_mul_f32_e32 v238, 0xbfb8aa3b, v238
	v_mul_f32_e32 v241, v119, v241
	v_cvt_pk_bf16_f32 v237, v240, v241
	v_exp_f32_e32 v240, v238
	v_add_co_u32_e32 v238, vcc, s67, v0
	v_add_f32_e32 v241, v139, v196
	s_nop 0
	v_addc_co_u32_e32 v239, vcc, 0, v1, vcc
	flat_store_dwordx4 v[238:239], v[234:237]
	v_add_f32_e32 v238, v136, v213
	v_max_f32_e32 v238, 0xc2200000, v238
	v_add_f32_e32 v235, v145, v216
	v_add_f32_e32 v236, v146, v215
	v_max_f32_e32 v235, 0xc2200000, v235
	v_max_f32_e32 v236, 0xc2200000, v236
	v_add_f32_e32 v237, v147, v214
	v_add_f32_e32 v239, v137, v212
	v_mul_f32_e32 v235, 0xbfb8aa3b, v235
	v_mul_f32_e32 v236, 0xbfb8aa3b, v236
	v_max_f32_e32 v237, 0xc2200000, v237
	v_mul_f32_e32 v238, 0xbfb8aa3b, v238
	v_max_f32_e32 v239, 0xc2200000, v239
	v_add_f32_e32 v234, 1.0, v240
	v_exp_f32_e32 v235, v235
	v_exp_f32_e32 v236, v236
	v_mul_f32_e32 v237, 0xbfb8aa3b, v237
	v_exp_f32_e32 v238, v238
	v_mul_f32_e32 v239, 0xbfb8aa3b, v239
	v_add_f32_e32 v240, v138, v197
	v_exp_f32_e32 v237, v237
	v_exp_f32_e32 v239, v239
	v_max_f32_e32 v240, 0xc2200000, v240
	v_mul_f32_e32 v240, 0xbfb8aa3b, v240
	v_max_f32_e32 v241, 0xc2200000, v241
	v_exp_f32_e32 v240, v240
	v_mul_f32_e32 v241, 0xbfb8aa3b, v241
	v_add_f32_e32 v235, 1.0, v235
	v_add_f32_e32 v236, 1.0, v236
	v_add_f32_e32 v238, 1.0, v238
	v_exp_f32_e32 v241, v241
	v_rcp_f32_e32 v234, v234
	v_rcp_f32_e32 v235, v235
	v_rcp_f32_e32 v236, v236
	v_add_f32_e32 v237, 1.0, v237
	v_rcp_f32_e32 v238, v238
	v_add_f32_e32 v239, 1.0, v239
	v_rcp_f32_e32 v237, v237
	v_rcp_f32_e32 v239, v239
	v_add_f32_e32 v240, 1.0, v240
	v_rcp_f32_e32 v240, v240
	v_add_f32_e32 v241, 1.0, v241
	v_mul_f32_e32 v234, v112, v234
	v_mul_f32_e32 v235, v113, v235
	v_mul_f32_e32 v236, v114, v236
	v_rcp_f32_e32 v241, v241
	v_mul_f32_e32 v238, v108, v238
	v_mul_f32_e32 v237, v115, v237
	v_mul_f32_e32 v239, v109, v239
	v_cvt_pk_bf16_f32 v234, v234, v235
	v_cvt_pk_bf16_f32 v235, v236, v237
	v_cvt_pk_bf16_f32 v236, v238, v239
	v_add_f32_e32 v238, v144, v195
	v_max_f32_e32 v238, 0xc2200000, v238
	v_mul_f32_e32 v240, v110, v240
	v_mul_f32_e32 v238, 0xbfb8aa3b, v238
	s_mov_b32 s1, 0x20000
	v_mul_f32_e32 v241, v111, v241
	v_cvt_pk_bf16_f32 v237, v240, v241
	v_exp_f32_e32 v240, v238
	v_add_co_u32_e32 v238, vcc, s1, v0
	v_add_f32_e32 v241, v139, v2
	s_nop 0
	v_addc_co_u32_e32 v239, vcc, 0, v1, vcc
	flat_store_dwordx4 v[238:239], v[234:237]
	v_add_f32_e32 v238, v136, v191
	v_max_f32_e32 v238, 0xc2200000, v238
	v_add_f32_e32 v235, v145, v194
	v_add_f32_e32 v236, v146, v193
	v_max_f32_e32 v235, 0xc2200000, v235
	v_max_f32_e32 v236, 0xc2200000, v236
	v_add_f32_e32 v237, v147, v192
	v_add_f32_e32 v239, v137, v190
	v_mul_f32_e32 v235, 0xbfb8aa3b, v235
	v_mul_f32_e32 v236, 0xbfb8aa3b, v236
	v_max_f32_e32 v237, 0xc2200000, v237
	v_mul_f32_e32 v238, 0xbfb8aa3b, v238
	v_max_f32_e32 v239, 0xc2200000, v239
	v_add_f32_e32 v234, 1.0, v240
	v_exp_f32_e32 v235, v235
	v_exp_f32_e32 v236, v236
	v_mul_f32_e32 v237, 0xbfb8aa3b, v237
	v_exp_f32_e32 v238, v238
	v_mul_f32_e32 v239, 0xbfb8aa3b, v239
	v_add_f32_e32 v240, v138, v189
	v_exp_f32_e32 v237, v237
	v_exp_f32_e32 v239, v239
	v_max_f32_e32 v240, 0xc2200000, v240
	v_max_f32_e32 v241, 0xc2200000, v241
	v_mul_f32_e32 v240, 0xbfb8aa3b, v240
	v_mul_f32_e32 v241, 0xbfb8aa3b, v241
	v_exp_f32_e32 v240, v240
	v_exp_f32_e32 v241, v241
	v_add_f32_e32 v235, 1.0, v235
	v_add_f32_e32 v236, 1.0, v236
	v_add_f32_e32 v238, 1.0, v238
	v_rcp_f32_e32 v234, v234
	v_rcp_f32_e32 v235, v235
	v_rcp_f32_e32 v236, v236
	v_add_f32_e32 v237, 1.0, v237
	v_rcp_f32_e32 v238, v238
	v_add_f32_e32 v239, 1.0, v239
	v_rcp_f32_e32 v237, v237
	v_rcp_f32_e32 v239, v239
	v_add_f32_e32 v240, 1.0, v240
	v_add_f32_e32 v241, 1.0, v241
	v_rcp_f32_e32 v240, v240
	v_rcp_f32_e32 v241, v241
	v_mul_f32_e32 v234, v104, v234
	v_mul_f32_e32 v235, v105, v235
	v_mul_f32_e32 v236, v106, v236
	v_mul_f32_e32 v238, v100, v238
	v_mul_f32_e32 v237, v107, v237
	v_mul_f32_e32 v239, v101, v239
	v_cvt_pk_bf16_f32 v234, v234, v235
	v_cvt_pk_bf16_f32 v235, v236, v237
	v_cvt_pk_bf16_f32 v236, v238, v239
	v_add_co_u32_e32 v238, vcc, 0x30000, v0
	s_mov_b64 s[8:9], 0
	s_nop 0
	v_addc_co_u32_e32 v239, vcc, 0, v1, vcc
	v_mul_f32_e32 v240, v102, v240
	v_mul_f32_e32 v241, v103, v241
	v_cvt_pk_bf16_f32 v237, v240, v241
	flat_store_dwordx4 v[238:239], v[234:237]

; #define PG8_WAIT_V(n) asm volatile("s_waitcnt vmcnt(" #n ")" ::: "memory")
; #define PG8_WAIT_L(n) asm volatile("s_waitcnt lgkmcnt(" #n ")" ::: "memory")
; #define PG8_BAR __builtin_amdgcn_s_barrier()
; #define PG8_SCHED __builtin_amdgcn_sched_barrier(0)
; template <class Epi, class AddrA, class AddrB>
; __device__ __forceinline__ void gemm_phase(const Sched S, const int lda, const int ldb, const int K, const AddrA addrA,
;                                            const AddrB addrB, const Epi E) {
;     ...
;       const char* a1 = cA + (size_t)(t + 1) * kstep;
;       const char* a2 = last ? nA : cA + (size_t)(t + 2) * kstep;
;       const char* b2 = last ? nB : cB + (size_t)(t + 2) * kstep;
;       const char* a3 = a2 + kstep;
;       const char* b3 = b2 + kstep;
;       PG8_LDB(B0, 0, 0); PG8_SCHED; PG8_LDA(At, 0, 0); PG8_STAGE(PG8_SA(1, 1), a1 + hstepA, voffA);
;       PG8_WAIT_L(8); PG8_BAR; PG8_WAIT_L(0); PG8_MMA(0, 0, At, B0); PG8_BAR; PG8_SCHED;
;       PG8_LDB(B1, 0, 1); PG8_STAGE(PG8_SB(0, 0), b2, voffB);
;       PG8_BAR; PG8_WAIT_L(0); PG8_MMA(0, 1, At, B1); PG8_BAR;
;       PG8_LDA(At, 0, 1); PG8_STAGE(PG8_SA(0, 0), a2, voffA);
;       PG8_BAR; PG8_WAIT_L(0); PG8_MMA(1, 0, At, B0); PG8_BAR; PG8_SCHED;
;       PG8_STAGE(PG8_SB(0, 1), b2 + hstepB, voffB);
;       PG8_WAIT_V(6); PG8_BAR; PG8_MMA(1, 1, At, B1); PG8_BAR;
.LBB0_619:
	s_add_u32 s16, s14, 0xfff80080
	s_addc_u32 s17, s15, -1
	s_add_i32 s39, 0, 0x10000
	v_add_u32_e32 v142, s39, v144
	ds_read_b128 v[148:151], v142
	ds_read_b128 v[152:155], v142 offset:1024
	ds_read_b128 v[156:159], v142 offset:2048
	ds_read_b128 v[160:163], v142 offset:3072
	s_cmp_eq_u32 s38, 28
	s_cselect_b32 s19, s3, s17
	s_cselect_b32 s18, s13, s16
	s_cselect_b32 s17, s5, s37
	s_cselect_b32 s16, s35, s36
	v_lshl_add_u64 v[142:143], s[14:15], 0, v[140:141]
	s_add_i32 m0, s26, 0xc000
	ds_read_b128 v[168:171], v146
	ds_read_b128 v[172:175], v146 offset:1024
	ds_read_b128 v[176:179], v146 offset:2048
	ds_read_b128 v[180:183], v146 offset:3072
	ds_read_b128 v[184:187], v146 offset:4096
	ds_read_b128 v[188:191], v146 offset:5120
	ds_read_b128 v[192:195], v146 offset:6144
	ds_read_b128 v[212:215], v146 offset:7168
	global_load_lds_dwordx4 v[142:143], off
	v_lshl_add_u64 v[142:143], s[14:15], 0, v[138:139]
	s_add_i32 m0, s26, 0xe000
	s_nop 0
	global_load_lds_dwordx4 v[142:143], off
	s_waitcnt lgkmcnt(8)
	s_barrier
	s_waitcnt lgkmcnt(0)
	s_setprio 1
	s_waitcnt lgkmcnt(0)
	v_mfma_f32_16x16x32_bf16 v[128:131], v[148:151], v[168:171], v[128:131]
	v_mfma_f32_16x16x32_bf16 v[128:131], v[152:155], v[172:175], v[128:131]
	v_mfma_f32_16x16x32_bf16 v[124:127], v[156:159], v[168:171], v[124:127]
	v_mfma_f32_16x16x32_bf16 v[124:127], v[160:163], v[172:175], v[124:127]
	v_mfma_f32_16x16x32_bf16 v[120:123], v[148:151], v[176:179], v[120:123]
	v_mfma_f32_16x16x32_bf16 v[120:123], v[152:155], v[180:183], v[120:123]
	v_mfma_f32_16x16x32_bf16 v[116:119], v[156:159], v[176:179], v[116:119]
	v_mfma_f32_16x16x32_bf16 v[116:119], v[160:163], v[180:183], v[116:119]
	v_mfma_f32_16x16x32_bf16 v[112:115], v[148:151], v[184:187], v[112:115]
	v_mfma_f32_16x16x32_bf16 v[112:115], v[152:155], v[188:191], v[112:115]
	v_mfma_f32_16x16x32_bf16 v[108:111], v[156:159], v[184:187], v[108:111]
	v_mfma_f32_16x16x32_bf16 v[108:111], v[160:163], v[188:191], v[108:111]
	v_mfma_f32_16x16x32_bf16 v[104:107], v[148:151], v[192:195], v[104:107]
	v_mfma_f32_16x16x32_bf16 v[104:107], v[152:155], v[212:215], v[104:107]
	v_mfma_f32_16x16x32_bf16 v[100:103], v[156:159], v[192:195], v[100:103]
	v_mfma_f32_16x16x32_bf16 v[100:103], v[160:163], v[212:215], v[100:103]
	s_setprio 0
	s_barrier
	s_add_i32 s42, 0, 0x14000
	v_add_u32_e32 v142, s42, v144
	s_add_i32 s39, s39, s25
	ds_read_b128 v[216:219], v142
	ds_read_b128 v[220:223], v142 offset:1024
	ds_read_b128 v[224:227], v142 offset:2048
	ds_read_b128 v[228:231], v142 offset:3072
	v_lshl_add_u64 v[142:143], s[16:17], 0, v[2:3]
	s_mov_b32 m0, s39
	v_lshl_add_u64 v[196:197], s[16:17], 0, v[0:1]
	global_load_lds_dwordx4 v[142:143], off
	s_add_i32 m0, s39, 0x2000
	s_nop 0
	global_load_lds_dwordx4 v[196:197], off
	s_barrier
	s_waitcnt lgkmcnt(0)
	s_setprio 1
	s_waitcnt lgkmcnt(0)
	v_mfma_f32_16x16x32_bf16 v[96:99], v[216:219], v[168:171], v[96:99]
	v_mfma_f32_16x16x32_bf16 v[96:99], v[220:223], v[172:175], v[96:99]
	v_mfma_f32_16x16x32_bf16 v[92:95], v[224:227], v[168:171], v[92:95]
	v_mfma_f32_16x16x32_bf16 v[92:95], v[228:231], v[172:175], v[92:95]
	v_mfma_f32_16x16x32_bf16 v[88:91], v[216:219], v[176:179], v[88:91]
	v_mfma_f32_16x16x32_bf16 v[88:91], v[220:223], v[180:183], v[88:91]
	v_mfma_f32_16x16x32_bf16 v[84:87], v[224:227], v[176:179], v[84:87]
	v_mfma_f32_16x16x32_bf16 v[84:87], v[228:231], v[180:183], v[84:87]
	v_mfma_f32_16x16x32_bf16 v[80:83], v[216:219], v[184:187], v[80:83]
	v_mfma_f32_16x16x32_bf16 v[80:83], v[220:223], v[188:191], v[80:83]
	v_mfma_f32_16x16x32_bf16 v[76:79], v[224:227], v[184:187], v[76:79]
	v_mfma_f32_16x16x32_bf16 v[76:79], v[228:231], v[188:191], v[76:79]
	v_mfma_f32_16x16x32_bf16 v[72:75], v[216:219], v[192:195], v[72:75]
	v_mfma_f32_16x16x32_bf16 v[72:75], v[220:223], v[212:215], v[72:75]
	v_mfma_f32_16x16x32_bf16 v[68:71], v[224:227], v[192:195], v[68:71]
	v_mfma_f32_16x16x32_bf16 v[68:71], v[228:231], v[212:215], v[68:71]
	s_setprio 0
	s_mov_b32 m0, s26
	v_lshl_add_u64 v[232:233], s[18:19], 0, v[134:135]
	s_barrier
	ds_read_b128 v[168:171], v146 offset:16384
	ds_read_b128 v[172:175], v146 offset:17408
	ds_read_b128 v[176:179], v146 offset:18432
	ds_read_b128 v[180:183], v146 offset:19456
	ds_read_b128 v[184:187], v146 offset:20480
	ds_read_b128 v[188:191], v146 offset:21504
	ds_read_b128 v[192:195], v146 offset:22528
	ds_read_b128 v[212:215], v146 offset:23552
	global_load_lds_dwordx4 v[232:233], off
	v_lshl_add_u64 v[234:235], s[18:19], 0, v[132:133]
	s_mov_b32 m0, s27
	s_nop 0
	global_load_lds_dwordx4 v[234:235], off
	s_barrier
	s_waitcnt lgkmcnt(0)
	s_setprio 1
	s_waitcnt lgkmcnt(0)
	v_mfma_f32_16x16x32_bf16 v[64:67], v[148:151], v[168:171], v[64:67]
	v_mfma_f32_16x16x32_bf16 v[64:67], v[152:155], v[172:175], v[64:67]
	v_mfma_f32_16x16x32_bf16 v[60:63], v[156:159], v[168:171], v[60:63]
	v_mfma_f32_16x16x32_bf16 v[60:63], v[160:163], v[172:175], v[60:63]
	v_mfma_f32_16x16x32_bf16 v[56:59], v[148:151], v[176:179], v[56:59]
	v_mfma_f32_16x16x32_bf16 v[56:59], v[152:155], v[180:183], v[56:59]
	v_mfma_f32_16x16x32_bf16 v[52:55], v[156:159], v[176:179], v[52:55]
	v_mfma_f32_16x16x32_bf16 v[52:55], v[160:163], v[180:183], v[52:55]
	v_mfma_f32_16x16x32_bf16 v[48:51], v[148:151], v[184:187], v[48:51]
	v_mfma_f32_16x16x32_bf16 v[48:51], v[152:155], v[188:191], v[48:51]
	v_mfma_f32_16x16x32_bf16 v[44:47], v[156:159], v[184:187], v[44:47]
	v_mfma_f32_16x16x32_bf16 v[44:47], v[160:163], v[188:191], v[44:47]
	v_mfma_f32_16x16x32_bf16 v[40:43], v[148:151], v[192:195], v[40:43]
	v_mfma_f32_16x16x32_bf16 v[40:43], v[152:155], v[212:215], v[40:43]
	v_mfma_f32_16x16x32_bf16 v[36:39], v[156:159], v[192:195], v[36:39]
	v_mfma_f32_16x16x32_bf16 v[36:39], v[160:163], v[212:215], v[36:39]
	s_setprio 0
	s_barrier
; #define PG8_WAIT_V(n) asm volatile("s_waitcnt vmcnt(" #n ")" ::: "memory")
; #define PG8_WAIT_L(n) asm volatile("s_waitcnt lgkmcnt(" #n ")" ::: "memory")
; #define PG8_BAR __builtin_amdgcn_s_barrier()
; #define PG8_SCHED __builtin_amdgcn_sched_barrier(0)
; template <class Epi, class AddrA, class AddrB>
; __device__ __forceinline__ void gemm_phase(const Sched S, const int lda, const int ldb, const int K, const AddrA addrA,
;                                            const AddrB addrB, const Epi E) {
;     ...
;       PG8_WAIT_V(6); PG8_BAR; PG8_MMA(1, 1, At, B1); PG8_BAR;
;       PG8_LDB(B0, 1, 0); PG8_SCHED; PG8_LDA(At, 1, 0); PG8_STAGE(PG8_SA(0, 1), a2 + hstepA, voffA);
;       PG8_WAIT_L(8); PG8_BAR; PG8_WAIT_L(0); PG8_MMA(0, 0, At, B0); PG8_BAR; PG8_SCHED;
;       PG8_LDB(B1, 1, 1); PG8_STAGE(PG8_SB(1, 0), b3, voffB);
;       PG8_BAR; PG8_WAIT_L(0); PG8_MMA(0, 1, At, B1); PG8_BAR;
;       PG8_LDA(At, 1, 1); PG8_STAGE(PG8_SA(1, 0), a3, voffA);
;       PG8_BAR; PG8_WAIT_L(0); PG8_MMA(1, 0, At, B0); PG8_BAR; PG8_SCHED;
	s_add_u32 s40, s16, 0x80000
	s_addc_u32 s41, s17, 0
	s_add_i32 s39, s42, s25
	v_lshl_add_u64 v[148:149], s[40:41], 0, v[2:3]
	s_mov_b32 m0, s39
	s_nop 0
	global_load_lds_dwordx4 v[148:149], off
	v_lshl_add_u64 v[148:149], s[40:41], 0, v[0:1]
	s_add_i32 m0, s39, 0x2000
	s_nop 0
	global_load_lds_dwordx4 v[148:149], off
	s_waitcnt vmcnt(6)
	s_barrier
	s_setprio 1
	v_mfma_f32_16x16x32_bf16 v[32:35], v[216:219], v[168:171], v[32:35]
	v_mfma_f32_16x16x32_bf16 v[32:35], v[220:223], v[172:175], v[32:35]
	v_mfma_f32_16x16x32_bf16 v[28:31], v[224:227], v[168:171], v[28:31]
	v_mfma_f32_16x16x32_bf16 v[28:31], v[228:231], v[172:175], v[28:31]
	v_mfma_f32_16x16x32_bf16 v[24:27], v[216:219], v[176:179], v[24:27]
	v_mfma_f32_16x16x32_bf16 v[24:27], v[220:223], v[180:183], v[24:27]
	v_mfma_f32_16x16x32_bf16 v[20:23], v[224:227], v[176:179], v[20:23]
	v_mfma_f32_16x16x32_bf16 v[20:23], v[228:231], v[180:183], v[20:23]
	v_mfma_f32_16x16x32_bf16 v[16:19], v[216:219], v[184:187], v[16:19]
	v_mfma_f32_16x16x32_bf16 v[16:19], v[220:223], v[188:191], v[16:19]
	v_mfma_f32_16x16x32_bf16 v[12:15], v[224:227], v[184:187], v[12:15]
	v_mfma_f32_16x16x32_bf16 v[12:15], v[228:231], v[188:191], v[12:15]
	v_mfma_f32_16x16x32_bf16 v[8:11], v[216:219], v[192:195], v[8:11]
	v_mfma_f32_16x16x32_bf16 v[8:11], v[220:223], v[212:215], v[8:11]
	v_mfma_f32_16x16x32_bf16 v[4:7], v[224:227], v[192:195], v[4:7]
	v_mfma_f32_16x16x32_bf16 v[4:7], v[228:231], v[212:215], v[4:7]
	s_setprio 0
	s_add_i32 s39, 0, 0x18000
	v_add_u32_e32 v147, s39, v144
	s_barrier
	ds_read_b128 v[148:151], v147
	ds_read_b128 v[152:155], v147 offset:1024
	ds_read_b128 v[156:159], v147 offset:2048
	ds_read_b128 v[160:163], v147 offset:3072
	s_add_u32 s18, s18, 0x80000
	s_addc_u32 s19, s19, 0
	s_mov_b32 m0, s28
	v_lshl_add_u64 v[216:217], s[18:19], 0, v[134:135]
	ds_read_b128 v[168:171], v146 offset:32768
	ds_read_b128 v[172:175], v146 offset:33792
	ds_read_b128 v[176:179], v146 offset:34816
	ds_read_b128 v[180:183], v146 offset:35840
	ds_read_b128 v[184:187], v146 offset:36864
	ds_read_b128 v[188:191], v146 offset:37888
	ds_read_b128 v[192:195], v146 offset:38912
	ds_read_b128 v[212:215], v146 offset:39936
	global_load_lds_dwordx4 v[216:217], off
	v_lshl_add_u64 v[216:217], s[18:19], 0, v[132:133]
	s_mov_b32 m0, s29
	s_nop 0
	global_load_lds_dwordx4 v[216:217], off
	s_waitcnt lgkmcnt(8)
	s_barrier
	s_waitcnt lgkmcnt(0)
	s_setprio 1
	s_waitcnt lgkmcnt(0)
	v_mfma_f32_16x16x32_bf16 v[128:131], v[148:151], v[168:171], v[128:131]
	v_mfma_f32_16x16x32_bf16 v[128:131], v[152:155], v[172:175], v[128:131]
	v_mfma_f32_16x16x32_bf16 v[124:127], v[156:159], v[168:171], v[124:127]
	v_mfma_f32_16x16x32_bf16 v[124:127], v[160:163], v[172:175], v[124:127]
	v_mfma_f32_16x16x32_bf16 v[120:123], v[148:151], v[176:179], v[120:123]
	v_mfma_f32_16x16x32_bf16 v[120:123], v[152:155], v[180:183], v[120:123]
	v_mfma_f32_16x16x32_bf16 v[116:119], v[156:159], v[176:179], v[116:119]
	v_mfma_f32_16x16x32_bf16 v[116:119], v[160:163], v[180:183], v[116:119]
	v_mfma_f32_16x16x32_bf16 v[112:115], v[148:151], v[184:187], v[112:115]
	v_mfma_f32_16x16x32_bf16 v[112:115], v[152:155], v[188:191], v[112:115]
	v_mfma_f32_16x16x32_bf16 v[108:111], v[156:159], v[184:187], v[108:111]
	v_mfma_f32_16x16x32_bf16 v[108:111], v[160:163], v[188:191], v[108:111]
	v_mfma_f32_16x16x32_bf16 v[104:107], v[148:151], v[192:195], v[104:107]
	v_mfma_f32_16x16x32_bf16 v[104:107], v[152:155], v[212:215], v[104:107]
	v_mfma_f32_16x16x32_bf16 v[100:103], v[156:159], v[192:195], v[100:103]
	v_mfma_f32_16x16x32_bf16 v[100:103], v[160:163], v[212:215], v[100:103]
	s_setprio 0
	s_barrier
	s_add_i32 s18, 0, 0x1c000
	s_add_i32 s19, s39, s25
	v_add_u32_e32 v147, s18, v144
	v_lshl_add_u64 v[142:143], v[142:143], 0, s[52:53]
	s_mov_b32 m0, s19
	ds_read_b128 v[216:219], v147
	ds_read_b128 v[220:223], v147 offset:1024
	ds_read_b128 v[224:227], v147 offset:2048
	ds_read_b128 v[228:231], v147 offset:3072
	global_load_lds_dwordx4 v[142:143], off
	v_lshl_add_u64 v[142:143], v[196:197], 0, s[52:53]
	s_add_i32 m0, s19, 0x2000
	s_nop 0
	global_load_lds_dwordx4 v[142:143], off
	s_barrier
	s_waitcnt lgkmcnt(0)
	s_setprio 1
	s_waitcnt lgkmcnt(0)
	v_mfma_f32_16x16x32_bf16 v[96:99], v[216:219], v[168:171], v[96:99]
	v_mfma_f32_16x16x32_bf16 v[96:99], v[220:223], v[172:175], v[96:99]
	v_mfma_f32_16x16x32_bf16 v[92:95], v[224:227], v[168:171], v[92:95]
	v_mfma_f32_16x16x32_bf16 v[92:95], v[228:231], v[172:175], v[92:95]
	v_mfma_f32_16x16x32_bf16 v[88:91], v[216:219], v[176:179], v[88:91]
	v_mfma_f32_16x16x32_bf16 v[88:91], v[220:223], v[180:183], v[88:91]
	v_mfma_f32_16x16x32_bf16 v[84:87], v[224:227], v[176:179], v[84:87]
	v_mfma_f32_16x16x32_bf16 v[84:87], v[228:231], v[180:183], v[84:87]
	v_mfma_f32_16x16x32_bf16 v[80:83], v[216:219], v[184:187], v[80:83]
	v_mfma_f32_16x16x32_bf16 v[80:83], v[220:223], v[188:191], v[80:83]
	v_mfma_f32_16x16x32_bf16 v[76:79], v[224:227], v[184:187], v[76:79]
	v_mfma_f32_16x16x32_bf16 v[76:79], v[228:231], v[188:191], v[76:79]
	v_mfma_f32_16x16x32_bf16 v[72:75], v[216:219], v[192:195], v[72:75]
	v_mfma_f32_16x16x32_bf16 v[72:75], v[220:223], v[212:215], v[72:75]
	v_mfma_f32_16x16x32_bf16 v[68:71], v[224:227], v[192:195], v[68:71]
	v_mfma_f32_16x16x32_bf16 v[68:71], v[228:231], v[212:215], v[68:71]
	s_setprio 0
	s_mov_b32 m0, s30
	v_lshl_add_u64 v[142:143], v[232:233], 0, s[52:53]
	s_barrier
	ds_read_b128 v[168:171], v146 offset:49152
	ds_read_b128 v[172:175], v146 offset:50176
	ds_read_b128 v[176:179], v146 offset:51200
	ds_read_b128 v[180:183], v146 offset:52224
	ds_read_b128 v[184:187], v146 offset:53248
	ds_read_b128 v[188:191], v146 offset:54272
	ds_read_b128 v[192:195], v146 offset:55296
	ds_read_b128 v[212:215], v146 offset:56320
	global_load_lds_dwordx4 v[142:143], off
	v_lshl_add_u64 v[142:143], v[234:235], 0, s[52:53]
	s_mov_b32 m0, s31
	s_nop 0
	global_load_lds_dwordx4 v[142:143], off
	s_barrier
; #define PG8_WAIT_V(n) asm volatile("s_waitcnt vmcnt(" #n ")" ::: "memory")
; #define PG8_WAIT_L(n) asm volatile("s_waitcnt lgkmcnt(" #n ")" ::: "memory")
; #define PG8_BAR __builtin_amdgcn_s_barrier()
; #define PG8_SCHED __builtin_amdgcn_sched_barrier(0)
; template <class Epi, class AddrA, class AddrB>
; __device__ __forceinline__ void gemm_phase(const Sched S, const int lda, const int ldb, const int K, const AddrA addrA,
;                                            const AddrB addrB, const Epi E) {
;     ...
;       PG8_BAR; PG8_WAIT_L(0); PG8_MMA(1, 0, At, B0); PG8_BAR; PG8_SCHED;
;       PG8_STAGE(PG8_SB(1, 1), b3 + hstepB, voffB);
;       PG8_WAIT_V(6); PG8_BAR; PG8_MMA(1, 1, At, B1); PG8_BAR;
;   __device__ __forceinline__ void operator()(EPI_ARGS) const {
;     const size_t row0 = (size_t)u.pm * 256 + wr * 64 + fr;
;     const int col0 = u.pn * 256 + wc * 32 + 8 * fq;
; #pragma unroll
;     for (int ai = 0; ai < 2; ++ai)
; #pragma unroll
;       for (int bj = 0; bj < 2; ++bj) {
;         f32x4 x0[4], x1[4];
; #pragma unroll
;         for (int m = 0; m < 4; ++m) {
;           const size_t o = (row0 + ai * HALF + m * 16) * DM + col0 + bj * HALF;
;           x0[m] = *(const f32x4*)(xres + o);
;           x1[m] = *(const f32x4*)(xres + o + 4);
;         }
;         __builtin_amdgcn_sched_barrier(0);
; #pragma unroll
;         for (int m = 0; m < 4; ++m) {
;           const size_t o = (row0 + ai * HALF + m * 16) * DM + col0 + bj * HALF;
;           *(f32x4*)(hbuf + o) = acc[ai][bj][m][0] + x0[m] * ALPHA;
;           *(f32x4*)(hbuf + o + 4) = acc[ai][bj][m][1] + x1[m] * ALPHA;
;         }
;       }
	s_waitcnt lgkmcnt(0)
	s_setprio 1
	s_waitcnt lgkmcnt(0)
	v_mfma_f32_16x16x32_bf16 v[64:67], v[148:151], v[168:171], v[64:67]
	v_mfma_f32_16x16x32_bf16 v[64:67], v[152:155], v[172:175], v[64:67]
	v_mfma_f32_16x16x32_bf16 v[60:63], v[156:159], v[168:171], v[60:63]
	v_mfma_f32_16x16x32_bf16 v[60:63], v[160:163], v[172:175], v[60:63]
	v_mfma_f32_16x16x32_bf16 v[56:59], v[148:151], v[176:179], v[56:59]
	v_mfma_f32_16x16x32_bf16 v[56:59], v[152:155], v[180:183], v[56:59]
	v_mfma_f32_16x16x32_bf16 v[52:55], v[156:159], v[176:179], v[52:55]
	v_mfma_f32_16x16x32_bf16 v[52:55], v[160:163], v[180:183], v[52:55]
	v_mfma_f32_16x16x32_bf16 v[48:51], v[148:151], v[184:187], v[48:51]
	v_mfma_f32_16x16x32_bf16 v[48:51], v[152:155], v[188:191], v[48:51]
	v_mfma_f32_16x16x32_bf16 v[44:47], v[156:159], v[184:187], v[44:47]
	v_mfma_f32_16x16x32_bf16 v[44:47], v[160:163], v[188:191], v[44:47]
	v_mfma_f32_16x16x32_bf16 v[40:43], v[148:151], v[192:195], v[40:43]
	v_mfma_f32_16x16x32_bf16 v[40:43], v[152:155], v[212:215], v[40:43]
	v_mfma_f32_16x16x32_bf16 v[36:39], v[156:159], v[192:195], v[36:39]
	v_mfma_f32_16x16x32_bf16 v[36:39], v[160:163], v[212:215], v[36:39]
	s_setprio 0
	s_barrier
	s_add_u32 s16, s16, 0x80080
	s_addc_u32 s17, s17, 0
	s_add_i32 s18, s18, s25
	v_lshl_add_u64 v[142:143], s[16:17], 0, v[2:3]
	s_mov_b32 m0, s18
	s_nop 0
	global_load_lds_dwordx4 v[142:143], off
	v_lshl_add_u64 v[142:143], s[16:17], 0, v[0:1]
	s_add_i32 m0, s18, 0x2000
	s_nop 0
	global_load_lds_dwordx4 v[142:143], off
	s_waitcnt vmcnt(6)
	s_barrier
	s_setprio 1
	v_mfma_f32_16x16x32_bf16 v[32:35], v[216:219], v[168:171], v[32:35]
	v_mfma_f32_16x16x32_bf16 v[32:35], v[220:223], v[172:175], v[32:35]
	v_mfma_f32_16x16x32_bf16 v[28:31], v[224:227], v[168:171], v[28:31]
	v_mfma_f32_16x16x32_bf16 v[28:31], v[228:231], v[172:175], v[28:31]
	v_mfma_f32_16x16x32_bf16 v[24:27], v[216:219], v[176:179], v[24:27]
	v_mfma_f32_16x16x32_bf16 v[24:27], v[220:223], v[180:183], v[24:27]
	v_mfma_f32_16x16x32_bf16 v[20:23], v[224:227], v[176:179], v[20:23]
	v_mfma_f32_16x16x32_bf16 v[20:23], v[228:231], v[180:183], v[20:23]
	v_mfma_f32_16x16x32_bf16 v[16:19], v[216:219], v[184:187], v[16:19]
	v_mfma_f32_16x16x32_bf16 v[16:19], v[220:223], v[188:191], v[16:19]
	v_mfma_f32_16x16x32_bf16 v[12:15], v[224:227], v[184:187], v[12:15]
	v_mfma_f32_16x16x32_bf16 v[12:15], v[228:231], v[188:191], v[12:15]
	v_mfma_f32_16x16x32_bf16 v[8:11], v[216:219], v[192:195], v[8:11]
	v_mfma_f32_16x16x32_bf16 v[8:11], v[220:223], v[212:215], v[8:11]
	v_mfma_f32_16x16x32_bf16 v[4:7], v[224:227], v[192:195], v[4:7]
	v_mfma_f32_16x16x32_bf16 v[4:7], v[228:231], v[212:215], v[4:7]
	s_setprio 0
	s_add_i32 s38, s38, 2
	s_add_u32 s36, s36, 0x100
	s_addc_u32 s37, s37, 0
	s_add_u32 s14, s14, 0x100
	s_addc_u32 s15, s15, 0
	s_cmp_gt_u32 s38, 29
	s_barrier
	s_cbranch_scc0 .LBB0_619
	s_ashr_i32 s13, s12, 31
	v_lshl_or_b32 v142, s34, 8, v145
	v_ashrrev_i32_e32 v143, 31, v142
	s_lshl_b64 s[12:13], s[12:13], 21
	v_lshlrev_b64 v[184:185], 2, v[142:143]
	v_lshl_add_u64 v[188:189], s[12:13], 0, v[136:137]
	v_lshl_add_u64 v[186:187], s[0:1], 0, v[184:185]
	v_or_b32_e32 v190, 0x20000, v188
	v_mov_b32_e32 v191, v189
	v_or_b32_e32 v192, 0x40000, v188
	v_mov_b32_e32 v193, v189
	v_or_b32_e32 v194, 0x60000, v188
	v_mov_b32_e32 v195, v189
	v_lshl_add_u64 v[142:143], v[186:187], 0, v[188:189]
	v_lshl_add_u64 v[160:161], v[186:187], 0, v[190:191]
	v_lshl_add_u64 v[172:173], v[186:187], 0, v[192:193]
	v_lshl_add_u64 v[180:181], v[186:187], 0, v[194:195]
	flat_load_dwordx4 v[148:151], v[142:143]
	flat_load_dwordx4 v[152:155], v[142:143] offset:16
	flat_load_dwordx4 v[156:159], v[160:161]
	s_nop 0
	flat_load_dwordx4 v[160:163], v[160:161] offset:16
	s_nop 0
	flat_load_dwordx4 v[168:171], v[172:173]
	s_nop 0
	flat_load_dwordx4 v[172:175], v[172:173] offset:16
	s_nop 0
	flat_load_dwordx4 v[176:179], v[180:181]
	s_nop 0
	flat_load_dwordx4 v[180:183], v[180:181] offset:16
	v_lshl_add_u64 v[184:185], s[48:49], 0, v[184:185]
	s_mov_b32 s14, 0x3fb504f3
	s_waitcnt vmcnt(0) lgkmcnt(0)
	v_pk_fma_f32 v[148:149], v[148:149], s[14:15], v[128:129] op_sel_hi:[1,0,1]
	v_lshl_add_u64 v[128:129], v[184:185], 0, v[188:189]
	v_pk_fma_f32 v[126:127], v[154:155], s[14:15], v[126:127] op_sel_hi:[1,0,1]
	v_pk_fma_f32 v[124:125], v[152:153], s[14:15], v[124:125] op_sel_hi:[1,0,1]
	global_store_dwordx4 v[128:129], v[124:127], off offset:16
	v_pk_fma_f32 v[118:119], v[162:163], s[14:15], v[118:119] op_sel_hi:[1,0,1]
	v_pk_fma_f32 v[116:117], v[160:161], s[14:15], v[116:117] op_sel_hi:[1,0,1]
	v_lshl_add_u64 v[124:125], v[184:185], 0, v[190:191]
	v_pk_fma_f32 v[122:123], v[158:159], s[14:15], v[122:123] op_sel_hi:[1,0,1]
	v_pk_fma_f32 v[120:121], v[156:157], s[14:15], v[120:121] op_sel_hi:[1,0,1]
	global_store_dwordx4 v[124:125], v[116:119], off offset:16
	v_pk_fma_f32 v[110:111], v[174:175], s[14:15], v[110:111] op_sel_hi:[1,0,1]
	v_pk_fma_f32 v[108:109], v[172:173], s[14:15], v[108:109] op_sel_hi:[1,0,1]
	v_lshl_add_u64 v[116:117], v[184:185], 0, v[192:193]
	s_mov_b64 s[12:13], 0x200
	v_pk_fma_f32 v[150:151], v[150:151], s[14:15], v[130:131] op_sel_hi:[1,0,1]
	global_store_dwordx4 v[124:125], v[120:123], off
	v_pk_fma_f32 v[114:115], v[170:171], s[14:15], v[114:115] op_sel_hi:[1,0,1]
	v_pk_fma_f32 v[112:113], v[168:169], s[14:15], v[112:113] op_sel_hi:[1,0,1]
	global_store_dwordx4 v[116:117], v[108:111], off offset:16
	v_pk_fma_f32 v[106:107], v[178:179], s[14:15], v[106:107] op_sel_hi:[1,0,1]
	v_pk_fma_f32 v[104:105], v[176:177], s[14:15], v[104:105] op_sel_hi:[1,0,1]
	v_lshl_add_u64 v[108:109], v[184:185], 0, v[194:195]
	v_pk_fma_f32 v[102:103], v[182:183], s[14:15], v[102:103] op_sel_hi:[1,0,1]
	v_pk_fma_f32 v[100:101], v[180:181], s[14:15], v[100:101] op_sel_hi:[1,0,1]
	v_lshl_add_u64 v[124:125], v[186:187], 0, s[12:13]
	global_store_dwordx4 v[128:129], v[148:151], off
	global_store_dwordx4 v[116:117], v[112:115], off
	global_store_dwordx4 v[108:109], v[104:107], off
	global_store_dwordx4 v[108:109], v[100:103], off offset:16
	v_lshl_add_u64 v[112:113], v[124:125], 0, v[190:191]
	v_lshl_add_u64 v[120:121], v[124:125], 0, v[192:193]
	v_lshl_add_u64 v[130:131], v[124:125], 0, v[194:195]
	flat_load_dwordx4 v[100:103], v[142:143] offset:512
	flat_load_dwordx4 v[104:107], v[142:143] offset:528
	flat_load_dwordx4 v[108:111], v[112:113]
	s_nop 0
	flat_load_dwordx4 v[112:115], v[112:113] offset:16
	s_nop 0
	flat_load_dwordx4 v[116:119], v[120:121]
	s_nop 0
	flat_load_dwordx4 v[120:123], v[120:121] offset:16
	s_nop 0
	flat_load_dwordx4 v[124:127], v[130:131]
	flat_load_dwordx4 v[148:151], v[130:131] offset:16
	s_mov_b32 s3, 0x100000
	s_waitcnt vmcnt(0) lgkmcnt(0)
;   __device__ __forceinline__ void operator()(EPI_ARGS) const {
;     ...
;     for (int ai = 0; ai < 2; ++ai)
; #pragma unroll
;       for (int bj = 0; bj < 2; ++bj) {
;         f32x4 x0[4], x1[4];
; #pragma unroll
;         for (int m = 0; m < 4; ++m) {
;           const size_t o = (row0 + ai * HALF + m * 16) * DM + col0 + bj * HALF;
;           x0[m] = *(const f32x4*)(xres + o);
;           x1[m] = *(const f32x4*)(xres + o + 4);
;         }
;         __builtin_amdgcn_sched_barrier(0);
; #pragma unroll
;         for (int m = 0; m < 4; ++m) {
;           const size_t o = (row0 + ai * HALF + m * 16) * DM + col0 + bj * HALF;
;           *(f32x4*)(hbuf + o) = acc[ai][bj][m][0] + x0[m] * ALPHA;
;           *(f32x4*)(hbuf + o + 4) = acc[ai][bj][m][1] + x1[m] * ALPHA;
;         }
;       }
	v_pk_fma_f32 v[96:97], v[100:101], s[14:15], v[96:97] op_sel_hi:[1,0,1]
	v_add_co_u32_e32 v100, vcc, s3, v142
	s_mov_b32 s5, 0x120000
	s_nop 0
	v_addc_co_u32_e32 v101, vcc, 0, v143, vcc
	v_pk_fma_f32 v[98:99], v[102:103], s[14:15], v[98:99] op_sel_hi:[1,0,1]
	v_add_co_u32_e32 v102, vcc, s5, v142
	v_lshl_add_u64 v[130:131], v[184:185], 0, s[12:13]
	v_pk_fma_f32 v[94:95], v[106:107], s[14:15], v[94:95] op_sel_hi:[1,0,1]
	v_pk_fma_f32 v[92:93], v[104:105], s[14:15], v[92:93] op_sel_hi:[1,0,1]
	v_addc_co_u32_e32 v103, vcc, 0, v143, vcc
	s_mov_b32 s12, 0x140000
	global_store_dwordx4 v[128:129], v[92:95], off offset:528
	v_pk_fma_f32 v[86:87], v[114:115], s[14:15], v[86:87] op_sel_hi:[1,0,1]
	v_pk_fma_f32 v[84:85], v[112:113], s[14:15], v[84:85] op_sel_hi:[1,0,1]
	v_lshl_add_u64 v[92:93], v[130:131], 0, v[190:191]
	v_add_co_u32_e32 v104, vcc, s12, v142
	global_store_dwordx4 v[92:93], v[84:87], off offset:16
	v_pk_fma_f32 v[78:79], v[122:123], s[14:15], v[78:79] op_sel_hi:[1,0,1]
	v_pk_fma_f32 v[76:77], v[120:121], s[14:15], v[76:77] op_sel_hi:[1,0,1]
	v_lshl_add_u64 v[84:85], v[130:131], 0, v[192:193]
	v_addc_co_u32_e32 v105, vcc, 0, v143, vcc
	s_mov_b32 s13, 0x160000
	v_pk_fma_f32 v[90:91], v[110:111], s[14:15], v[90:91] op_sel_hi:[1,0,1]
	v_pk_fma_f32 v[88:89], v[108:109], s[14:15], v[88:89] op_sel_hi:[1,0,1]
	v_pk_fma_f32 v[82:83], v[118:119], s[14:15], v[82:83] op_sel_hi:[1,0,1]
	v_pk_fma_f32 v[80:81], v[116:117], s[14:15], v[80:81] op_sel_hi:[1,0,1]
	global_store_dwordx4 v[84:85], v[76:79], off offset:16
	v_pk_fma_f32 v[74:75], v[126:127], s[14:15], v[74:75] op_sel_hi:[1,0,1]
	v_pk_fma_f32 v[72:73], v[124:125], s[14:15], v[72:73] op_sel_hi:[1,0,1]
	v_lshl_add_u64 v[76:77], v[130:131], 0, v[194:195]
	v_pk_fma_f32 v[70:71], v[150:151], s[14:15], v[70:71] op_sel_hi:[1,0,1]
	v_pk_fma_f32 v[68:69], v[148:149], s[14:15], v[68:69] op_sel_hi:[1,0,1]
	s_mov_b64 s[16:17], 0x100000
	s_mov_b64 s[18:19], 0x120000
	s_mov_b64 s[34:35], 0x140000
	s_mov_b64 s[36:37], 0x160000
	v_add_co_u32_e32 v106, vcc, s13, v142
	global_store_dwordx4 v[128:129], v[96:99], off offset:512
	global_store_dwordx4 v[92:93], v[88:91], off
	global_store_dwordx4 v[84:85], v[80:83], off
	global_store_dwordx4 v[76:77], v[72:75], off
	global_store_dwordx4 v[76:77], v[68:71], off offset:16
	v_lshl_add_u64 v[80:81], v[142:143], 0, s[18:19]
	v_lshl_add_u64 v[72:73], v[142:143], 0, s[16:17]
	v_lshl_add_u64 v[88:89], v[142:143], 0, s[34:35]
	v_lshl_add_u64 v[96:97], v[142:143], 0, s[36:37]
	v_addc_co_u32_e32 v107, vcc, 0, v143, vcc
	flat_load_dwordx4 v[68:71], v[100:101]
	s_nop 0
	flat_load_dwordx4 v[72:75], v[72:73] offset:16
	s_nop 0
	flat_load_dwordx4 v[76:79], v[102:103]
	s_nop 0
	flat_load_dwordx4 v[80:83], v[80:81] offset:16
	s_nop 0
	flat_load_dwordx4 v[84:87], v[104:105]
	s_nop 0
	flat_load_dwordx4 v[88:91], v[88:89] offset:16
	s_nop 0
	flat_load_dwordx4 v[92:95], v[106:107]
	s_nop 0
	flat_load_dwordx4 v[96:99], v[96:97] offset:16
	s_waitcnt vmcnt(0) lgkmcnt(0)
; #define PG8_WAIT_V(n) asm volatile("s_waitcnt vmcnt(" #n ")" ::: "memory")
; #define PG8_BAR __builtin_amdgcn_s_barrier()
; template <class Epi, class AddrA, class AddrB>
; __device__ __forceinline__ void gemm_phase(const Sched S, const int lda, const int ldb, const int K, const AddrA addrA,
;                                            const AddrB addrB, const Epi E) {
;     ...
;     cur = nxt; cA = nA; cB = nB; ++ui;
;   }
;   PG8_WAIT_V(0);
;   if (wr == 0) PG8_BAR;
;   PG8_BAR;
;   __device__ __forceinline__ void operator()(EPI_ARGS) const {
;     ...
;     for (int ai = 0; ai < 2; ++ai)
; #pragma unroll
;       for (int bj = 0; bj < 2; ++bj) {
;         f32x4 x0[4], x1[4];
; #pragma unroll
;         for (int m = 0; m < 4; ++m) {
;           const size_t o = (row0 + ai * HALF + m * 16) * DM + col0 + bj * HALF;
;           x0[m] = *(const f32x4*)(xres + o);
;           x1[m] = *(const f32x4*)(xres + o + 4);
;         }
;         __builtin_amdgcn_sched_barrier(0);
; #pragma unroll
;         for (int m = 0; m < 4; ++m) {
;           const size_t o = (row0 + ai * HALF + m * 16) * DM + col0 + bj * HALF;
;           *(f32x4*)(hbuf + o) = acc[ai][bj][m][0] + x0[m] * ALPHA;
;           *(f32x4*)(hbuf + o + 4) = acc[ai][bj][m][1] + x1[m] * ALPHA;
;         }
;       }
	v_pk_fma_f32 v[66:67], v[70:71], s[14:15], v[66:67] op_sel_hi:[1,0,1]
	v_add_co_u32_e32 v70, vcc, s3, v128
	v_pk_fma_f32 v[64:65], v[68:69], s[14:15], v[64:65] op_sel_hi:[1,0,1]
	v_lshl_add_u64 v[68:69], v[128:129], 0, s[16:17]
	v_addc_co_u32_e32 v71, vcc, 0, v129, vcc
	v_pk_fma_f32 v[62:63], v[74:75], s[14:15], v[62:63] op_sel_hi:[1,0,1]
	v_pk_fma_f32 v[60:61], v[72:73], s[14:15], v[60:61] op_sel_hi:[1,0,1]
	global_store_dwordx4 v[68:69], v[60:63], off offset:16
	v_add_co_u32_e32 v68, vcc, s5, v128
	s_nop 0
	v_lshl_add_u64 v[60:61], v[128:129], 0, s[18:19]
	v_addc_co_u32_e32 v69, vcc, 0, v129, vcc
	v_add_co_u32_e32 v72, vcc, s12, v128
	v_pk_fma_f32 v[54:55], v[82:83], s[14:15], v[54:55] op_sel_hi:[1,0,1]
	v_pk_fma_f32 v[52:53], v[80:81], s[14:15], v[52:53] op_sel_hi:[1,0,1]
	v_addc_co_u32_e32 v73, vcc, 0, v129, vcc
	global_store_dwordx4 v[60:61], v[52:55], off offset:16
	v_pk_fma_f32 v[46:47], v[90:91], s[14:15], v[46:47] op_sel_hi:[1,0,1]
	v_pk_fma_f32 v[44:45], v[88:89], s[14:15], v[44:45] op_sel_hi:[1,0,1]
	v_lshl_add_u64 v[52:53], v[128:129], 0, s[34:35]
	v_add_co_u32_e32 v74, vcc, s13, v128
	v_pk_fma_f32 v[58:59], v[78:79], s[14:15], v[58:59] op_sel_hi:[1,0,1]
	v_pk_fma_f32 v[56:57], v[76:77], s[14:15], v[56:57] op_sel_hi:[1,0,1]
	v_pk_fma_f32 v[50:51], v[86:87], s[14:15], v[50:51] op_sel_hi:[1,0,1]
	v_pk_fma_f32 v[48:49], v[84:85], s[14:15], v[48:49] op_sel_hi:[1,0,1]
	global_store_dwordx4 v[52:53], v[44:47], off offset:16
	v_pk_fma_f32 v[42:43], v[94:95], s[14:15], v[42:43] op_sel_hi:[1,0,1]
	v_pk_fma_f32 v[40:41], v[92:93], s[14:15], v[40:41] op_sel_hi:[1,0,1]
	v_lshl_add_u64 v[44:45], v[128:129], 0, s[36:37]
	v_addc_co_u32_e32 v75, vcc, 0, v129, vcc
	v_pk_fma_f32 v[38:39], v[98:99], s[14:15], v[38:39] op_sel_hi:[1,0,1]
	v_pk_fma_f32 v[36:37], v[96:97], s[14:15], v[36:37] op_sel_hi:[1,0,1]
	s_mov_b64 s[12:13], 0x100200
	s_mov_b64 s[16:17], 0x120200
	s_mov_b64 s[18:19], 0x140200
	s_mov_b64 s[34:35], 0x160200
	global_store_dwordx4 v[70:71], v[64:67], off
	global_store_dwordx4 v[68:69], v[56:59], off
	global_store_dwordx4 v[72:73], v[48:51], off
	global_store_dwordx4 v[74:75], v[40:43], off
	global_store_dwordx4 v[44:45], v[36:39], off offset:16
	v_lshl_add_u64 v[44:45], v[142:143], 0, s[12:13]
	v_lshl_add_u64 v[48:49], v[142:143], 0, s[16:17]
	v_lshl_add_u64 v[60:61], v[142:143], 0, s[18:19]
	v_lshl_add_u64 v[64:65], v[142:143], 0, s[34:35]
	flat_load_dwordx4 v[36:39], v[100:101] offset:512
	flat_load_dwordx4 v[40:43], v[102:103] offset:512
	s_nop 0
	flat_load_dwordx4 v[44:47], v[44:45] offset:16
	s_nop 0
	flat_load_dwordx4 v[48:51], v[48:49] offset:16
	s_nop 0
	flat_load_dwordx4 v[52:55], v[104:105] offset:512
	flat_load_dwordx4 v[56:59], v[106:107] offset:512
	s_nop 0
	flat_load_dwordx4 v[60:63], v[60:61] offset:16
	s_nop 0
	flat_load_dwordx4 v[64:67], v[64:65] offset:16
	s_waitcnt vmcnt(0) lgkmcnt(0)
	v_pk_fma_f32 v[32:33], v[36:37], s[14:15], v[32:33] op_sel_hi:[1,0,1]
	v_lshl_add_u64 v[36:37], v[128:129], 0, s[12:13]
	v_pk_fma_f32 v[30:31], v[46:47], s[14:15], v[30:31] op_sel_hi:[1,0,1]
	v_pk_fma_f32 v[28:29], v[44:45], s[14:15], v[28:29] op_sel_hi:[1,0,1]
	global_store_dwordx4 v[36:37], v[28:31], off offset:16
	v_pk_fma_f32 v[22:23], v[50:51], s[14:15], v[22:23] op_sel_hi:[1,0,1]
	v_pk_fma_f32 v[20:21], v[48:49], s[14:15], v[20:21] op_sel_hi:[1,0,1]
	v_lshl_add_u64 v[28:29], v[128:129], 0, s[16:17]
	global_store_dwordx4 v[28:29], v[20:23], off offset:16
	v_pk_fma_f32 v[14:15], v[62:63], s[14:15], v[14:15] op_sel_hi:[1,0,1]
	v_pk_fma_f32 v[12:13], v[60:61], s[14:15], v[12:13] op_sel_hi:[1,0,1]
	v_lshl_add_u64 v[20:21], v[128:129], 0, s[18:19]
	v_pk_fma_f32 v[34:35], v[38:39], s[14:15], v[34:35] op_sel_hi:[1,0,1]
	v_pk_fma_f32 v[26:27], v[42:43], s[14:15], v[26:27] op_sel_hi:[1,0,1]
	v_pk_fma_f32 v[24:25], v[40:41], s[14:15], v[24:25] op_sel_hi:[1,0,1]
	v_pk_fma_f32 v[18:19], v[54:55], s[14:15], v[18:19] op_sel_hi:[1,0,1]
	v_pk_fma_f32 v[16:17], v[52:53], s[14:15], v[16:17] op_sel_hi:[1,0,1]
	global_store_dwordx4 v[20:21], v[12:15], off offset:16
	v_pk_fma_f32 v[10:11], v[58:59], s[14:15], v[10:11] op_sel_hi:[1,0,1]
	v_pk_fma_f32 v[8:9], v[56:57], s[14:15], v[8:9] op_sel_hi:[1,0,1]
	v_lshl_add_u64 v[12:13], v[128:129], 0, s[34:35]
	v_pk_fma_f32 v[6:7], v[66:67], s[14:15], v[6:7] op_sel_hi:[1,0,1]
	v_pk_fma_f32 v[4:5], v[64:65], s[14:15], v[4:5] op_sel_hi:[1,0,1]
	s_and_b64 vcc, exec, s[6:7]
	s_mov_b32 s34, s4
	s_mov_b32 s12, s2
	s_mov_b64 s[14:15], s[10:11]
	s_mov_b64 s[16:17], s[8:9]
	global_store_dwordx4 v[70:71], v[32:35], off offset:512
	global_store_dwordx4 v[68:69], v[24:27], off offset:512
	global_store_dwordx4 v[72:73], v[16:19], off offset:512
	global_store_dwordx4 v[74:75], v[8:11], off offset:512
	global_store_dwordx4 v[12:13], v[4:7], off offset:16
	s_cbranch_vccz .LBB0_616
	s_waitcnt vmcnt(0)
	s_cmpk_gt_u32 s20, 0xff
	s_cbranch_scc1 .LBB0_623
	s_barrier
